# topk sub-key pieces 1..3: key loads issued right after the buffer-free barrier (registers v240-v251) instead of 50 instructions before use
# baseline (speedup 1.0000x reference)
.LBB0_1062:
	s_mov_b64 s[52:53], 0
	v_mov_b32_e32 v128, v176
	s_nop 7
	v_cvt_pk_bf16_f32 v16, v16, v17
	v_bfe_u32 v129, v128, 5, 1
	v_and_b32_e32 v134, 31, v128
	v_ashrrev_i32_e32 v135, 1, v128
	v_and_b32_e32 v130, 0xc0, v128
	v_lshlrev_b32_e32 v132, 3, v129
	v_and_or_b32 v131, v135, s93, v134
	v_lshl_or_b32 v130, v130, 1, v132
	v_mad_u64_u32 v[130:131], s[54:55], v131, s0, v[130:131]
	v_cvt_pk_bf16_f32 v17, v18, v19
	v_cvt_pk_bf16_f32 v18, v20, v21
	v_add_u32_e32 v20, 0xc000, v130
	v_cvt_pk_bf16_f32 v0, v0, v1
	v_cvt_pk_bf16_f32 v1, v2, v3
	v_cvt_pk_bf16_f32 v2, v4, v5
	v_cvt_pk_bf16_f32 v3, v6, v7
	s_waitcnt vmcnt(0) lgkmcnt(0)
	s_barrier
	v_cvt_pk_bf16_f32 v80, v80, v81
	v_cvt_pk_bf16_f32 v81, v82, v83
	v_cvt_pk_bf16_f32 v82, v84, v85
	v_cvt_pk_bf16_f32 v83, v86, v87
	ds_write2_b64 v20, v[0:1], v[2:3] offset0:200 offset1:202
	v_cvt_pk_bf16_f32 v0, v8, v9
	v_cvt_pk_bf16_f32 v1, v10, v11
	v_cvt_pk_bf16_f32 v2, v12, v13
	v_cvt_pk_bf16_f32 v3, v14, v15
	s_add_u32 s52, s96, s52
	ds_write2_b64 v130, v[80:81], v[82:83] offset0:8 offset1:10
	v_cvt_pk_bf16_f32 v80, v88, v89
	v_cvt_pk_bf16_f32 v81, v90, v91
	v_cvt_pk_bf16_f32 v82, v92, v93
	v_cvt_pk_bf16_f32 v83, v94, v95
	ds_write2_b64 v20, v[0:1], v[2:3] offset0:204 offset1:206
	v_lshlrev_b32_e32 v0, 4, v128
	s_addc_u32 s53, s97, s53
	ds_write2_b64 v130, v[80:81], v[82:83] offset0:12 offset1:14
	v_cvt_pk_bf16_f32 v80, v96, v97
	v_cvt_pk_bf16_f32 v81, v98, v99
	v_cvt_pk_bf16_f32 v82, v100, v101
	v_cvt_pk_bf16_f32 v83, v102, v103
	v_add_u32_e32 v84, 0x4000, v130
	v_and_b32_e32 v132, 0xf0, v0
	ds_write2_b64 v84, v[80:81], v[82:83] offset0:64 offset1:66
	v_cvt_pk_bf16_f32 v80, v104, v105
	v_cvt_pk_bf16_f32 v81, v106, v107
	v_cvt_pk_bf16_f32 v82, v108, v109
	v_cvt_pk_bf16_f32 v83, v110, v111
	s_lshl_b32 s16, s9, 8
	v_lshl_add_u64 v[0:1], s[52:53], 0, v[132:133]
	s_mov_b64 s[54:55], 0x1880000
	v_ashrrev_i32_e32 v110, 4, v128
	ds_write2_b64 v84, v[80:81], v[82:83] offset0:68 offset1:70
	v_cvt_pk_bf16_f32 v48, v48, v49
	v_cvt_pk_bf16_f32 v49, v50, v51
	v_cvt_pk_bf16_f32 v50, v52, v53
	v_cvt_pk_bf16_f32 v51, v54, v55
	v_add_u32_e32 v52, 0x8000, v130
	v_cvt_pk_bf16_f32 v19, v22, v23
	v_lshl_add_u64 v[82:83], v[0:1], 0, s[54:55]
	v_add_u32_e32 v0, s16, v110
	ds_write2_b64 v84, v[48:49], v[50:51] offset0:72 offset1:74
	v_cvt_pk_bf16_f32 v48, v56, v57
	v_cvt_pk_bf16_f32 v49, v58, v59
	v_cvt_pk_bf16_f32 v50, v60, v61
	v_cvt_pk_bf16_f32 v51, v62, v63
	ds_write2_b64 v52, v[16:17], v[18:19] offset0:136 offset1:138
	v_cvt_pk_bf16_f32 v16, v24, v25
	v_cvt_pk_bf16_f32 v17, v26, v27
	v_cvt_pk_bf16_f32 v18, v28, v29
	v_cvt_pk_bf16_f32 v19, v30, v31
	v_ashrrev_i32_e32 v1, 31, v0
	v_cvt_pk_bf16_f32 v112, v112, v113
	v_cvt_pk_bf16_f32 v113, v114, v115
	v_cvt_pk_bf16_f32 v114, v116, v117
	v_cvt_pk_bf16_f32 v115, v118, v119
	ds_write2_b64 v84, v[48:49], v[50:51] offset0:76 offset1:78
	v_cvt_pk_bf16_f32 v48, v64, v65
	v_cvt_pk_bf16_f32 v49, v66, v67
	v_cvt_pk_bf16_f32 v50, v68, v69
	v_cvt_pk_bf16_f32 v51, v70, v71
	ds_write2_b64 v52, v[16:17], v[18:19] offset0:140 offset1:142
	v_cvt_pk_bf16_f32 v16, v32, v33
	v_cvt_pk_bf16_f32 v17, v34, v35
	v_cvt_pk_bf16_f32 v18, v36, v37
	v_cvt_pk_bf16_f32 v19, v38, v39
	v_lshlrev_b64 v[0:1], 8, v[0:1]
	ds_write2_b64 v130, v[112:113], v[114:115] offset1:2
	v_cvt_pk_bf16_f32 v112, v120, v121
	v_cvt_pk_bf16_f32 v113, v122, v123
	v_cvt_pk_bf16_f32 v114, v124, v125
	v_cvt_pk_bf16_f32 v115, v126, v127
	ds_write2_b64 v52, v[48:49], v[50:51] offset0:128 offset1:130
	v_cvt_pk_bf16_f32 v48, v72, v73
	v_cvt_pk_bf16_f32 v49, v74, v75
	v_cvt_pk_bf16_f32 v50, v76, v77
	v_cvt_pk_bf16_f32 v51, v78, v79
	ds_write2_b64 v20, v[16:17], v[18:19] offset0:192 offset1:194
	v_cvt_pk_bf16_f32 v16, v40, v41
	v_cvt_pk_bf16_f32 v17, v42, v43
	v_cvt_pk_bf16_f32 v18, v44, v45
	v_cvt_pk_bf16_f32 v19, v46, v47
	v_lshl_add_u64 v[0:1], v[82:83], 0, v[0:1]
	ds_write2_b64 v130, v[112:113], v[114:115] offset0:4 offset1:6
	ds_write2_b64 v52, v[48:49], v[50:51] offset0:132 offset1:134
	ds_write2_b64 v20, v[16:17], v[18:19] offset0:196 offset1:198
	s_waitcnt lgkmcnt(0)
	s_barrier
	global_load_dwordx4 v[0:3], v[0:1], off
	v_add_u32_e32 v4, 0x200, v128
	v_ashrrev_i32_e32 v111, 4, v4
	v_add_u32_e32 v4, s16, v111
	v_ashrrev_i32_e32 v5, 31, v4
	v_lshlrev_b64 v[4:5], 8, v[4:5]
	v_lshl_add_u64 v[4:5], v[82:83], 0, v[4:5]
	global_load_dwordx4 v[4:7], v[4:5], off
	v_xor_b32_e32 v9, v110, v128
	v_lshlrev_b32_e32 v9, 4, v9
	v_and_b32_e32 v9, 0xf0, v9
	v_lshl_or_b32 v9, v110, 8, v9
	v_add_u32_e32 v109, 0x21000, v9
	v_lshrrev_b32_e32 v8, 5, v128
	v_and_b32_e32 v28, 15, v128
	v_lshl_add_u32 v29, v134, 8, v139
	s_movk_i32 s3, 0xffe0
	v_bfi_b32 v80, s3, v135, v128
	v_bitop3_b32 v24, v129, v28, 2 bitop3:0x36
	v_lshl_or_b32 v107, v24, 4, v29
	v_lshlrev_b32_e32 v85, 2, v129
	v_xor_b32_e32 v127, 0x7f, v85
	v_xor_b32_e32 v126, 0x7e, v85
	v_xor_b32_e32 v124, 0x7d, v85
	v_xor_b32_e32 v125, 0x7c, v85
	v_xor_b32_e32 v121, 0x77, v85
	v_xor_b32_e32 v120, 0x76, v85
	v_xor_b32_e32 v122, 0x75, v85
	v_xor_b32_e32 v123, 0x74, v85
	v_xor_b32_e32 v115, 0x6f, v85
	v_xor_b32_e32 v114, 0x6e, v85
	v_xor_b32_e32 v112, 0x6d, v85
	v_xor_b32_e32 v113, 0x6c, v85
	v_xor_b32_e32 v117, 0x67, v85
	v_xor_b32_e32 v116, 0x66, v85
	v_xor_b32_e32 v118, 0x65, v85
	v_xor_b32_e32 v119, 0x64, v85
	v_xor_b32_e32 v155, 0x5f, v85
	v_xor_b32_e32 v153, 0x5e, v85
	v_xor_b32_e32 v150, 0x5d, v85
	v_xor_b32_e32 v151, 0x5c, v85
	v_xor_b32_e32 v148, 0x55, v85
	v_xor_b32_e32 v149, 0x54, v85
	s_or_b32 s3, s16, 64
	v_xor_b32_e32 v174, 63, v85
	v_xor_b32_e32 v173, 62, v85
	v_xor_b32_e32 v169, 61, v85
	v_xor_b32_e32 v172, 60, v85
	v_xor_b32_e32 v163, 55, v85
	v_xor_b32_e32 v162, 54, v85
	v_xor_b32_e32 v166, 53, v85
	v_xor_b32_e32 v167, 52, v85
	v_xor_b32_e32 v154, 39, v85
	v_xor_b32_e32 v152, 38, v85
	v_xor_b32_e32 v156, 37, v85
	v_xor_b32_e32 v158, 36, v85
	s_waitcnt vmcnt(1)
	ds_write_b128 v109, v[0:3]
	v_xor_b32_e32 v0, v111, v128
	v_lshlrev_b32_e32 v0, 4, v0
	v_and_b32_e32 v0, 0xf0, v0
	v_lshl_or_b32 v0, v111, 8, v0
	v_add_u32_e32 v108, 0x21000, v0
	v_bitop3_b32 v0, v8, v28, 1 bitop3:0x6c
	v_lshl_or_b32 v84, v0, 4, v29
	s_waitcnt vmcnt(0)
	ds_write_b128 v108, v[4:7]
	s_waitcnt lgkmcnt(0)
	s_barrier
	ds_read_b128 v[0:3], v84
	v_mul_lo_u32 v4, v80, s0
	v_lshl_add_u32 v81, v129, 4, v4
	ds_read_b128 v[20:23], v81
	ds_read_b128 v[16:19], v81 offset:32
	ds_read_b128 v[36:39], v84 offset:8192
	s_waitcnt lgkmcnt(2)
	v_mfma_f32_32x32x16_bf16 v[0:15], v[0:3], v[20:23], 0
	ds_read_b128 v[24:27], v107
	ds_read_b128 v[44:47], v107 offset:8192
	s_waitcnt lgkmcnt(1)
	v_mfma_f32_32x32x16_bf16 v[0:15], v[24:27], v[16:19], v[0:15]
	v_bitop3_b32 v24, v129, v28, 4 bitop3:0x36
	v_lshl_or_b32 v106, v24, 4, v29
	ds_read_b128 v[24:27], v106
	ds_read_b128 v[40:43], v81 offset:64
	ds_read_b128 v[32:35], v81 offset:96
	ds_read_b128 v[48:51], v106 offset:8192
	s_waitcnt lgkmcnt(2)
	v_mfma_f32_32x32x16_bf16 v[0:15], v[24:27], v[40:43], v[0:15]
	v_bitop3_b32 v24, v129, v28, 6 bitop3:0x36
	v_lshl_or_b32 v105, v24, 4, v29
	ds_read_b128 v[24:27], v105
	ds_read_b128 v[60:63], v105 offset:8192
	s_waitcnt lgkmcnt(1)
	v_mfma_f32_32x32x16_bf16 v[0:15], v[24:27], v[32:35], v[0:15]
	v_bitop3_b32 v24, v129, v28, 8 bitop3:0x36
	v_lshl_or_b32 v104, v24, 4, v29
	ds_read_b128 v[24:27], v104
	ds_read_b128 v[56:59], v81 offset:128
	ds_read_b128 v[52:55], v81 offset:160
	ds_read_b128 v[64:67], v104 offset:8192
	s_waitcnt lgkmcnt(2)
	v_mfma_f32_32x32x16_bf16 v[0:15], v[24:27], v[56:59], v[0:15]
	v_bitop3_b32 v24, v129, v28, 10 bitop3:0x36
	v_lshl_or_b32 v103, v24, 4, v29
	ds_read_b128 v[24:27], v103
	ds_read_b128 v[72:75], v103 offset:8192
	s_waitcnt lgkmcnt(1)
	v_mfma_f32_32x32x16_bf16 v[0:15], v[24:27], v[52:55], v[0:15]
	v_bitop3_b32 v24, v129, v28, 12 bitop3:0x36
	v_lshl_or_b32 v102, v24, 4, v29
	ds_read_b128 v[76:79], v102
	ds_read_b128 v[68:71], v81 offset:192
	ds_read_b128 v[24:27], v81 offset:224
	ds_read_b128 v[86:89], v102 offset:8192
	v_bitop3_b32 v28, v129, v28, 14 bitop3:0x36
	v_lshl_or_b32 v101, v28, 4, v29
	ds_read_b128 v[28:31], v101 offset:8192
	s_waitcnt lgkmcnt(3)
	v_mfma_f32_32x32x16_bf16 v[0:15], v[76:79], v[68:71], v[0:15]
	ds_read_b128 v[76:79], v101
	s_waitcnt lgkmcnt(0)
	s_barrier
	v_add_u32_e32 v248, s3, v110
	v_add_u32_e32 v250, s3, v111
	v_ashrrev_i32_e32 v249, 31, v248
	v_ashrrev_i32_e32 v251, 31, v250
	v_lshlrev_b64 v[248:249], 8, v[248:249]
	v_lshlrev_b64 v[250:251], 8, v[250:251]
	v_lshl_add_u64 v[248:249], v[82:83], 0, v[248:249]
	v_lshl_add_u64 v[250:251], v[82:83], 0, v[250:251]
	global_load_dwordx4 v[240:243], v[248:249], off
	global_load_dwordx4 v[244:247], v[250:251], off
	v_mfma_f32_32x32x16_bf16 v[0:15], v[76:79], v[24:27], v[0:15]
	s_nop 11
	v_ashrrev_i32_e32 v76, 31, v0
	v_ashrrev_i32_e32 v77, 31, v3
	v_ashrrev_i32_e32 v79, 31, v7
	v_ashrrev_i32_e32 v90, 31, v4
	v_ashrrev_i32_e32 v93, 31, v15
	v_ashrrev_i32_e32 v94, 31, v12
	v_ashrrev_i32_e32 v96, 31, v8
	v_ashrrev_i32_e32 v97, 31, v11
	v_bitop3_b32 v0, v76, v0, s76 bitop3:0x36
	v_ashrrev_i32_e32 v76, 31, v1
	v_bitop3_b32 v3, v77, v3, s76 bitop3:0x36
	v_ashrrev_i32_e32 v77, 31, v2
	v_bitop3_b32 v7, v79, v7, s76 bitop3:0x36
	v_ashrrev_i32_e32 v79, 31, v6
	v_bitop3_b32 v4, v90, v4, s76 bitop3:0x36
	v_ashrrev_i32_e32 v90, 31, v5
	v_bitop3_b32 v15, v93, v15, s76 bitop3:0x36
	v_ashrrev_i32_e32 v93, 31, v14
	v_bitop3_b32 v12, v94, v12, s76 bitop3:0x36
	v_ashrrev_i32_e32 v94, 31, v13
	v_bitop3_b32 v8, v96, v8, s76 bitop3:0x36
	v_ashrrev_i32_e32 v96, 31, v9
	v_bitop3_b32 v11, v97, v11, s76 bitop3:0x36
	v_ashrrev_i32_e32 v97, 31, v10
	v_bitop3_b32 v1, v76, v1, s76 bitop3:0x36
	v_bitop3_b32 v2, v77, v2, s76 bitop3:0x36
	v_bitop3_b32 v6, v79, v6, s76 bitop3:0x36
	v_bitop3_b32 v5, v90, v5, s76 bitop3:0x36
	v_bitop3_b32 v14, v93, v14, s76 bitop3:0x36
	v_bitop3_b32 v13, v94, v13, s76 bitop3:0x36
	v_bitop3_b32 v9, v96, v9, s76 bitop3:0x36
	v_bitop3_b32 v10, v97, v10, s76 bitop3:0x36
	v_and_or_b32 v0, v0, s77, v127
	v_and_or_b32 v1, v1, s77, v126
	v_and_or_b32 v3, v3, s77, v125
	v_and_or_b32 v2, v2, s77, v124
	v_and_or_b32 v7, v7, s77, v123
	v_and_or_b32 v6, v6, s77, v122
	v_and_or_b32 v4, v4, s77, v121
	v_and_or_b32 v5, v5, s77, v120
	v_and_or_b32 v15, v15, s77, v119
	v_and_or_b32 v14, v14, s77, v118
	v_and_or_b32 v12, v12, s77, v117
	v_and_or_b32 v13, v13, s77, v116
	v_and_or_b32 v8, v8, s77, v115
	v_and_or_b32 v9, v9, s77, v114
	v_and_or_b32 v11, v11, s77, v113
	v_and_or_b32 v10, v10, s77, v112
	v_max_u32_e32 v76, v0, v1
	v_min_u32_e32 v77, v3, v2
	v_min_u32_e32 v0, v0, v1
	v_max_u32_e32 v1, v3, v2
	v_max_u32_e32 v79, v7, v6
	v_min_u32_e32 v90, v4, v5
	v_min_u32_e32 v6, v7, v6
	v_max_u32_e32 v4, v4, v5
	v_max_u32_e32 v93, v15, v14
	v_min_u32_e32 v94, v12, v13
	v_min_u32_e32 v14, v15, v14
	v_max_u32_e32 v12, v12, v13
	v_max_u32_e32 v96, v8, v9
	v_min_u32_e32 v97, v11, v10
	v_min_u32_e32 v8, v8, v9
	v_max_u32_e32 v9, v11, v10
	v_max_u32_e32 v78, v76, v77
	v_max_u32_e32 v2, v0, v1
	v_min_u32_e32 v91, v79, v90
	v_min_u32_e32 v5, v6, v4
	v_min_u32_e32 v76, v76, v77
	v_min_u32_e32 v0, v0, v1
	v_max_u32_e32 v77, v79, v90
	v_max_u32_e32 v4, v6, v4
	v_max_u32_e32 v95, v93, v94
	v_max_u32_e32 v13, v14, v12
	v_min_u32_e32 v98, v96, v97
	v_min_u32_e32 v10, v8, v9
	v_min_u32_e32 v93, v93, v94
	v_min_u32_e32 v12, v14, v12
	v_max_u32_e32 v94, v96, v97
	v_max_u32_e32 v8, v8, v9
	v_max_u32_e32 v3, v78, v2
	v_min_u32_e32 v7, v91, v5
	v_max_u32_e32 v1, v76, v0
	v_min_u32_e32 v6, v77, v4
	v_min_u32_e32 v2, v78, v2
	v_max_u32_e32 v5, v91, v5
	v_min_u32_e32 v0, v76, v0
	v_max_u32_e32 v4, v77, v4
	v_max_u32_e32 v15, v95, v13
	v_min_u32_e32 v11, v98, v10
	v_max_u32_e32 v14, v93, v12
	v_min_u32_e32 v9, v94, v8
	v_min_u32_e32 v13, v95, v13
	v_max_u32_e32 v10, v98, v10
	v_min_u32_e32 v12, v93, v12
	v_max_u32_e32 v8, v94, v8
	v_max_u32_e32 v92, v3, v7
	v_max_u32_e32 v79, v1, v6
	v_max_u32_e32 v78, v2, v5
	v_max_u32_e32 v76, v0, v4
	v_min_u32_e32 v99, v15, v11
	v_min_u32_e32 v96, v14, v9
	v_min_u32_e32 v95, v13, v10
	v_min_u32_e32 v93, v12, v8
	v_min_u32_e32 v3, v3, v7
	v_min_u32_e32 v1, v1, v6
	v_min_u32_e32 v2, v2, v5
	v_min_u32_e32 v0, v0, v4
	v_max_u32_e32 v5, v15, v11
	v_max_u32_e32 v7, v14, v9
	v_max_u32_e32 v10, v13, v10
	v_max_u32_e32 v8, v12, v8
	v_max_u32_e32 v90, v92, v79
	v_max_u32_e32 v77, v78, v76
	v_min_u32_e32 v97, v99, v96
	v_min_u32_e32 v94, v95, v93
	v_max_u32_e32 v6, v3, v1
	v_max_u32_e32 v4, v2, v0
	v_min_u32_e32 v9, v5, v7
	v_min_u32_e32 v11, v10, v8
	v_min_u32_e32 v12, v92, v79
	v_min_u32_e32 v13, v78, v76
	v_max_u32_e32 v91, v90, v77
	v_min_u32_e32 v98, v97, v94
	v_max_u32_e32 v129, v6, v4
	v_min_u32_e32 v130, v9, v11
	v_max_u32_e32 v78, v12, v13
	v_max_u32_e32 v79, v99, v96
	v_min_u32_e32 v96, v3, v1
	v_min_u32_e32 v99, v2, v0
	v_max_u32_e32 v135, v5, v7
	v_max_u32_e32 v136, v10, v8
	v_min_u32_e32 v77, v90, v77
	v_max_u32_e32 v90, v97, v94
	v_min_u32_e32 v97, v6, v4
	v_max_u32_e32 v144, v9, v11
	v_min_u32_e32 v147, v12, v13
	v_mfma_f32_32x32x16_bf16 v[0:15], v[36:39], v[20:23], 0
	v_max_u32_e32 v92, v95, v93
	v_min_u32_e32 v93, v79, v92
	v_max_u32_e32 v134, v96, v99
	v_min_u32_e32 v137, v135, v136
	v_max_u32_e32 v39, v79, v92
	v_min_u32_e32 v79, v96, v99
	v_max_u32_e32 v92, v135, v136
	v_mfma_f32_32x32x16_bf16 v[0:15], v[44:47], v[16:19], v[0:15]
	v_min_u32_e32 v100, v91, v98
	v_min_u32_e32 v131, v129, v130
	v_min_u32_e32 v95, v78, v93
	v_min_u32_e32 v142, v134, v137
	v_min_u32_e32 v94, v77, v90
	v_min_u32_e32 v145, v97, v144
	v_min_u32_e32 v22, v147, v39
	v_mfma_f32_32x32x16_bf16 v[0:15], v[48:51], v[40:43], v[0:15]
	v_min_u32_e32 v23, v79, v92
	v_max_u32_e32 v45, v77, v90
	v_max_u32_e32 v46, v97, v144
	v_max_u32_e32 v48, v147, v39
	v_max_u32_e32 v49, v79, v92
	v_min_u32_e32 v146, v94, v145
	v_min_u32_e32 v21, v22, v23
	v_mfma_f32_32x32x16_bf16 v[0:15], v[60:63], v[32:35], v[0:15]
	v_max_u32_e32 v36, v100, v131
	v_max_u32_e32 v37, v95, v142
	v_max_u32_e32 v38, v94, v145
	v_max_u32_e32 v40, v22, v23
	v_max_u32_e32 v41, v91, v98
	v_max_u32_e32 v42, v129, v130
	v_max_u32_e32 v43, v78, v93
	v_mfma_f32_32x32x16_bf16 v[0:15], v[64:67], v[56:59], v[0:15]
	v_max_u32_e32 v44, v134, v137
	v_min_u32_e32 v47, v45, v46
	v_min_u32_e32 v39, v48, v49
	v_min_u32_e32 v20, v146, v21
	v_max_u32_e32 v18, v146, v21
	v_min_u32_e32 v21, v36, v37
	v_min_u32_e32 v22, v38, v40
	v_mfma_f32_32x32x16_bf16 v[0:15], v[72:75], v[52:55], v[0:15]
	v_max_u32_e32 v36, v36, v37
	v_max_u32_e32 v37, v38, v40
	v_min_u32_e32 v40, v43, v44
	v_min_u32_e32 v33, v47, v39
	v_max_u32_e32 v39, v47, v39
	v_max_u32_e32 v47, v41, v42
	v_max_u32_e32 v44, v43, v44
	v_mfma_f32_32x32x16_bf16 v[0:15], v[86:89], v[68:71], v[0:15]
	v_min_u32_e32 v35, v41, v42
	v_min_u32_e32 v41, v47, v44
	v_max_u32_e32 v45, v45, v46
	v_max_u32_e32 v46, v48, v49
	v_max_u32_e32 v44, v47, v44
	v_min_u32_e32 v132, v100, v131
	v_min_u32_e32 v143, v95, v142
	v_mfma_f32_32x32x16_bf16 v[0:15], v[28:31], v[24:27], v[0:15]
	v_min_u32_e32 v76, v132, v143
	v_max_u32_e32 v17, v132, v143
	v_xor_b32_e32 v144, 0x57, v85
	v_xor_b32_e32 v143, 0x56, v85
	v_xor_b32_e32 v132, 0x4f, v85
	v_xor_b32_e32 v131, 0x4e, v85
	v_xor_b32_e32 v129, 0x4d, v85
	s_nop 4
	v_ashrrev_i32_e32 v24, 31, v0
	v_ashrrev_i32_e32 v25, 31, v3
	v_ashrrev_i32_e32 v27, 31, v7
	v_ashrrev_i32_e32 v28, 31, v4
	v_ashrrev_i32_e32 v31, 31, v15
	v_ashrrev_i32_e32 v47, 31, v12
	v_ashrrev_i32_e32 v49, 31, v8
	v_ashrrev_i32_e32 v50, 31, v11
	v_bitop3_b32 v0, v24, v0, s76 bitop3:0x36
	v_ashrrev_i32_e32 v24, 31, v1
	v_bitop3_b32 v3, v25, v3, s76 bitop3:0x36
	v_ashrrev_i32_e32 v25, 31, v2
	v_bitop3_b32 v7, v27, v7, s76 bitop3:0x36
	v_ashrrev_i32_e32 v27, 31, v6
	v_bitop3_b32 v4, v28, v4, s76 bitop3:0x36
	v_ashrrev_i32_e32 v28, 31, v5
	v_bitop3_b32 v15, v31, v15, s76 bitop3:0x36
	v_ashrrev_i32_e32 v31, 31, v14
	v_bitop3_b32 v12, v47, v12, s76 bitop3:0x36
	v_ashrrev_i32_e32 v47, 31, v13
	v_bitop3_b32 v8, v49, v8, s76 bitop3:0x36
	v_ashrrev_i32_e32 v49, 31, v9
	v_bitop3_b32 v11, v50, v11, s76 bitop3:0x36
	v_ashrrev_i32_e32 v50, 31, v10
	v_xor_b32_e32 v130, 0x4c, v85
	v_xor_b32_e32 v135, 0x47, v85
	v_xor_b32_e32 v134, 0x46, v85
	v_xor_b32_e32 v136, 0x45, v85
	v_xor_b32_e32 v137, 0x44, v85
	v_bitop3_b32 v1, v24, v1, s76 bitop3:0x36
	v_bitop3_b32 v2, v25, v2, s76 bitop3:0x36
	v_bitop3_b32 v6, v27, v6, s76 bitop3:0x36
	v_bitop3_b32 v5, v28, v5, s76 bitop3:0x36
	v_bitop3_b32 v14, v31, v14, s76 bitop3:0x36
	v_bitop3_b32 v13, v47, v13, s76 bitop3:0x36
	v_bitop3_b32 v9, v49, v9, s76 bitop3:0x36
	v_bitop3_b32 v10, v50, v10, s76 bitop3:0x36
	v_and_or_b32 v0, v0, s77, v155
	v_and_or_b32 v1, v1, s77, v153
	v_and_or_b32 v3, v3, s77, v151
	v_and_or_b32 v2, v2, s77, v150
	v_and_or_b32 v7, v7, s77, v149
	v_and_or_b32 v6, v6, s77, v148
	v_and_or_b32 v4, v4, s77, v144
	v_and_or_b32 v5, v5, s77, v143
	v_and_or_b32 v15, v15, s77, v137
	v_and_or_b32 v14, v14, s77, v136
	v_and_or_b32 v12, v12, s77, v135
	v_and_or_b32 v13, v13, s77, v134
	v_and_or_b32 v8, v8, s77, v132
	v_and_or_b32 v9, v9, s77, v131
	v_and_or_b32 v11, v11, s77, v130
	v_and_or_b32 v10, v10, s77, v129
	v_max_u32_e32 v24, v0, v1
	v_min_u32_e32 v25, v3, v2
	v_min_u32_e32 v0, v0, v1
	v_max_u32_e32 v1, v3, v2
	v_max_u32_e32 v27, v7, v6
	v_min_u32_e32 v28, v4, v5
	v_min_u32_e32 v6, v7, v6
	v_max_u32_e32 v4, v4, v5
	v_max_u32_e32 v31, v15, v14
	v_min_u32_e32 v47, v12, v13
	v_min_u32_e32 v14, v15, v14
	v_max_u32_e32 v12, v12, v13
	v_max_u32_e32 v49, v8, v9
	v_min_u32_e32 v50, v11, v10
	v_min_u32_e32 v8, v8, v9
	v_max_u32_e32 v9, v11, v10
	v_max_u32_e32 v26, v24, v25
	v_max_u32_e32 v2, v0, v1
	v_min_u32_e32 v29, v27, v28
	v_min_u32_e32 v5, v6, v4
	v_min_u32_e32 v24, v24, v25
	v_min_u32_e32 v0, v0, v1
	v_max_u32_e32 v25, v27, v28
	v_max_u32_e32 v4, v6, v4
	v_max_u32_e32 v48, v31, v47
	v_max_u32_e32 v13, v14, v12
	v_min_u32_e32 v51, v49, v50
	v_min_u32_e32 v10, v8, v9
	v_min_u32_e32 v31, v31, v47
	v_min_u32_e32 v12, v14, v12
	v_max_u32_e32 v47, v49, v50
	v_max_u32_e32 v8, v8, v9
	v_max_u32_e32 v3, v26, v2
	v_min_u32_e32 v7, v29, v5
	v_max_u32_e32 v1, v24, v0
	v_min_u32_e32 v6, v25, v4
	v_min_u32_e32 v2, v26, v2
	v_max_u32_e32 v5, v29, v5
	v_min_u32_e32 v0, v24, v0
	v_max_u32_e32 v4, v25, v4
	v_max_u32_e32 v15, v48, v13
	v_min_u32_e32 v11, v51, v10
	v_max_u32_e32 v14, v31, v12
	v_min_u32_e32 v9, v47, v8
	v_max_u32_e32 v30, v3, v7
	v_max_u32_e32 v27, v1, v6
	v_max_u32_e32 v26, v2, v5
	v_max_u32_e32 v24, v0, v4
	v_min_u32_e32 v52, v15, v11
	v_min_u32_e32 v49, v14, v9
	v_min_u32_e32 v2, v2, v5
	v_min_u32_e32 v0, v0, v4
	v_max_u32_e32 v28, v30, v27
	v_min_u32_e32 v50, v52, v49
	v_min_u32_e32 v13, v48, v13
	v_max_u32_e32 v10, v51, v10
	v_min_u32_e32 v12, v31, v12
	v_max_u32_e32 v8, v47, v8
	v_min_u32_e32 v3, v3, v7
	v_min_u32_e32 v1, v1, v6
	v_max_u32_e32 v4, v2, v0
	v_max_u32_e32 v5, v15, v11
	v_min_u32_e32 v15, v30, v27
	v_max_u32_e32 v27, v52, v49
	v_min_u32_e32 v52, v2, v0
	v_add_u32_e32 v0, s3, v110
	v_add_u32_e32 v2, s3, v111
	v_min_u32_e32 v48, v13, v10
	v_min_u32_e32 v31, v12, v8
	v_max_u32_e32 v6, v3, v1
	v_min_u32_e32 v49, v3, v1
	v_ashrrev_i32_e32 v1, 31, v0
	v_ashrrev_i32_e32 v3, 31, v2
	v_max_u32_e32 v25, v26, v24
	v_min_u32_e32 v47, v48, v31
	v_max_u32_e32 v7, v14, v9
	v_lshlrev_b64 v[0:1], 8, v[0:1]
	v_lshlrev_b64 v[2:3], 8, v[2:3]
	v_max_u32_e32 v29, v28, v25
	v_min_u32_e32 v51, v50, v47
	v_max_u32_e32 v54, v6, v4
	v_min_u32_e32 v9, v5, v7
	v_max_u32_e32 v56, v5, v7
	v_min_u32_e32 v25, v28, v25
	v_max_u32_e32 v28, v50, v47
	v_min_u32_e32 v50, v6, v4
	v_lshl_add_u64 v[0:1], v[82:83], 0, v[0:1]
	v_lshl_add_u64 v[4:5], v[82:83], 0, v[2:3]
	s_nop 0
	v_max_u32_e32 v10, v13, v10
	v_max_u32_e32 v8, v12, v8
	v_min_u32_e32 v11, v10, v8
	v_min_u32_e32 v24, v26, v24
	v_max_u32_e32 v30, v48, v31
	v_max_u32_e32 v8, v10, v8
	v_min_u32_e32 v12, v9, v11
	v_max_u32_e32 v26, v15, v24
	v_min_u32_e32 v31, v27, v30
	v_max_u32_e32 v55, v49, v52
	v_min_u32_e32 v10, v56, v8
	v_min_u32_e32 v53, v29, v51
	v_min_u32_e32 v13, v54, v12
	v_min_u32_e32 v48, v26, v31
	v_min_u32_e32 v57, v55, v10
	v_max_u32_e32 v9, v9, v11
	v_min_u32_e32 v15, v15, v24
	v_max_u32_e32 v24, v27, v30
	v_min_u32_e32 v30, v49, v52
	v_max_u32_e32 v8, v56, v8
	v_min_u32_e32 v14, v53, v13
	v_min_u32_e32 v58, v48, v57
	v_min_u32_e32 v47, v25, v28
	v_min_u32_e32 v11, v50, v9
	v_min_u32_e32 v27, v15, v24
	v_min_u32_e32 v49, v30, v8
	v_max_u32_e32 v13, v53, v13
	v_max_u32_e32 v48, v48, v57
	v_max_u32_e32 v29, v29, v51
	v_max_u32_e32 v12, v54, v12
	v_max_u32_e32 v26, v26, v31
	v_max_u32_e32 v10, v55, v10
	v_max_u32_e32 v25, v25, v28
	v_max_u32_e32 v9, v50, v9
	v_max_u32_e32 v15, v15, v24
	v_max_u32_e32 v8, v30, v8
	v_min_u32_e32 v60, v47, v11
	v_min_u32_e32 v52, v27, v49
	v_min_u32_e32 v53, v13, v48
	v_max_u32_e32 v11, v47, v11
	v_max_u32_e32 v27, v27, v49
	v_max_u32_e32 v13, v13, v48
	v_min_u32_e32 v48, v29, v12
	v_min_u32_e32 v31, v26, v10
	v_min_u32_e32 v28, v25, v9
	v_min_u32_e32 v24, v15, v8
	v_max_u32_e32 v12, v29, v12
	v_max_u32_e32 v10, v26, v10
	v_max_u32_e32 v9, v25, v9
	v_max_u32_e32 v8, v15, v8
	s_waitcnt vmcnt(1)
	ds_write_b128 v109, v[240:243]
	s_waitcnt vmcnt(0)
	ds_write_b128 v108, v[244:247]
	s_waitcnt lgkmcnt(0)
	s_barrier
	ds_read_b128 v[0:3], v84
	v_min_u32_e32 v32, v35, v40
	v_min_u32_e32 v59, v14, v58
	v_min_u32_e32 v56, v60, v52
	v_min_u32_e32 v47, v11, v27
	v_min_u32_e32 v51, v48, v31
	v_min_u32_e32 v30, v28, v24
	v_min_u32_e32 v26, v12, v10
	v_min_u32_e32 v15, v9, v8
	v_min_u32_e32 v34, v32, v33
	v_max_u32_e32 v35, v35, v40
	v_min_u32_e32 v42, v45, v46
	v_max_u32_e32 v45, v45, v46
	v_min_u32_e32 v61, v59, v56
	v_min_u32_e32 v49, v53, v47
	v_max_u32_e32 v11, v11, v27
	v_min_u32_e32 v50, v51, v30
	v_max_u32_e32 v31, v48, v31
	v_max_u32_e32 v24, v28, v24
	v_min_u32_e32 v25, v26, v15
	v_min_u32_e32 v16, v76, v20
	v_min_u32_e32 v19, v17, v18
	v_min_u32_e32 v23, v21, v22
	v_min_u32_e32 v38, v36, v37
	v_min_u32_e32 v40, v35, v39
	v_min_u32_e32 v27, v13, v11
	v_min_u32_e32 v28, v31, v24
	v_max_u32_e32 v10, v12, v10
	v_max_u32_e32 v8, v9, v8
	v_max3_u32 v12, v44, v45, v61
	v_max3_u32 v35, v35, v39, v49
	v_max3_u32 v11, v34, v13, v11
	v_max3_u32 v13, v36, v37, v50
	v_max3_u32 v17, v17, v18, v25
	v_min_u32_e32 v9, v10, v8
	v_max3_u32 v30, v38, v51, v30
	v_max3_u32 v21, v21, v22, v28
	v_max3_u32 v22, v23, v31, v24
	v_max3_u32 v15, v19, v26, v15
	v_max3_u32 v8, v16, v10, v8
	v_max_u32_e32 v10, v12, v13
	v_min_u32_e32 v31, v12, v13
	v_max_u32_e32 v13, v35, v17
	v_min_u32_e32 v38, v35, v17
	ds_read_b128 v[16:19], v81
	v_max_u32_e32 v14, v14, v58
	v_max_u32_e32 v52, v60, v52
	v_min_u32_e32 v43, v41, v42
	v_min_u32_e32 v46, v44, v45
	v_min_u32_e32 v58, v14, v52
	v_max3_u32 v29, v46, v59, v56
	v_max3_u32 v41, v41, v42, v58
	v_max3_u32 v14, v43, v14, v52
	v_max3_u32 v42, v40, v53, v47
	v_max3_u32 v27, v32, v33, v27
	v_max3_u32 v9, v76, v20, v9
	v_max_u32_e32 v12, v29, v30
	v_max_u32_e32 v40, v14, v22
	v_min_u32_e32 v28, v14, v22
	v_max_u32_e32 v14, v42, v15
	v_min_u32_e32 v29, v29, v30
	v_max_u32_e32 v39, v41, v21
	v_min_u32_e32 v30, v41, v21
	v_min_u32_e32 v36, v42, v15
	v_max_u32_e32 v41, v27, v9
	v_min_u32_e32 v37, v27, v9
	v_max_u32_e32 v42, v11, v8
	v_min_u32_e32 v56, v11, v8
	v_max_u32_e32 v55, v10, v13
	v_min_u32_e32 v52, v10, v13
	v_max_u32_e32 v54, v12, v14
	v_min_u32_e32 v53, v12, v14
	s_waitcnt lgkmcnt(0)
	v_mfma_f32_32x32x16_bf16 v[0:15], v[0:3], v[16:19], 0
	ds_read_b128 v[24:27], v107
	ds_read_b128 v[20:23], v81 offset:32
	ds_read_b128 v[32:35], v84 offset:8192
	v_max_u32_e32 v57, v39, v41
	v_min_u32_e32 v64, v39, v41
	v_max_u32_e32 v65, v40, v42
	v_min_u32_e32 v66, v40, v42
	ds_read_b128 v[58:61], v106
	ds_read_b128 v[44:47], v107 offset:8192
	ds_read_b128 v[40:43], v81 offset:64
	s_waitcnt lgkmcnt(4)
	v_mfma_f32_32x32x16_bf16 v[0:15], v[24:27], v[20:23], v[0:15]
	v_max_u32_e32 v68, v31, v38
	v_min_u32_e32 v69, v31, v38
	v_max_u32_e32 v70, v29, v36
	v_min_u32_e32 v76, v29, v36
	v_max_u32_e32 v71, v30, v37
	v_min_u32_e32 v77, v30, v37
	ds_read_b128 v[24:27], v105
	ds_read_b128 v[36:39], v81 offset:96
	ds_read_b128 v[48:51], v106 offset:8192
	s_waitcnt lgkmcnt(3)
	v_mfma_f32_32x32x16_bf16 v[0:15], v[58:61], v[40:43], v[0:15]
	v_max_u32_e32 v72, v28, v56
	v_min_u32_e32 v78, v28, v56
	v_max_u32_e32 v90, v55, v57
	v_min_u32_e32 v91, v55, v57
	ds_read_b128 v[28:31], v104
	ds_read_b128 v[60:63], v105 offset:8192
	ds_read_b128 v[56:59], v81 offset:128
	v_max_u32_e32 v92, v54, v65
	s_waitcnt lgkmcnt(4)
	v_mfma_f32_32x32x16_bf16 v[0:15], v[24:27], v[36:39], v[0:15]
	v_min_u32_e32 v93, v54, v65
	v_max_u32_e32 v94, v52, v64
	v_min_u32_e32 v95, v52, v64
	v_max_u32_e32 v96, v53, v66
	v_min_u32_e32 v97, v53, v66
	ds_read_b128 v[24:27], v103
	ds_read_b128 v[52:55], v81 offset:160
	ds_read_b128 v[64:67], v104 offset:8192
	v_max_u32_e32 v98, v68, v71
	s_waitcnt lgkmcnt(3)
	v_mfma_f32_32x32x16_bf16 v[0:15], v[28:31], v[56:59], v[0:15]
	v_min_u32_e32 v99, v68, v71
	v_max_u32_e32 v100, v70, v72
	v_min_u32_e32 v157, v70, v72
	v_max_u32_e32 v159, v69, v77
	ds_read_b128 v[28:31], v102
	ds_read_b128 v[72:75], v103 offset:8192
	v_min_u32_e32 v160, v69, v77
	ds_read_b128 v[68:71], v81 offset:192
	s_waitcnt lgkmcnt(4)
	v_mfma_f32_32x32x16_bf16 v[0:15], v[24:27], v[52:55], v[0:15]
	v_max_u32_e32 v161, v76, v78
	v_min_u32_e32 v164, v76, v78
	ds_read_b128 v[86:89], v101
	ds_read_b128 v[24:27], v81 offset:224
	ds_read_b128 v[76:79], v102 offset:8192
	v_xor_b32_e32 v147, 47, v85
	v_xor_b32_e32 v146, 46, v85
	v_xor_b32_e32 v142, 45, v85
	v_xor_b32_e32 v145, 44, v85
	s_waitcnt lgkmcnt(3)
	v_mfma_f32_32x32x16_bf16 v[0:15], v[28:31], v[68:71], v[0:15]
	v_min_u32_e32 v165, v90, v92
	v_min_u32_e32 v168, v91, v93
	v_min_u32_e32 v175, v95, v97
	v_min_u32_e32 v179, v98, v100
	v_min_u32_e32 v170, v94, v96
	v_min_u32_e32 v180, v99, v157
	v_min_u32_e32 v181, v159, v161
	s_waitcnt lgkmcnt(1)
	v_mfma_f32_32x32x16_bf16 v[0:15], v[86:89], v[24:27], v[0:15]
	v_min_u32_e32 v182, v160, v164
	ds_read_b128 v[28:31], v101 offset:8192
	s_or_b32 s3, s16, 0x80
	s_waitcnt lgkmcnt(0)
	s_barrier
	v_add_u32_e32 v248, s3, v110
	v_add_u32_e32 v250, s3, v111
	v_ashrrev_i32_e32 v249, 31, v248
	v_ashrrev_i32_e32 v251, 31, v250
	v_lshlrev_b64 v[248:249], 8, v[248:249]
	v_lshlrev_b64 v[250:251], 8, v[250:251]
	v_lshl_add_u64 v[248:249], v[82:83], 0, v[248:249]
	v_lshl_add_u64 v[250:251], v[82:83], 0, v[250:251]
	global_load_dwordx4 v[240:243], v[248:249], off
	global_load_dwordx4 v[244:247], v[250:251], off
	s_nop 6
	v_ashrrev_i32_e32 v86, 31, v0
	v_ashrrev_i32_e32 v87, 31, v3
	v_ashrrev_i32_e32 v89, 31, v7
	v_ashrrev_i32_e32 v183, 31, v4
	v_ashrrev_i32_e32 v186, 31, v15
	v_ashrrev_i32_e32 v187, 31, v12
	v_ashrrev_i32_e32 v189, 31, v8
	v_ashrrev_i32_e32 v190, 31, v11
	v_bitop3_b32 v0, v86, v0, s76 bitop3:0x36
	v_ashrrev_i32_e32 v86, 31, v1
	v_bitop3_b32 v3, v87, v3, s76 bitop3:0x36
	v_ashrrev_i32_e32 v87, 31, v2
	v_bitop3_b32 v7, v89, v7, s76 bitop3:0x36
	v_ashrrev_i32_e32 v89, 31, v6
	v_bitop3_b32 v4, v183, v4, s76 bitop3:0x36
	v_ashrrev_i32_e32 v183, 31, v5
	v_bitop3_b32 v15, v186, v15, s76 bitop3:0x36
	v_ashrrev_i32_e32 v186, 31, v14
	v_bitop3_b32 v12, v187, v12, s76 bitop3:0x36
	v_ashrrev_i32_e32 v187, 31, v13
	v_bitop3_b32 v8, v189, v8, s76 bitop3:0x36
	v_ashrrev_i32_e32 v189, 31, v9
	v_bitop3_b32 v11, v190, v11, s76 bitop3:0x36
	v_ashrrev_i32_e32 v190, 31, v10
	v_bitop3_b32 v1, v86, v1, s76 bitop3:0x36
	v_bitop3_b32 v2, v87, v2, s76 bitop3:0x36
	v_bitop3_b32 v6, v89, v6, s76 bitop3:0x36
	v_bitop3_b32 v5, v183, v5, s76 bitop3:0x36
	v_bitop3_b32 v14, v186, v14, s76 bitop3:0x36
	v_bitop3_b32 v13, v187, v13, s76 bitop3:0x36
	v_bitop3_b32 v9, v189, v9, s76 bitop3:0x36
	v_bitop3_b32 v10, v190, v10, s76 bitop3:0x36
	v_and_or_b32 v0, v0, s77, v174
	v_and_or_b32 v1, v1, s77, v173
	v_and_or_b32 v3, v3, s77, v172
	v_and_or_b32 v2, v2, s77, v169
	v_and_or_b32 v7, v7, s77, v167
	v_and_or_b32 v6, v6, s77, v166
	v_and_or_b32 v4, v4, s77, v163
	v_and_or_b32 v5, v5, s77, v162
	v_and_or_b32 v15, v15, s77, v158
	v_and_or_b32 v14, v14, s77, v156
	v_and_or_b32 v12, v12, s77, v154
	v_and_or_b32 v13, v13, s77, v152
	v_and_or_b32 v8, v8, s77, v147
	v_and_or_b32 v9, v9, s77, v146
	v_and_or_b32 v11, v11, s77, v145
	v_and_or_b32 v10, v10, s77, v142
	v_max_u32_e32 v86, v0, v1
	v_min_u32_e32 v87, v3, v2
	v_min_u32_e32 v0, v0, v1
	v_max_u32_e32 v1, v3, v2
	v_max_u32_e32 v89, v7, v6
	v_min_u32_e32 v183, v4, v5
	v_min_u32_e32 v6, v7, v6
	v_max_u32_e32 v4, v4, v5
	v_max_u32_e32 v186, v15, v14
	v_min_u32_e32 v187, v12, v13
	v_min_u32_e32 v14, v15, v14
	v_max_u32_e32 v12, v12, v13
	v_max_u32_e32 v189, v8, v9
	v_min_u32_e32 v190, v11, v10
	v_min_u32_e32 v8, v8, v9
	v_max_u32_e32 v9, v11, v10
	v_max_u32_e32 v88, v86, v87
	v_max_u32_e32 v2, v0, v1
	v_min_u32_e32 v184, v89, v183
	v_min_u32_e32 v5, v6, v4
	v_min_u32_e32 v86, v86, v87
	v_min_u32_e32 v0, v0, v1
	v_max_u32_e32 v87, v89, v183
	v_max_u32_e32 v4, v6, v4
	v_max_u32_e32 v188, v186, v187
	v_max_u32_e32 v13, v14, v12
	v_min_u32_e32 v191, v189, v190
	v_min_u32_e32 v10, v8, v9
	v_min_u32_e32 v186, v186, v187
	v_min_u32_e32 v12, v14, v12
	v_max_u32_e32 v187, v189, v190
	v_max_u32_e32 v8, v8, v9
	v_max_u32_e32 v3, v88, v2
	v_min_u32_e32 v7, v184, v5
	v_max_u32_e32 v1, v86, v0
	v_min_u32_e32 v6, v87, v4
	v_min_u32_e32 v2, v88, v2
	v_max_u32_e32 v5, v184, v5
	v_min_u32_e32 v0, v86, v0
	v_max_u32_e32 v4, v87, v4
	v_max_u32_e32 v15, v188, v13
	v_min_u32_e32 v11, v191, v10
	v_max_u32_e32 v14, v186, v12
	v_min_u32_e32 v9, v187, v8
	v_min_u32_e32 v13, v188, v13
	v_max_u32_e32 v10, v191, v10
	v_min_u32_e32 v12, v186, v12
	v_max_u32_e32 v8, v187, v8
	v_max_u32_e32 v185, v3, v7
	v_max_u32_e32 v89, v1, v6
	v_max_u32_e32 v88, v2, v5
	v_max_u32_e32 v86, v0, v4
	v_min_u32_e32 v192, v15, v11
	v_min_u32_e32 v189, v14, v9
	v_min_u32_e32 v188, v13, v10
	v_min_u32_e32 v186, v12, v8
	v_min_u32_e32 v3, v3, v7
	v_min_u32_e32 v1, v1, v6
	v_min_u32_e32 v2, v2, v5
	v_min_u32_e32 v0, v0, v4
	v_max_u32_e32 v7, v15, v11
	v_max_u32_e32 v9, v14, v9
	v_max_u32_e32 v10, v13, v10
	v_max_u32_e32 v8, v12, v8
	v_max_u32_e32 v183, v185, v89
	v_max_u32_e32 v87, v88, v86
	v_min_u32_e32 v190, v192, v189
	v_min_u32_e32 v187, v188, v186
	v_max_u32_e32 v6, v3, v1
	v_max_u32_e32 v4, v2, v0
	v_min_u32_e32 v11, v7, v9
	v_min_u32_e32 v12, v10, v8
	v_min_u32_e32 v89, v185, v89
	v_min_u32_e32 v86, v88, v86
	v_max_u32_e32 v185, v192, v189
	v_max_u32_e32 v186, v188, v186
	v_min_u32_e32 v1, v3, v1
	v_min_u32_e32 v0, v2, v0
	v_max_u32_e32 v3, v7, v9
	v_max_u32_e32 v7, v10, v8
	v_max_u32_e32 v184, v183, v87
	v_min_u32_e32 v191, v190, v187
	v_max_u32_e32 v5, v6, v4
	v_min_u32_e32 v13, v11, v12
	v_max_u32_e32 v88, v89, v86
	v_min_u32_e32 v188, v185, v186
	v_max_u32_e32 v2, v1, v0
	v_min_u32_e32 v8, v3, v7
	v_min_u32_e32 v193, v184, v191
	v_min_u32_e32 v14, v5, v13
	v_min_u32_e32 v189, v88, v188
	v_min_u32_e32 v9, v2, v8
	v_min_u32_e32 v15, v193, v14
	v_min_u32_e32 v10, v189, v9
	v_min_u32_e32 v87, v183, v87
	v_max_u32_e32 v183, v190, v187
	v_min_u32_e32 v4, v6, v4
	v_max_u32_e32 v6, v11, v12
	v_min_u32_e32 v86, v89, v86
	v_max_u32_e32 v89, v185, v186
	v_min_u32_e32 v0, v1, v0
	v_max_u32_e32 v1, v3, v7
	v_max_u32_e32 v14, v193, v14
	v_max_u32_e32 v9, v189, v9
	v_min_u32_e32 v192, v15, v10
	v_min_u32_e32 v187, v87, v183
	v_min_u32_e32 v11, v4, v6
	v_min_u32_e32 v185, v86, v89
	v_min_u32_e32 v3, v0, v1
	v_max_u32_e32 v10, v15, v10
	v_min_u32_e32 v15, v14, v9
	v_max_u32_e32 v9, v14, v9
	v_max_u32_e32 v14, v184, v191
	v_max_u32_e32 v5, v5, v13
	v_max_u32_e32 v88, v88, v188
	v_max_u32_e32 v2, v2, v8
	v_max_u32_e32 v87, v87, v183
	v_max_u32_e32 v4, v4, v6
	v_max_u32_e32 v86, v86, v89
	v_max_u32_e32 v0, v0, v1
	v_min_u32_e32 v12, v187, v11
	v_min_u32_e32 v7, v185, v3
	v_min_u32_e32 v13, v14, v5
	v_min_u32_e32 v8, v88, v2
	v_min_u32_e32 v6, v87, v4
	v_min_u32_e32 v1, v86, v0
	v_min_u32_e32 v186, v12, v7
	v_max_u32_e32 v7, v12, v7
	v_max_u32_e32 v11, v187, v11
	v_max_u32_e32 v3, v185, v3
	v_min_u32_e32 v184, v13, v8
	v_min_u32_e32 v89, v6, v1
	v_max_u32_e32 v8, v13, v8
	v_max_u32_e32 v1, v6, v1
	v_max_u32_e32 v5, v14, v5
	v_max_u32_e32 v2, v88, v2
	v_max_u32_e32 v4, v87, v4
	v_max_u32_e32 v0, v86, v0
	v_min_u32_e32 v190, v192, v186
	v_min_u32_e32 v12, v10, v7
	v_min_u32_e32 v185, v11, v3
	v_max_u32_e32 v3, v11, v3
	v_min_u32_e32 v183, v184, v89
	v_min_u32_e32 v6, v8, v1
	v_min_u32_e32 v13, v5, v2
	v_min_u32_e32 v14, v4, v0
	v_max_u32_e32 v2, v5, v2
	v_max_u32_e32 v0, v4, v0
	v_min_u32_e32 v187, v15, v185
	v_min_u32_e32 v11, v9, v3
	v_min_u32_e32 v4, v2, v0
	v_max3_u32 v5, v90, v92, v190
	v_max3_u32 v87, v165, v192, v186
	v_max3_u32 v12, v91, v93, v12
	v_max3_u32 v88, v168, v10, v7
	v_max3_u32 v93, v175, v9, v3
	v_max3_u32 v3, v98, v100, v183
	v_max3_u32 v7, v179, v184, v89
	v_max3_u32 v6, v99, v157, v6
	v_min_u32_e32 v86, v13, v14
	v_max3_u32 v90, v94, v96, v187
	v_max3_u32 v91, v170, v15, v185
	v_max3_u32 v92, v95, v97, v11
	v_max3_u32 v89, v180, v8, v1
	v_max3_u32 v94, v181, v13, v14
	v_max3_u32 v95, v160, v164, v4
	v_max3_u32 v96, v182, v2, v0
	v_max_u32_e32 v97, v5, v3
	v_min_u32_e32 v98, v5, v3
	v_max_u32_e32 v99, v87, v7
	v_min_u32_e32 v87, v87, v7
	v_max_u32_e32 v100, v12, v6
	v_min_u32_e32 v157, v12, v6
	v_mfma_f32_32x32x16_bf16 v[0:15], v[32:35], v[16:19], 0
	v_max3_u32 v86, v159, v161, v86
	v_max_u32_e32 v159, v88, v89
	v_min_u32_e32 v34, v92, v95
	v_xor_b32_e32 v185, 31, v85
	v_xor_b32_e32 v184, 30, v85
	v_xor_b32_e32 v182, 29, v85
	v_xor_b32_e32 v183, 28, v85
	v_mfma_f32_32x32x16_bf16 v[0:15], v[44:47], v[20:23], v[0:15]
	v_max_u32_e32 v20, v93, v96
	v_xor_b32_e32 v179, 23, v85
	v_xor_b32_e32 v175, 22, v85
	v_xor_b32_e32 v180, 21, v85
	v_xor_b32_e32 v181, 20, v85
	v_xor_b32_e32 v161, 15, v85
	v_xor_b32_e32 v160, 14, v85
	v_mfma_f32_32x32x16_bf16 v[0:15], v[48:51], v[40:43], v[0:15]
	v_max_u32_e32 v40, v159, v20
	v_min_u32_e32 v41, v159, v20
	v_xor_b32_e32 v159, 12, v85
	v_xor_b32_e32 v165, 7, v85
	v_xor_b32_e32 v164, 6, v85
	v_xor_b32_e32 v168, 5, v85
	v_xor_b32_e32 v170, 4, v85
	v_mfma_f32_32x32x16_bf16 v[0:15], v[60:63], v[36:39], v[0:15]
	v_max_u32_e32 v36, v157, v34
	v_min_u32_e32 v37, v157, v34
	v_xor_b32_e32 v157, 13, v85
	v_min_u32_e32 v16, v88, v89
	v_max_u32_e32 v17, v90, v86
	v_min_u32_e32 v18, v90, v86
	v_max_u32_e32 v19, v91, v94
	v_mfma_f32_32x32x16_bf16 v[0:15], v[64:67], v[56:59], v[0:15]
	v_min_u32_e32 v32, v91, v94
	v_max_u32_e32 v33, v92, v95
	v_min_u32_e32 v21, v93, v96
	v_max_u32_e32 v22, v97, v17
	v_min_u32_e32 v35, v97, v17
	v_max_u32_e32 v44, v99, v19
	v_min_u32_e32 v19, v99, v19
	v_mfma_f32_32x32x16_bf16 v[0:15], v[72:75], v[52:55], v[0:15]
	v_max_u32_e32 v23, v100, v33
	v_min_u32_e32 v33, v100, v33
	v_max_u32_e32 v42, v98, v18
	v_min_u32_e32 v43, v98, v18
	v_max_u32_e32 v45, v87, v32
	v_min_u32_e32 v46, v87, v32
	v_max_u32_e32 v34, v16, v21
	v_mfma_f32_32x32x16_bf16 v[0:15], v[76:79], v[68:71], v[0:15]
	v_min_u32_e32 v47, v16, v21
	v_max_u32_e32 v17, v22, v23
	v_min_u32_e32 v16, v22, v23
	v_max_u32_e32 v23, v44, v40
	v_min_u32_e32 v32, v44, v40
	v_max_u32_e32 v20, v35, v33
	v_min_u32_e32 v18, v35, v33
	v_mfma_f32_32x32x16_bf16 v[0:15], v[28:31], v[24:27], v[0:15]
	v_max_u32_e32 v35, v19, v41
	v_min_u32_e32 v33, v19, v41
	v_max_u32_e32 v21, v42, v36
	v_min_u32_e32 v19, v42, v36
	v_max_u32_e32 v38, v45, v34
	v_min_u32_e32 v36, v45, v34
	v_max_u32_e32 v34, v43, v37
	s_nop 4
	v_ashrrev_i32_e32 v24, 31, v0
	v_ashrrev_i32_e32 v25, 31, v3
	v_ashrrev_i32_e32 v27, 31, v7
	v_ashrrev_i32_e32 v28, 31, v4
	v_ashrrev_i32_e32 v31, 31, v15
	v_ashrrev_i32_e32 v48, 31, v12
	v_ashrrev_i32_e32 v50, 31, v8
	v_ashrrev_i32_e32 v51, 31, v11
	v_bitop3_b32 v0, v24, v0, s76 bitop3:0x36
	v_ashrrev_i32_e32 v24, 31, v1
	v_bitop3_b32 v3, v25, v3, s76 bitop3:0x36
	v_ashrrev_i32_e32 v25, 31, v2
	v_bitop3_b32 v7, v27, v7, s76 bitop3:0x36
	v_ashrrev_i32_e32 v27, 31, v6
	v_bitop3_b32 v4, v28, v4, s76 bitop3:0x36
	v_ashrrev_i32_e32 v28, 31, v5
	v_bitop3_b32 v15, v31, v15, s76 bitop3:0x36
	v_ashrrev_i32_e32 v31, 31, v14
	v_bitop3_b32 v12, v48, v12, s76 bitop3:0x36
	v_ashrrev_i32_e32 v48, 31, v13
	v_bitop3_b32 v8, v50, v8, s76 bitop3:0x36
	v_ashrrev_i32_e32 v50, 31, v9
	v_bitop3_b32 v11, v51, v11, s76 bitop3:0x36
	v_ashrrev_i32_e32 v51, 31, v10
	v_bitop3_b32 v1, v24, v1, s76 bitop3:0x36
	v_bitop3_b32 v2, v25, v2, s76 bitop3:0x36
	v_bitop3_b32 v6, v27, v6, s76 bitop3:0x36
	v_bitop3_b32 v5, v28, v5, s76 bitop3:0x36
	v_bitop3_b32 v14, v31, v14, s76 bitop3:0x36
	v_bitop3_b32 v13, v48, v13, s76 bitop3:0x36
	v_bitop3_b32 v9, v50, v9, s76 bitop3:0x36
	v_bitop3_b32 v10, v51, v10, s76 bitop3:0x36
	v_and_or_b32 v0, v0, s77, v185
	v_and_or_b32 v1, v1, s77, v184
	v_and_or_b32 v3, v3, s77, v183
	v_and_or_b32 v2, v2, s77, v182
	v_and_or_b32 v7, v7, s77, v181
	v_and_or_b32 v6, v6, s77, v180
	v_and_or_b32 v4, v4, s77, v179
	v_and_or_b32 v5, v5, s77, v175
	v_and_or_b32 v15, v15, s77, v170
	v_and_or_b32 v14, v14, s77, v168
	v_and_or_b32 v12, v12, s77, v165
	v_and_or_b32 v13, v13, s77, v164
	v_and_or_b32 v8, v8, s77, v161
	v_and_or_b32 v9, v9, s77, v160
	v_and_or_b32 v11, v11, s77, v159
	v_and_or_b32 v10, v10, s77, v157
	v_max_u32_e32 v24, v0, v1
	v_min_u32_e32 v25, v3, v2
	v_min_u32_e32 v0, v0, v1
	v_max_u32_e32 v1, v3, v2
	v_max_u32_e32 v27, v7, v6
	v_min_u32_e32 v28, v4, v5
	v_min_u32_e32 v6, v7, v6
	v_max_u32_e32 v4, v4, v5
	v_max_u32_e32 v31, v15, v14
	v_min_u32_e32 v48, v12, v13
	v_min_u32_e32 v14, v15, v14
	v_max_u32_e32 v12, v12, v13
	v_max_u32_e32 v50, v8, v9
	v_min_u32_e32 v51, v11, v10
	v_min_u32_e32 v8, v8, v9
	v_max_u32_e32 v9, v11, v10
	v_max_u32_e32 v26, v24, v25
	v_max_u32_e32 v2, v0, v1
	v_min_u32_e32 v29, v27, v28
	v_min_u32_e32 v5, v6, v4
	v_min_u32_e32 v24, v24, v25
	v_min_u32_e32 v0, v0, v1
	v_max_u32_e32 v25, v27, v28
	v_max_u32_e32 v4, v6, v4
	v_max_u32_e32 v49, v31, v48
	v_max_u32_e32 v13, v14, v12
	v_min_u32_e32 v52, v50, v51
	v_min_u32_e32 v10, v8, v9
	v_min_u32_e32 v31, v31, v48
	v_min_u32_e32 v12, v14, v12
	v_max_u32_e32 v48, v50, v51
	v_max_u32_e32 v8, v8, v9
	v_max_u32_e32 v3, v26, v2
	v_min_u32_e32 v7, v29, v5
	v_max_u32_e32 v1, v24, v0
	v_min_u32_e32 v6, v25, v4
	v_min_u32_e32 v2, v26, v2
	v_max_u32_e32 v5, v29, v5
	v_min_u32_e32 v0, v24, v0
	v_max_u32_e32 v4, v25, v4
	v_max_u32_e32 v15, v49, v13
	v_min_u32_e32 v11, v52, v10
	v_max_u32_e32 v14, v31, v12
	v_min_u32_e32 v9, v48, v8
	v_min_u32_e32 v13, v49, v13
	v_max_u32_e32 v10, v52, v10
	v_min_u32_e32 v12, v31, v12
	v_max_u32_e32 v8, v48, v8
	v_max_u32_e32 v30, v3, v7
	v_max_u32_e32 v27, v1, v6
	v_max_u32_e32 v26, v2, v5
	v_max_u32_e32 v24, v0, v4
	v_min_u32_e32 v53, v15, v11
	v_min_u32_e32 v50, v14, v9
	v_min_u32_e32 v49, v13, v10
	v_min_u32_e32 v31, v12, v8
	v_min_u32_e32 v3, v3, v7
	v_min_u32_e32 v1, v1, v6
	v_min_u32_e32 v2, v2, v5
	v_min_u32_e32 v0, v0, v4
	v_max_u32_e32 v7, v15, v11
	v_max_u32_e32 v9, v14, v9
	v_max_u32_e32 v10, v13, v10
	v_max_u32_e32 v8, v12, v8
	v_max_u32_e32 v28, v30, v27
	v_max_u32_e32 v25, v26, v24
	v_min_u32_e32 v51, v53, v50
	v_min_u32_e32 v48, v49, v31
	v_max_u32_e32 v6, v3, v1
	v_max_u32_e32 v4, v2, v0
	v_min_u32_e32 v11, v7, v9
	v_min_u32_e32 v12, v10, v8
	v_min_u32_e32 v27, v30, v27
	v_min_u32_e32 v24, v26, v24
	v_max_u32_e32 v30, v53, v50
	v_max_u32_e32 v31, v49, v31
	v_min_u32_e32 v1, v3, v1
	v_min_u32_e32 v0, v2, v0
	v_max_u32_e32 v3, v7, v9
	v_max_u32_e32 v7, v10, v8
	v_max_u32_e32 v29, v28, v25
	v_min_u32_e32 v52, v51, v48
	v_max_u32_e32 v5, v6, v4
	v_min_u32_e32 v13, v11, v12
	v_max_u32_e32 v26, v27, v24
	v_min_u32_e32 v49, v30, v31
	v_max_u32_e32 v2, v1, v0
	v_min_u32_e32 v8, v3, v7
	v_min_u32_e32 v54, v29, v52
	v_min_u32_e32 v14, v5, v13
	v_min_u32_e32 v50, v26, v49
	v_min_u32_e32 v9, v2, v8
	v_min_u32_e32 v15, v54, v14
	v_min_u32_e32 v10, v50, v9
	v_min_u32_e32 v25, v28, v25
	v_max_u32_e32 v28, v51, v48
	v_min_u32_e32 v4, v6, v4
	v_max_u32_e32 v6, v11, v12
	v_min_u32_e32 v24, v27, v24
	v_max_u32_e32 v27, v30, v31
	v_min_u32_e32 v0, v1, v0
	v_max_u32_e32 v1, v3, v7
	v_max_u32_e32 v14, v54, v14
	v_max_u32_e32 v9, v50, v9
	v_min_u32_e32 v53, v15, v10
	v_min_u32_e32 v48, v25, v28
	v_min_u32_e32 v11, v4, v6
	v_min_u32_e32 v30, v24, v27
	v_min_u32_e32 v3, v0, v1
	v_max_u32_e32 v10, v15, v10
	v_min_u32_e32 v15, v14, v9
	v_max_u32_e32 v9, v14, v9
	v_max_u32_e32 v14, v29, v52
	v_max_u32_e32 v5, v5, v13
	v_max_u32_e32 v26, v26, v49
	v_max_u32_e32 v2, v2, v8
	v_max_u32_e32 v25, v25, v28
	v_max_u32_e32 v4, v4, v6
	v_max_u32_e32 v24, v24, v27
	v_max_u32_e32 v0, v0, v1
	v_min_u32_e32 v12, v48, v11
	v_min_u32_e32 v7, v30, v3
	v_max_u32_e32 v11, v48, v11
	v_max_u32_e32 v3, v30, v3
	v_min_u32_e32 v13, v14, v5
	v_min_u32_e32 v8, v26, v2
	v_min_u32_e32 v6, v25, v4
	v_min_u32_e32 v1, v24, v0
	v_max_u32_e32 v5, v14, v5
	v_max_u32_e32 v2, v26, v2
	v_max_u32_e32 v4, v25, v4
	v_max_u32_e32 v0, v24, v0
	v_max_u32_e32 v39, v46, v47
	v_min_u32_e32 v31, v12, v7
	v_max_u32_e32 v7, v12, v7
	v_min_u32_e32 v30, v11, v3
	v_max_u32_e32 v3, v11, v3
	v_min_u32_e32 v29, v13, v8
	v_min_u32_e32 v27, v6, v1
	v_max_u32_e32 v8, v13, v8
	v_max_u32_e32 v1, v6, v1
	v_min_u32_e32 v13, v5, v2
	v_min_u32_e32 v14, v4, v0
	v_max_u32_e32 v2, v5, v2
	v_max_u32_e32 v0, v4, v0
	v_min_u32_e32 v22, v43, v37
	v_min_u32_e32 v37, v46, v47
	v_min_u32_e32 v46, v17, v23
	v_min_u32_e32 v47, v16, v32
	v_min_u32_e32 v45, v20, v35
	v_min_u32_e32 v44, v18, v33
	v_min_u32_e32 v43, v21, v38
	v_min_u32_e32 v42, v19, v36
	v_min_u32_e32 v41, v34, v39
	v_min_u32_e32 v51, v53, v31
	v_min_u32_e32 v12, v10, v7
	v_min_u32_e32 v48, v15, v30
	v_min_u32_e32 v11, v9, v3
	v_min_u32_e32 v28, v29, v27
	v_min_u32_e32 v6, v8, v1
	v_min_u32_e32 v24, v13, v14
	v_min_u32_e32 v4, v2, v0
	v_min_u32_e32 v40, v22, v37
	v_max3_u32 v5, v17, v23, v51
	v_max3_u32 v17, v46, v53, v31
	v_max3_u32 v12, v16, v32, v12
	v_max3_u32 v7, v47, v10, v7
	v_max3_u32 v10, v20, v35, v48
	v_max3_u32 v15, v45, v15, v30
	v_max3_u32 v11, v18, v33, v11
	v_max3_u32 v3, v44, v9, v3
	v_max3_u32 v9, v21, v38, v28
	v_max3_u32 v16, v43, v29, v27
	v_max3_u32 v6, v19, v36, v6
	v_max3_u32 v1, v42, v8, v1
	v_max3_u32 v8, v34, v39, v24
	v_max3_u32 v13, v41, v13, v14
	v_max3_u32 v4, v22, v37, v4
	v_max3_u32 v0, v40, v2, v0
	v_max_u32_e32 v2, v5, v9
	v_min_u32_e32 v5, v5, v9
	v_max_u32_e32 v9, v17, v16
	v_min_u32_e32 v14, v17, v16
	v_max_u32_e32 v16, v12, v6
	v_min_u32_e32 v6, v12, v6
	v_max_u32_e32 v12, v7, v1
	v_min_u32_e32 v1, v7, v1
	v_max_u32_e32 v7, v10, v8
	v_min_u32_e32 v8, v10, v8
	v_max_u32_e32 v10, v15, v13
	v_min_u32_e32 v13, v15, v13
	v_max_u32_e32 v15, v11, v4
	v_min_u32_e32 v4, v11, v4
	v_max_u32_e32 v11, v3, v0
	v_min_u32_e32 v0, v3, v0
	v_max_u32_e32 v3, v2, v7
	v_min_u32_e32 v2, v2, v7
	v_max_u32_e32 v7, v9, v10
	v_min_u32_e32 v9, v9, v10
	v_max_u32_e32 v10, v16, v15
	v_min_u32_e32 v15, v16, v15
	v_max_u32_e32 v19, v1, v0
	v_min_u32_e32 v20, v1, v0
	v_max_u32_e32 v23, v2, v15
	v_min_u32_e32 v15, v2, v15
	v_add_u32_e32 v0, s3, v110
	v_add_u32_e32 v2, s3, v111
	v_max_u32_e32 v21, v3, v10
	v_min_u32_e32 v10, v3, v10
	v_ashrrev_i32_e32 v1, 31, v0
	v_ashrrev_i32_e32 v3, 31, v2
	v_lshlrev_b64 v[0:1], 8, v[0:1]
	v_lshlrev_b64 v[2:3], 8, v[2:3]
	v_max_u32_e32 v16, v12, v11
	v_min_u32_e32 v11, v12, v11
	v_max_u32_e32 v12, v5, v8
	v_min_u32_e32 v8, v5, v8
	v_max_u32_e32 v17, v14, v13
	v_min_u32_e32 v13, v14, v13
	v_max_u32_e32 v14, v6, v4
	v_min_u32_e32 v18, v6, v4
	v_lshl_add_u64 v[0:1], v[82:83], 0, v[0:1]
	v_lshl_add_u64 v[4:5], v[82:83], 0, v[2:3]
	v_max_u32_e32 v22, v7, v16
	v_min_u32_e32 v16, v7, v16
	s_nop 0
	v_max_u32_e32 v24, v9, v11
	v_min_u32_e32 v9, v9, v11
	v_max_u32_e32 v11, v12, v14
	v_min_u32_e32 v12, v12, v14
	v_max_u32_e32 v14, v17, v19
	v_min_u32_e32 v17, v17, v19
	v_max_u32_e32 v19, v8, v18
	v_min_u32_e32 v8, v8, v18
	v_max_u32_e32 v18, v13, v20
	v_min_u32_e32 v13, v13, v20
	v_max_u32_e32 v20, v21, v22
	v_min_u32_e32 v21, v21, v22
	v_max_u32_e32 v22, v10, v16
	v_min_u32_e32 v10, v10, v16
	v_max_u32_e32 v16, v23, v24
	v_min_u32_e32 v23, v23, v24
	v_max_u32_e32 v24, v15, v9
	v_min_u32_e32 v9, v15, v9
	v_max_u32_e32 v15, v11, v14
	v_min_u32_e32 v11, v11, v14
	v_max_u32_e32 v14, v12, v17
	v_min_u32_e32 v12, v12, v17
	v_max_u32_e32 v17, v19, v18
	v_min_u32_e32 v18, v19, v18
	v_max_u32_e32 v19, v8, v13
	v_min_u32_e32 v8, v8, v13
	ds_bpermute_b32 v13, v141, v20
	ds_bpermute_b32 v25, v141, v21
	ds_bpermute_b32 v26, v141, v22
	ds_bpermute_b32 v27, v141, v10
	ds_bpermute_b32 v28, v141, v16
	ds_bpermute_b32 v29, v141, v23
	ds_bpermute_b32 v30, v141, v24
	ds_bpermute_b32 v31, v141, v9
	ds_bpermute_b32 v32, v141, v15
	ds_bpermute_b32 v33, v141, v11
	ds_bpermute_b32 v34, v141, v14
	ds_bpermute_b32 v35, v141, v8
	ds_bpermute_b32 v36, v141, v19
	ds_bpermute_b32 v37, v141, v18
	ds_bpermute_b32 v38, v141, v17
	ds_bpermute_b32 v39, v141, v12
	s_waitcnt vmcnt(1)
	ds_write_b128 v109, v[240:243]
	s_waitcnt vmcnt(0)
	ds_write_b128 v108, v[244:247]
	s_waitcnt lgkmcnt(0)
	s_barrier
	ds_read_b128 v[0:3], v84
	v_max_u32_e32 v20, v20, v35
	v_max_u32_e32 v21, v21, v36
	v_max_u32_e32 v22, v22, v37
	v_max_u32_e32 v10, v10, v38
	v_max_u32_e32 v16, v16, v39
	v_max_u32_e32 v23, v23, v34
	v_max_u32_e32 v24, v24, v33
	v_max_u32_e32 v9, v9, v32
	v_max_u32_e32 v15, v15, v31
	v_max_u32_e32 v11, v11, v30
	v_max_u32_e32 v14, v14, v29
	v_max_u32_e32 v12, v12, v28
	v_max_u32_e32 v17, v17, v27
	v_max_u32_e32 v18, v18, v26
	v_max_u32_e32 v19, v19, v25
	v_max_u32_e32 v8, v8, v13
	v_max_u32_e32 v13, v20, v15
	v_min_u32_e32 v15, v20, v15
	v_max_u32_e32 v20, v21, v11
	v_min_u32_e32 v11, v21, v11
	v_max_u32_e32 v21, v22, v14
	v_min_u32_e32 v33, v22, v14
	v_max_u32_e32 v14, v10, v12
	v_min_u32_e32 v34, v10, v12
	v_max_u32_e32 v10, v16, v17
	v_min_u32_e32 v12, v16, v17
	v_max_u32_e32 v16, v23, v18
	v_min_u32_e32 v22, v23, v18
	v_max_u32_e32 v17, v24, v19
	v_max_u32_e32 v18, v9, v8
	v_min_u32_e32 v36, v24, v19
	v_max_u32_e32 v41, v20, v16
	v_min_u32_e32 v44, v20, v16
	v_max_u32_e32 v35, v21, v17
	v_min_u32_e32 v42, v21, v17
	v_max_u32_e32 v43, v14, v18
	v_min_u32_e32 v49, v14, v18
	ds_read_b128 v[16:19], v81 offset:256
	v_min_u32_e32 v37, v9, v8
	v_max_u32_e32 v32, v13, v10
	v_min_u32_e32 v40, v13, v10
	v_max_u32_e32 v48, v15, v12
	v_min_u32_e32 v45, v15, v12
	v_max_u32_e32 v47, v11, v22
	v_min_u32_e32 v46, v11, v22
	s_waitcnt lgkmcnt(0)
	v_mfma_f32_32x32x16_bf16 v[0:15], v[0:3], v[16:19], 0
	ds_read_b128 v[24:27], v107
	ds_read_b128 v[20:23], v81 offset:288
	ds_read_b128 v[28:31], v84 offset:8192
	v_max_u32_e32 v54, v33, v36
	v_min_u32_e32 v60, v33, v36
	v_max_u32_e32 v61, v34, v37
	v_min_u32_e32 v62, v34, v37
	v_max_u32_e32 v68, v32, v35
	ds_read_b128 v[50:53], v106
	ds_read_b128 v[36:39], v107 offset:8192
	s_waitcnt lgkmcnt(3)
	v_mfma_f32_32x32x16_bf16 v[0:15], v[24:27], v[20:23], v[0:15]
	v_min_u32_e32 v69, v32, v35
	ds_read_b128 v[32:35], v81 offset:320
	v_max_u32_e32 v70, v41, v43
	v_min_u32_e32 v71, v41, v43
	v_max_u32_e32 v76, v40, v42
	v_min_u32_e32 v77, v40, v42
	ds_read_b128 v[56:59], v105
	ds_read_b128 v[24:27], v81 offset:352
	ds_read_b128 v[40:43], v106 offset:8192
	s_waitcnt lgkmcnt(3)
	v_mfma_f32_32x32x16_bf16 v[0:15], v[50:53], v[32:35], v[0:15]
	v_max_u32_e32 v78, v44, v49
	v_min_u32_e32 v79, v44, v49
	v_max_u32_e32 v94, v48, v54
	v_min_u32_e32 v96, v48, v54
	ds_read_b128 v[64:67], v104
	ds_read_b128 v[52:55], v105 offset:8192
	ds_read_b128 v[48:51], v81 offset:384
	v_max_u32_e32 v95, v47, v61
	s_waitcnt lgkmcnt(4)
	v_mfma_f32_32x32x16_bf16 v[0:15], v[56:59], v[24:27], v[0:15]
	v_min_u32_e32 v97, v47, v61
	v_max_u32_e32 v98, v45, v60
	v_min_u32_e32 v100, v45, v60
	v_max_u32_e32 v99, v46, v62
	v_min_u32_e32 v190, v46, v62
	ds_read_b128 v[56:59], v103
	ds_read_b128 v[44:47], v81 offset:416
	ds_read_b128 v[60:63], v104 offset:8192
	v_max_u32_e32 v85, v68, v70
	s_waitcnt lgkmcnt(3)
	v_mfma_f32_32x32x16_bf16 v[0:15], v[64:67], v[48:51], v[0:15]
	v_min_u32_e32 v86, v68, v70
	v_max_u32_e32 v87, v69, v71
	v_min_u32_e32 v88, v69, v71
	ds_read_b128 v[68:71], v102
	ds_read_b128 v[72:75], v103 offset:8192
	ds_read_b128 v[64:67], v81 offset:448
	v_max_u32_e32 v89, v76, v78
	v_min_u32_e32 v90, v76, v78
	s_waitcnt lgkmcnt(4)
	v_mfma_f32_32x32x16_bf16 v[0:15], v[56:59], v[44:47], v[0:15]
	v_max_u32_e32 v91, v77, v79
	v_min_u32_e32 v92, v77, v79
	ds_read_b128 v[76:79], v101
	ds_read_b128 v[56:59], v81 offset:480
	ds_read_b128 v[186:189], v102 offset:8192
	v_max_u32_e32 v93, v94, v95
	v_min_u32_e32 v94, v94, v95
	v_max_u32_e32 v95, v96, v97
	v_min_u32_e32 v96, v96, v97
	s_waitcnt lgkmcnt(3)
	v_mfma_f32_32x32x16_bf16 v[0:15], v[68:71], v[64:67], v[0:15]
	v_max_u32_e32 v97, v98, v99
	v_min_u32_e32 v98, v98, v99
	v_max_u32_e32 v99, v100, v190
	v_min_u32_e32 v100, v100, v190
	ds_read_b128 v[190:193], v101 offset:8192
	s_or_b32 s3, s16, 0xc0
	s_waitcnt lgkmcnt(0)
	v_mfma_f32_32x32x16_bf16 v[0:15], v[76:79], v[56:59], v[0:15]
	s_barrier
	v_add_u32_e32 v248, s3, v110
	v_add_u32_e32 v250, s3, v111
	v_ashrrev_i32_e32 v249, 31, v248
	v_ashrrev_i32_e32 v251, 31, v250
	v_lshlrev_b64 v[248:249], 8, v[248:249]
	v_lshlrev_b64 v[250:251], 8, v[250:251]
	v_lshl_add_u64 v[248:249], v[82:83], 0, v[248:249]
	v_lshl_add_u64 v[250:251], v[82:83], 0, v[250:251]
	global_load_dwordx4 v[240:243], v[248:249], off
	global_load_dwordx4 v[244:247], v[250:251], off
	v_cmp_lt_i32_e32 vcc, -1, v85
	s_lshl_b32 s16, s9, 4
	s_nop 8
	v_ashrrev_i32_e32 v79, 31, v15
	v_bitop3_b32 v15, v79, v15, s76 bitop3:0x36
	v_ashrrev_i32_e32 v79, 31, v14
	v_bitop3_b32 v14, v79, v14, s76 bitop3:0x36
	v_and_or_b32 v14, v14, s77, v118
	v_ashrrev_i32_e32 v118, 31, v12
	v_bitop3_b32 v12, v118, v12, s76 bitop3:0x36
	v_ashrrev_i32_e32 v118, 31, v8
	v_bitop3_b32 v8, v118, v8, s76 bitop3:0x36
	v_and_or_b32 v8, v8, s77, v115
	v_ashrrev_i32_e32 v115, 31, v9
	v_bitop3_b32 v9, v115, v9, s76 bitop3:0x36
	v_ashrrev_i32_e32 v115, 31, v11
	v_ashrrev_i32_e32 v68, 31, v0
	v_ashrrev_i32_e32 v69, 31, v3
	v_ashrrev_i32_e32 v71, 31, v7
	v_ashrrev_i32_e32 v76, 31, v4
	v_bitop3_b32 v11, v115, v11, s76 bitop3:0x36
	v_bitop3_b32 v0, v68, v0, s76 bitop3:0x36
	v_ashrrev_i32_e32 v68, 31, v1
	v_bitop3_b32 v3, v69, v3, s76 bitop3:0x36
	v_ashrrev_i32_e32 v69, 31, v2
	v_bitop3_b32 v7, v71, v7, s76 bitop3:0x36
	v_ashrrev_i32_e32 v71, 31, v6
	v_bitop3_b32 v4, v76, v4, s76 bitop3:0x36
	v_ashrrev_i32_e32 v76, 31, v5
	v_and_or_b32 v12, v12, s77, v117
	v_ashrrev_i32_e32 v117, 31, v13
	v_and_or_b32 v11, v11, s77, v113
	v_ashrrev_i32_e32 v113, 31, v10
	v_bitop3_b32 v1, v68, v1, s76 bitop3:0x36
	v_bitop3_b32 v2, v69, v2, s76 bitop3:0x36
	v_bitop3_b32 v6, v71, v6, s76 bitop3:0x36
	v_bitop3_b32 v5, v76, v5, s76 bitop3:0x36
	v_bitop3_b32 v13, v117, v13, s76 bitop3:0x36
	v_bitop3_b32 v10, v113, v10, s76 bitop3:0x36
	v_and_or_b32 v0, v0, s77, v127
	v_and_or_b32 v1, v1, s77, v126
	v_and_or_b32 v3, v3, s77, v125
	v_and_or_b32 v2, v2, s77, v124
	v_and_or_b32 v7, v7, s77, v123
	v_and_or_b32 v6, v6, s77, v122
	v_and_or_b32 v4, v4, s77, v121
	v_and_or_b32 v5, v5, s77, v120
	v_and_or_b32 v15, v15, s77, v119
	v_and_or_b32 v13, v13, s77, v116
	v_and_or_b32 v9, v9, s77, v114
	v_and_or_b32 v10, v10, s77, v112
	v_max_u32_e32 v68, v0, v1
	v_min_u32_e32 v69, v3, v2
	v_min_u32_e32 v0, v0, v1
	v_max_u32_e32 v1, v3, v2
	v_max_u32_e32 v71, v7, v6
	v_min_u32_e32 v76, v4, v5
	v_min_u32_e32 v6, v7, v6
	v_max_u32_e32 v4, v4, v5
	v_max_u32_e32 v79, v15, v14
	v_min_u32_e32 v116, v12, v13
	v_min_u32_e32 v14, v15, v14
	v_max_u32_e32 v12, v12, v13
	v_max_u32_e32 v114, v8, v9
	v_min_u32_e32 v112, v11, v10
	v_min_u32_e32 v8, v8, v9
	v_max_u32_e32 v9, v11, v10
	v_max_u32_e32 v70, v68, v69
	v_max_u32_e32 v2, v0, v1
	v_min_u32_e32 v77, v71, v76
	v_min_u32_e32 v5, v6, v4
	v_min_u32_e32 v68, v68, v69
	v_min_u32_e32 v0, v0, v1
	v_max_u32_e32 v69, v71, v76
	v_max_u32_e32 v4, v6, v4
	v_max_u32_e32 v117, v79, v116
	v_max_u32_e32 v13, v14, v12
	v_min_u32_e32 v113, v114, v112
	v_min_u32_e32 v10, v8, v9
	v_min_u32_e32 v79, v79, v116
	v_min_u32_e32 v12, v14, v12
	v_max_u32_e32 v112, v114, v112
	v_max_u32_e32 v8, v8, v9
	v_max_u32_e32 v3, v70, v2
	v_min_u32_e32 v7, v77, v5
	v_max_u32_e32 v1, v68, v0
	v_min_u32_e32 v6, v69, v4
	v_min_u32_e32 v2, v70, v2
	v_max_u32_e32 v5, v77, v5
	v_min_u32_e32 v0, v68, v0
	v_max_u32_e32 v4, v69, v4
	v_max_u32_e32 v15, v117, v13
	v_min_u32_e32 v11, v113, v10
	v_max_u32_e32 v14, v79, v12
	v_min_u32_e32 v9, v112, v8
	v_min_u32_e32 v13, v117, v13
	v_max_u32_e32 v10, v113, v10
	v_min_u32_e32 v12, v79, v12
	v_max_u32_e32 v8, v112, v8
	v_max_u32_e32 v78, v3, v7
	v_max_u32_e32 v71, v1, v6
	v_max_u32_e32 v70, v2, v5
	v_max_u32_e32 v68, v0, v4
	v_min_u32_e32 v115, v15, v11
	v_min_u32_e32 v114, v14, v9
	v_min_u32_e32 v113, v13, v10
	v_min_u32_e32 v79, v12, v8
	v_min_u32_e32 v3, v3, v7
	v_min_u32_e32 v1, v1, v6
	v_min_u32_e32 v2, v2, v5
	v_min_u32_e32 v0, v0, v4
	v_max_u32_e32 v5, v15, v11
	v_max_u32_e32 v7, v14, v9
	v_max_u32_e32 v10, v13, v10
	v_max_u32_e32 v8, v12, v8
	v_max_u32_e32 v76, v78, v71
	v_max_u32_e32 v69, v70, v68
	v_min_u32_e32 v116, v115, v114
	v_min_u32_e32 v112, v113, v79
	v_max_u32_e32 v6, v3, v1
	v_max_u32_e32 v4, v2, v0
	v_min_u32_e32 v9, v5, v7
	v_min_u32_e32 v11, v10, v8
	v_min_u32_e32 v12, v78, v71
	v_min_u32_e32 v13, v70, v68
	v_max_u32_e32 v77, v76, v69
	v_min_u32_e32 v117, v116, v112
	v_max_u32_e32 v119, v6, v4
	v_min_u32_e32 v120, v9, v11
	v_max_u32_e32 v70, v12, v13
	v_max_u32_e32 v71, v115, v114
	v_min_u32_e32 v114, v3, v1
	v_min_u32_e32 v115, v2, v0
	v_max_u32_e32 v124, v5, v7
	v_max_u32_e32 v125, v10, v8
	v_min_u32_e32 v69, v76, v69
	v_max_u32_e32 v76, v116, v112
	v_min_u32_e32 v116, v6, v4
	v_max_u32_e32 v195, v9, v11
	v_min_u32_e32 v198, v12, v13
	v_mfma_f32_32x32x16_bf16 v[0:15], v[28:31], v[16:19], 0
	v_max_u32_e32 v78, v113, v79
	v_min_u32_e32 v79, v71, v78
	v_max_u32_e32 v123, v114, v115
	v_min_u32_e32 v126, v124, v125
	v_max_u32_e32 v31, v71, v78
	v_min_u32_e32 v71, v114, v115
	v_max_u32_e32 v78, v124, v125
	v_mfma_f32_32x32x16_bf16 v[0:15], v[36:39], v[20:23], v[0:15]
	v_min_u32_e32 v118, v77, v117
	v_min_u32_e32 v121, v119, v120
	v_min_u32_e32 v113, v70, v79
	v_min_u32_e32 v127, v123, v126
	v_min_u32_e32 v112, v69, v76
	v_min_u32_e32 v196, v116, v195
	v_min_u32_e32 v28, v198, v31
	v_mfma_f32_32x32x16_bf16 v[0:15], v[40:43], v[32:35], v[0:15]
	v_min_u32_e32 v29, v71, v78
	v_min_u32_e32 v19, v28, v29
	v_max_u32_e32 v30, v118, v121
	v_max_u32_e32 v36, v113, v127
	v_max_u32_e32 v32, v112, v196
	v_max_u32_e32 v29, v28, v29
	v_min_u32_e32 v21, v30, v36
	v_mfma_f32_32x32x16_bf16 v[0:15], v[52:55], v[24:27], v[0:15]
	v_min_u32_e32 v22, v32, v29
	v_max_u32_e32 v28, v30, v36
	v_max_u32_e32 v29, v32, v29
	v_max_u32_e32 v24, v77, v117
	v_max_u32_e32 v25, v119, v120
	v_max_u32_e32 v27, v70, v79
	v_max_u32_e32 v32, v123, v126
	v_mfma_f32_32x32x16_bf16 v[0:15], v[60:63], v[48:51], v[0:15]
	v_max_u32_e32 v35, v69, v76
	v_max_u32_e32 v36, v116, v195
	v_max_u32_e32 v31, v198, v31
	v_max_u32_e32 v38, v71, v78
	v_min_u32_e32 v26, v24, v25
	v_min_u32_e32 v33, v27, v32
	v_min_u32_e32 v39, v31, v38
	v_mfma_f32_32x32x16_bf16 v[0:15], v[72:75], v[44:47], v[0:15]
	v_max_u32_e32 v24, v24, v25
	v_max_u32_e32 v25, v27, v32
	v_max_u32_e32 v32, v35, v36
	v_max_u32_e32 v31, v31, v38
	v_min_u32_e32 v37, v35, v36
	v_min_u32_e32 v27, v24, v25
	v_min_u32_e32 v35, v32, v31
	v_mfma_f32_32x32x16_bf16 v[0:15], v[186:189], v[64:67], v[0:15]
	v_max_u32_e32 v24, v24, v25
	v_max_u32_e32 v25, v32, v31
	v_min_u32_e32 v34, v26, v33
	v_min_u32_e32 v40, v37, v39
	v_max_u32_e32 v26, v26, v33
	v_max_u32_e32 v33, v37, v39
	v_min_u32_e32 v122, v118, v121
	v_mfma_f32_32x32x16_bf16 v[0:15], v[190:193], v[56:59], v[0:15]
	v_min_u32_e32 v194, v113, v127
	v_min_u32_e32 v197, v112, v196
	v_min_u32_e32 v68, v122, v194
	v_min_u32_e32 v16, v197, v19
	v_max_u32_e32 v18, v122, v194
	v_max_u32_e32 v19, v197, v19
	v_min_u32_e32 v41, v34, v40
	s_nop 4
	v_ashrrev_i32_e32 v32, 31, v0
	v_ashrrev_i32_e32 v38, 31, v3
	v_ashrrev_i32_e32 v42, 31, v7
	v_ashrrev_i32_e32 v43, 31, v4
	v_ashrrev_i32_e32 v46, 31, v15
	v_ashrrev_i32_e32 v47, 31, v12
	v_ashrrev_i32_e32 v49, 31, v8
	v_ashrrev_i32_e32 v50, 31, v11
	v_bitop3_b32 v0, v32, v0, s76 bitop3:0x36
	v_ashrrev_i32_e32 v32, 31, v1
	v_bitop3_b32 v3, v38, v3, s76 bitop3:0x36
	v_ashrrev_i32_e32 v38, 31, v2
	v_bitop3_b32 v7, v42, v7, s76 bitop3:0x36
	v_ashrrev_i32_e32 v42, 31, v6
	v_bitop3_b32 v4, v43, v4, s76 bitop3:0x36
	v_ashrrev_i32_e32 v43, 31, v5
	v_bitop3_b32 v15, v46, v15, s76 bitop3:0x36
	v_ashrrev_i32_e32 v46, 31, v14
	v_bitop3_b32 v12, v47, v12, s76 bitop3:0x36
	v_ashrrev_i32_e32 v47, 31, v13
	v_bitop3_b32 v8, v49, v8, s76 bitop3:0x36
	v_ashrrev_i32_e32 v49, 31, v9
	v_bitop3_b32 v11, v50, v11, s76 bitop3:0x36
	v_ashrrev_i32_e32 v50, 31, v10
	v_bitop3_b32 v1, v32, v1, s76 bitop3:0x36
	v_bitop3_b32 v2, v38, v2, s76 bitop3:0x36
	v_bitop3_b32 v6, v42, v6, s76 bitop3:0x36
	v_bitop3_b32 v5, v43, v5, s76 bitop3:0x36
	v_bitop3_b32 v14, v46, v14, s76 bitop3:0x36
	v_bitop3_b32 v13, v47, v13, s76 bitop3:0x36
	v_bitop3_b32 v9, v49, v9, s76 bitop3:0x36
	v_bitop3_b32 v10, v50, v10, s76 bitop3:0x36
	v_and_or_b32 v0, v0, s77, v155
	v_and_or_b32 v1, v1, s77, v153
	v_and_or_b32 v3, v3, s77, v151
	v_and_or_b32 v2, v2, s77, v150
	v_and_or_b32 v7, v7, s77, v149
	v_and_or_b32 v6, v6, s77, v148
	v_and_or_b32 v4, v4, s77, v144
	v_and_or_b32 v5, v5, s77, v143
	v_and_or_b32 v15, v15, s77, v137
	v_and_or_b32 v14, v14, s77, v136
	v_and_or_b32 v12, v12, s77, v135
	v_and_or_b32 v13, v13, s77, v134
	v_and_or_b32 v8, v8, s77, v132
	v_and_or_b32 v9, v9, s77, v131
	v_and_or_b32 v11, v11, s77, v130
	v_and_or_b32 v10, v10, s77, v129
	v_max_u32_e32 v32, v0, v1
	v_min_u32_e32 v38, v3, v2
	v_min_u32_e32 v0, v0, v1
	v_max_u32_e32 v1, v3, v2
	v_max_u32_e32 v42, v7, v6
	v_min_u32_e32 v43, v4, v5
	v_min_u32_e32 v6, v7, v6
	v_max_u32_e32 v4, v4, v5
	v_max_u32_e32 v46, v15, v14
	v_min_u32_e32 v47, v12, v13
	v_min_u32_e32 v14, v15, v14
	v_max_u32_e32 v12, v12, v13
	v_max_u32_e32 v49, v8, v9
	v_min_u32_e32 v50, v11, v10
	v_min_u32_e32 v8, v8, v9
	v_max_u32_e32 v9, v11, v10
	v_max_u32_e32 v39, v32, v38
	v_max_u32_e32 v2, v0, v1
	v_min_u32_e32 v44, v42, v43
	v_min_u32_e32 v5, v6, v4
	v_min_u32_e32 v32, v32, v38
	v_min_u32_e32 v0, v0, v1
	v_max_u32_e32 v38, v42, v43
	v_max_u32_e32 v4, v6, v4
	v_max_u32_e32 v48, v46, v47
	v_max_u32_e32 v13, v14, v12
	v_min_u32_e32 v51, v49, v50
	v_min_u32_e32 v10, v8, v9
	v_min_u32_e32 v46, v46, v47
	v_min_u32_e32 v12, v14, v12
	v_max_u32_e32 v47, v49, v50
	v_max_u32_e32 v8, v8, v9
	v_max_u32_e32 v3, v39, v2
	v_min_u32_e32 v7, v44, v5
	v_max_u32_e32 v1, v32, v0
	v_min_u32_e32 v6, v38, v4
	v_min_u32_e32 v2, v39, v2
	v_max_u32_e32 v5, v44, v5
	v_min_u32_e32 v0, v32, v0
	v_max_u32_e32 v4, v38, v4
	v_max_u32_e32 v15, v48, v13
	v_min_u32_e32 v11, v51, v10
	v_max_u32_e32 v14, v46, v12
	v_min_u32_e32 v9, v47, v8
	v_max_u32_e32 v45, v3, v7
	v_max_u32_e32 v42, v1, v6
	v_max_u32_e32 v39, v2, v5
	v_max_u32_e32 v32, v0, v4
	v_min_u32_e32 v52, v15, v11
	v_min_u32_e32 v49, v14, v9
	v_min_u32_e32 v2, v2, v5
	v_min_u32_e32 v0, v0, v4
	v_max_u32_e32 v43, v45, v42
	v_min_u32_e32 v50, v52, v49
	v_min_u32_e32 v13, v48, v13
	v_max_u32_e32 v10, v51, v10
	v_min_u32_e32 v12, v46, v12
	v_max_u32_e32 v8, v47, v8
	v_min_u32_e32 v3, v3, v7
	v_min_u32_e32 v1, v1, v6
	v_max_u32_e32 v4, v2, v0
	v_max_u32_e32 v5, v15, v11
	v_min_u32_e32 v15, v45, v42
	v_max_u32_e32 v42, v52, v49
	v_min_u32_e32 v52, v2, v0
	v_add_u32_e32 v0, s3, v110
	v_add_u32_e32 v2, s3, v111
	v_min_u32_e32 v48, v13, v10
	v_min_u32_e32 v46, v12, v8
	v_max_u32_e32 v6, v3, v1
	v_min_u32_e32 v49, v3, v1
	v_ashrrev_i32_e32 v1, 31, v0
	v_ashrrev_i32_e32 v3, 31, v2
	v_max_u32_e32 v38, v39, v32
	v_min_u32_e32 v47, v48, v46
	v_max_u32_e32 v7, v14, v9
	v_lshlrev_b64 v[0:1], 8, v[0:1]
	v_lshlrev_b64 v[2:3], 8, v[2:3]
	v_max_u32_e32 v44, v43, v38
	v_min_u32_e32 v51, v50, v47
	v_max_u32_e32 v54, v6, v4
	v_min_u32_e32 v9, v5, v7
	v_max_u32_e32 v56, v5, v7
	v_min_u32_e32 v38, v43, v38
	v_max_u32_e32 v43, v50, v47
	v_min_u32_e32 v50, v6, v4
	v_lshl_add_u64 v[0:1], v[82:83], 0, v[0:1]
	v_lshl_add_u64 v[4:5], v[82:83], 0, v[2:3]
	s_nop 0
	v_max_u32_e32 v10, v13, v10
	v_max_u32_e32 v8, v12, v8
	v_min_u32_e32 v11, v10, v8
	v_min_u32_e32 v32, v39, v32
	v_max_u32_e32 v45, v48, v46
	v_max_u32_e32 v8, v10, v8
	v_min_u32_e32 v12, v9, v11
	v_max_u32_e32 v39, v15, v32
	v_min_u32_e32 v46, v42, v45
	v_max_u32_e32 v55, v49, v52
	v_min_u32_e32 v10, v56, v8
	v_min_u32_e32 v53, v44, v51
	v_min_u32_e32 v13, v54, v12
	v_min_u32_e32 v48, v39, v46
	v_min_u32_e32 v57, v55, v10
	v_max_u32_e32 v9, v9, v11
	v_min_u32_e32 v15, v15, v32
	v_max_u32_e32 v32, v42, v45
	v_min_u32_e32 v45, v49, v52
	v_max_u32_e32 v8, v56, v8
	v_min_u32_e32 v14, v53, v13
	v_min_u32_e32 v58, v48, v57
	v_min_u32_e32 v47, v38, v43
	v_min_u32_e32 v11, v50, v9
	v_min_u32_e32 v42, v15, v32
	v_min_u32_e32 v49, v45, v8
	v_max_u32_e32 v13, v53, v13
	v_max_u32_e32 v48, v48, v57
	v_max_u32_e32 v44, v44, v51
	v_max_u32_e32 v12, v54, v12
	v_max_u32_e32 v39, v39, v46
	v_max_u32_e32 v10, v55, v10
	v_max_u32_e32 v38, v38, v43
	v_max_u32_e32 v9, v50, v9
	v_max_u32_e32 v15, v15, v32
	v_max_u32_e32 v8, v45, v8
	v_min_u32_e32 v60, v47, v11
	v_min_u32_e32 v52, v42, v49
	v_min_u32_e32 v53, v13, v48
	v_max_u32_e32 v11, v47, v11
	v_max_u32_e32 v42, v42, v49
	v_max_u32_e32 v13, v13, v48
	v_min_u32_e32 v48, v44, v12
	v_min_u32_e32 v46, v39, v10
	v_min_u32_e32 v43, v38, v9
	v_min_u32_e32 v32, v15, v8
	v_max_u32_e32 v12, v44, v12
	v_max_u32_e32 v10, v39, v10
	v_max_u32_e32 v9, v38, v9
	v_max_u32_e32 v8, v15, v8
	s_waitcnt vmcnt(1)
	ds_write_b128 v109, v[240:243]
	s_waitcnt vmcnt(0)
	ds_write_b128 v108, v[244:247]
	s_waitcnt lgkmcnt(0)
	s_barrier
	ds_read_b128 v[0:3], v84
	v_min_u32_e32 v59, v14, v58
	v_min_u32_e32 v56, v60, v52
	v_min_u32_e32 v47, v11, v42
	v_min_u32_e32 v51, v48, v46
	v_min_u32_e32 v45, v43, v32
	v_min_u32_e32 v39, v12, v10
	v_min_u32_e32 v15, v9, v8
	v_min_u32_e32 v61, v59, v56
	v_min_u32_e32 v49, v53, v47
	v_max_u32_e32 v11, v11, v42
	v_min_u32_e32 v50, v51, v45
	v_min_u32_e32 v38, v39, v15
	v_max_u32_e32 v10, v12, v10
	v_max_u32_e32 v8, v9, v8
	v_min_u32_e32 v17, v68, v16
	v_min_u32_e32 v20, v18, v19
	v_min_u32_e32 v37, v26, v33
	v_min_u32_e32 v31, v24, v25
	v_min_u32_e32 v42, v13, v11
	v_min_u32_e32 v9, v10, v8
	v_max3_u32 v12, v24, v25, v61
	v_max3_u32 v26, v26, v33, v49
	v_max3_u32 v11, v41, v13, v11
	v_max3_u32 v13, v28, v29, v50
	v_max3_u32 v18, v18, v19, v38
	v_max3_u32 v24, v31, v59, v56
	v_max3_u32 v9, v68, v16, v9
	v_max3_u32 v8, v17, v10, v8
	v_max_u32_e32 v10, v12, v13
	v_min_u32_e32 v31, v12, v13
	v_max_u32_e32 v13, v26, v18
	v_min_u32_e32 v38, v26, v18
	ds_read_b128 v[16:19], v81 offset:256
	v_max_u32_e32 v14, v14, v58
	v_max_u32_e32 v52, v60, v52
	v_max_u32_e32 v46, v48, v46
	v_max_u32_e32 v32, v43, v32
	v_min_u32_e32 v23, v21, v22
	v_min_u32_e32 v30, v28, v29
	v_min_u32_e32 v36, v27, v35
	v_min_u32_e32 v58, v14, v52
	v_min_u32_e32 v43, v46, v32
	v_max3_u32 v25, v27, v35, v58
	v_max3_u32 v14, v36, v14, v52
	v_max3_u32 v27, v37, v53, v47
	v_max3_u32 v28, v30, v51, v45
	v_max3_u32 v21, v21, v22, v43
	v_max3_u32 v22, v23, v46, v32
	v_max3_u32 v15, v20, v39, v15
	v_max3_u32 v33, v34, v40, v42
	v_max_u32_e32 v12, v24, v28
	v_min_u32_e32 v29, v24, v28
	v_max_u32_e32 v40, v14, v22
	v_min_u32_e32 v28, v14, v22
	v_max_u32_e32 v14, v27, v15
	v_min_u32_e32 v36, v27, v15
	v_max_u32_e32 v41, v33, v9
	v_min_u32_e32 v37, v33, v9
	v_max_u32_e32 v42, v11, v8
	v_min_u32_e32 v56, v11, v8
	v_max_u32_e32 v55, v10, v13
	v_min_u32_e32 v52, v10, v13
	v_max_u32_e32 v54, v12, v14
	v_min_u32_e32 v53, v12, v14
	s_waitcnt lgkmcnt(0)
	v_mfma_f32_32x32x16_bf16 v[0:15], v[0:3], v[16:19], 0
	v_max_u32_e32 v39, v25, v21
	v_min_u32_e32 v30, v25, v21
	ds_read_b128 v[24:27], v107
	ds_read_b128 v[20:23], v81 offset:288
	ds_read_b128 v[32:35], v84 offset:8192
	v_max_u32_e32 v57, v39, v41
	v_min_u32_e32 v64, v39, v41
	v_max_u32_e32 v65, v40, v42
	v_min_u32_e32 v66, v40, v42
	s_waitcnt lgkmcnt(1)
	v_mfma_f32_32x32x16_bf16 v[0:15], v[24:27], v[20:23], v[0:15]
	ds_read_b128 v[58:61], v106
	ds_read_b128 v[44:47], v107 offset:8192
	ds_read_b128 v[40:43], v81 offset:320
	v_max_u32_e32 v68, v31, v38
	v_min_u32_e32 v69, v31, v38
	v_max_u32_e32 v70, v29, v36
	v_min_u32_e32 v76, v29, v36
	v_max_u32_e32 v71, v30, v37
	s_waitcnt lgkmcnt(0)
	v_mfma_f32_32x32x16_bf16 v[0:15], v[58:61], v[40:43], v[0:15]
	v_min_u32_e32 v77, v30, v37
	ds_read_b128 v[24:27], v105
	ds_read_b128 v[36:39], v81 offset:352
	ds_read_b128 v[48:51], v106 offset:8192
	v_max_u32_e32 v72, v28, v56
	v_min_u32_e32 v78, v28, v56
	v_max_u32_e32 v82, v55, v57
	v_min_u32_e32 v83, v55, v57
	ds_read_b128 v[28:31], v104
	ds_read_b128 v[60:63], v105 offset:8192
	s_waitcnt lgkmcnt(3)
	v_mfma_f32_32x32x16_bf16 v[0:15], v[24:27], v[36:39], v[0:15]
	ds_read_b128 v[56:59], v81 offset:384
	v_max_u32_e32 v84, v54, v65
	v_min_u32_e32 v108, v54, v65
	v_max_u32_e32 v109, v52, v64
	v_min_u32_e32 v110, v52, v64
	v_max_u32_e32 v111, v53, v66
	v_min_u32_e32 v112, v53, v66
	s_waitcnt lgkmcnt(0)
	v_mfma_f32_32x32x16_bf16 v[0:15], v[28:31], v[56:59], v[0:15]
	ds_read_b128 v[24:27], v103
	ds_read_b128 v[52:55], v81 offset:416
	ds_read_b128 v[64:67], v104 offset:8192
	v_max_u32_e32 v113, v68, v71
	v_min_u32_e32 v114, v68, v71
	v_max_u32_e32 v115, v70, v72
	v_min_u32_e32 v116, v70, v72
	v_max_u32_e32 v117, v69, v77
	ds_read_b128 v[28:31], v102
	ds_read_b128 v[72:75], v103 offset:8192
	s_waitcnt lgkmcnt(3)
	v_mfma_f32_32x32x16_bf16 v[0:15], v[24:27], v[52:55], v[0:15]
	v_min_u32_e32 v103, v69, v77
	ds_read_b128 v[68:71], v81 offset:448
	v_max_u32_e32 v118, v76, v78
	v_min_u32_e32 v119, v76, v78
	ds_read_b128 v[104:107], v101
	ds_read_b128 v[24:27], v81 offset:480
	ds_read_b128 v[76:79], v102 offset:8192
	v_min_u32_e32 v120, v82, v84
	v_min_u32_e32 v121, v83, v108
	s_waitcnt lgkmcnt(3)
	v_mfma_f32_32x32x16_bf16 v[0:15], v[28:31], v[68:71], v[0:15]
	ds_read_b128 v[28:31], v101 offset:8192
	v_min_u32_e32 v102, v110, v112
	v_min_u32_e32 v122, v113, v115
	v_min_u32_e32 v81, v109, v111
	v_min_u32_e32 v123, v114, v116
	v_min_u32_e32 v124, v117, v118
	v_min_u32_e32 v125, v103, v119
	s_waitcnt lgkmcnt(2)
	v_mfma_f32_32x32x16_bf16 v[0:15], v[104:107], v[24:27], v[0:15]
	s_nop 11
	v_ashrrev_i32_e32 v101, 31, v0
	v_ashrrev_i32_e32 v104, 31, v3
	v_ashrrev_i32_e32 v106, 31, v7
	v_ashrrev_i32_e32 v107, 31, v4
	v_ashrrev_i32_e32 v129, 31, v15
	v_ashrrev_i32_e32 v130, 31, v12
	v_ashrrev_i32_e32 v132, 31, v8
	v_ashrrev_i32_e32 v134, 31, v11
	v_bitop3_b32 v0, v101, v0, s76 bitop3:0x36
	v_ashrrev_i32_e32 v101, 31, v1
	v_bitop3_b32 v3, v104, v3, s76 bitop3:0x36
	v_ashrrev_i32_e32 v104, 31, v2
	v_bitop3_b32 v7, v106, v7, s76 bitop3:0x36
	v_ashrrev_i32_e32 v106, 31, v6
	v_bitop3_b32 v4, v107, v4, s76 bitop3:0x36
	v_ashrrev_i32_e32 v107, 31, v5
	v_bitop3_b32 v15, v129, v15, s76 bitop3:0x36
	v_ashrrev_i32_e32 v129, 31, v14
	v_bitop3_b32 v12, v130, v12, s76 bitop3:0x36
	v_ashrrev_i32_e32 v130, 31, v13
	v_bitop3_b32 v8, v132, v8, s76 bitop3:0x36
	v_ashrrev_i32_e32 v132, 31, v9
	v_bitop3_b32 v11, v134, v11, s76 bitop3:0x36
	v_ashrrev_i32_e32 v134, 31, v10
	v_bitop3_b32 v1, v101, v1, s76 bitop3:0x36
	v_bitop3_b32 v2, v104, v2, s76 bitop3:0x36
	v_bitop3_b32 v6, v106, v6, s76 bitop3:0x36
	v_bitop3_b32 v5, v107, v5, s76 bitop3:0x36
	v_bitop3_b32 v14, v129, v14, s76 bitop3:0x36
	v_bitop3_b32 v13, v130, v13, s76 bitop3:0x36
	v_bitop3_b32 v9, v132, v9, s76 bitop3:0x36
	v_bitop3_b32 v10, v134, v10, s76 bitop3:0x36
	v_and_or_b32 v0, v0, s77, v174
	v_and_or_b32 v1, v1, s77, v173
	v_and_or_b32 v3, v3, s77, v172
	v_and_or_b32 v2, v2, s77, v169
	v_and_or_b32 v7, v7, s77, v167
	v_and_or_b32 v6, v6, s77, v166
	v_and_or_b32 v4, v4, s77, v163
	v_and_or_b32 v5, v5, s77, v162
	v_and_or_b32 v15, v15, s77, v158
	v_and_or_b32 v14, v14, s77, v156
	v_and_or_b32 v12, v12, s77, v154
	v_and_or_b32 v13, v13, s77, v152
	v_and_or_b32 v8, v8, s77, v147
	v_and_or_b32 v9, v9, s77, v146
	v_and_or_b32 v11, v11, s77, v145
	v_and_or_b32 v10, v10, s77, v142
	v_max_u32_e32 v101, v0, v1
	v_min_u32_e32 v104, v3, v2
	v_min_u32_e32 v0, v0, v1
	v_max_u32_e32 v1, v3, v2
	v_max_u32_e32 v106, v7, v6
	v_min_u32_e32 v107, v4, v5
	v_min_u32_e32 v6, v7, v6
	v_max_u32_e32 v4, v4, v5
	v_max_u32_e32 v129, v15, v14
	v_min_u32_e32 v130, v12, v13
	v_min_u32_e32 v14, v15, v14
	v_max_u32_e32 v12, v12, v13
	v_max_u32_e32 v132, v8, v9
	v_min_u32_e32 v134, v11, v10
	v_min_u32_e32 v8, v8, v9
	v_max_u32_e32 v9, v11, v10
	v_max_u32_e32 v105, v101, v104
	v_max_u32_e32 v2, v0, v1
	v_min_u32_e32 v126, v106, v107
	v_min_u32_e32 v5, v6, v4
	v_min_u32_e32 v101, v101, v104
	v_min_u32_e32 v0, v0, v1
	v_max_u32_e32 v104, v106, v107
	v_max_u32_e32 v4, v6, v4
	v_max_u32_e32 v131, v129, v130
	v_max_u32_e32 v13, v14, v12
	v_min_u32_e32 v135, v132, v134
	v_min_u32_e32 v10, v8, v9
	v_min_u32_e32 v129, v129, v130
	v_min_u32_e32 v12, v14, v12
	v_max_u32_e32 v130, v132, v134
	v_max_u32_e32 v8, v8, v9
	v_max_u32_e32 v3, v105, v2
	v_min_u32_e32 v7, v126, v5
	v_max_u32_e32 v1, v101, v0
	v_min_u32_e32 v6, v104, v4
	v_min_u32_e32 v2, v105, v2
	v_max_u32_e32 v5, v126, v5
	v_min_u32_e32 v0, v101, v0
	v_max_u32_e32 v4, v104, v4
	v_max_u32_e32 v15, v131, v13
	v_min_u32_e32 v11, v135, v10
	v_max_u32_e32 v14, v129, v12
	v_min_u32_e32 v9, v130, v8
	v_min_u32_e32 v13, v131, v13
	v_max_u32_e32 v10, v135, v10
	v_min_u32_e32 v12, v129, v12
	v_max_u32_e32 v8, v130, v8
	v_max_u32_e32 v127, v3, v7
	v_max_u32_e32 v106, v1, v6
	v_max_u32_e32 v105, v2, v5
	v_max_u32_e32 v101, v0, v4
	v_min_u32_e32 v136, v15, v11
	v_min_u32_e32 v132, v14, v9
	v_min_u32_e32 v131, v13, v10
	v_min_u32_e32 v129, v12, v8
	v_min_u32_e32 v3, v3, v7
	v_min_u32_e32 v1, v1, v6
	v_min_u32_e32 v2, v2, v5
	v_min_u32_e32 v0, v0, v4
	v_max_u32_e32 v7, v15, v11
	v_max_u32_e32 v9, v14, v9
	v_max_u32_e32 v10, v13, v10
	v_max_u32_e32 v8, v12, v8
	v_max_u32_e32 v107, v127, v106
	v_max_u32_e32 v104, v105, v101
	v_min_u32_e32 v134, v136, v132
	v_min_u32_e32 v130, v131, v129
	v_max_u32_e32 v6, v3, v1
	v_max_u32_e32 v4, v2, v0
	v_min_u32_e32 v11, v7, v9
	v_min_u32_e32 v12, v10, v8
	v_min_u32_e32 v106, v127, v106
	v_min_u32_e32 v101, v105, v101
	v_max_u32_e32 v127, v136, v132
	v_max_u32_e32 v129, v131, v129
	v_min_u32_e32 v1, v3, v1
	v_min_u32_e32 v0, v2, v0
	v_max_u32_e32 v3, v7, v9
	v_max_u32_e32 v7, v10, v8
	v_max_u32_e32 v126, v107, v104
	v_min_u32_e32 v135, v134, v130
	v_max_u32_e32 v5, v6, v4
	v_min_u32_e32 v13, v11, v12
	v_max_u32_e32 v105, v106, v101
	v_min_u32_e32 v131, v127, v129
	v_max_u32_e32 v2, v1, v0
	v_min_u32_e32 v8, v3, v7
	v_min_u32_e32 v137, v126, v135
	v_min_u32_e32 v14, v5, v13
	v_min_u32_e32 v132, v105, v131
	v_min_u32_e32 v9, v2, v8
	v_min_u32_e32 v15, v137, v14
	v_min_u32_e32 v10, v132, v9
	v_min_u32_e32 v104, v107, v104
	v_max_u32_e32 v107, v134, v130
	v_min_u32_e32 v4, v6, v4
	v_max_u32_e32 v6, v11, v12
	v_min_u32_e32 v101, v106, v101
	v_max_u32_e32 v106, v127, v129
	v_min_u32_e32 v0, v1, v0
	v_max_u32_e32 v1, v3, v7
	v_max_u32_e32 v14, v137, v14
	v_max_u32_e32 v9, v132, v9
	v_min_u32_e32 v136, v15, v10
	v_min_u32_e32 v130, v104, v107
	v_min_u32_e32 v11, v4, v6
	v_min_u32_e32 v127, v101, v106
	v_min_u32_e32 v3, v0, v1
	v_max_u32_e32 v10, v15, v10
	v_min_u32_e32 v15, v14, v9
	v_max_u32_e32 v9, v14, v9
	v_max_u32_e32 v14, v126, v135
	v_max_u32_e32 v5, v5, v13
	v_max_u32_e32 v105, v105, v131
	v_max_u32_e32 v2, v2, v8
	v_max_u32_e32 v104, v104, v107
	v_max_u32_e32 v4, v4, v6
	v_max_u32_e32 v101, v101, v106
	v_max_u32_e32 v0, v0, v1
	v_min_u32_e32 v12, v130, v11
	v_min_u32_e32 v7, v127, v3
	v_min_u32_e32 v13, v14, v5
	v_min_u32_e32 v8, v105, v2
	v_min_u32_e32 v6, v104, v4
	v_min_u32_e32 v1, v101, v0
	v_min_u32_e32 v129, v12, v7
	v_max_u32_e32 v7, v12, v7
	v_max_u32_e32 v11, v130, v11
	v_max_u32_e32 v3, v127, v3
	v_min_u32_e32 v126, v13, v8
	v_min_u32_e32 v106, v6, v1
	v_max_u32_e32 v8, v13, v8
	v_max_u32_e32 v1, v6, v1
	v_max_u32_e32 v5, v14, v5
	v_max_u32_e32 v2, v105, v2
	v_max_u32_e32 v4, v104, v4
	v_max_u32_e32 v0, v101, v0
	v_min_u32_e32 v134, v136, v129
	v_min_u32_e32 v12, v10, v7
	v_min_u32_e32 v127, v11, v3
	v_max_u32_e32 v3, v11, v3
	v_min_u32_e32 v107, v126, v106
	v_min_u32_e32 v6, v8, v1
	v_min_u32_e32 v13, v5, v2
	v_min_u32_e32 v14, v4, v0
	v_max_u32_e32 v2, v5, v2
	v_max_u32_e32 v0, v4, v0
	v_min_u32_e32 v130, v15, v127
	v_min_u32_e32 v11, v9, v3
	v_min_u32_e32 v4, v2, v0
	v_max3_u32 v5, v82, v84, v134
	v_max3_u32 v82, v120, v136, v129
	v_max3_u32 v12, v83, v108, v12
	v_max3_u32 v83, v121, v10, v7
	v_max3_u32 v102, v102, v9, v3
	v_max3_u32 v3, v113, v115, v107
	v_max3_u32 v7, v122, v126, v106
	v_max3_u32 v6, v114, v116, v6
	v_min_u32_e32 v101, v13, v14
	v_max3_u32 v84, v109, v111, v130
	v_max3_u32 v81, v81, v15, v127
	v_max3_u32 v104, v110, v112, v11
	v_max3_u32 v105, v123, v8, v1
	v_max3_u32 v106, v124, v13, v14
	v_max3_u32 v103, v103, v119, v4
	v_max3_u32 v107, v125, v2, v0
	v_max_u32_e32 v108, v5, v3
	v_min_u32_e32 v109, v5, v3
	v_max_u32_e32 v110, v82, v7
	v_min_u32_e32 v82, v82, v7
	v_max_u32_e32 v111, v12, v6
	v_min_u32_e32 v112, v12, v6
	v_mfma_f32_32x32x16_bf16 v[0:15], v[32:35], v[16:19], 0
	v_max3_u32 v101, v117, v118, v101
	v_max_u32_e32 v113, v83, v105
	v_min_u32_e32 v16, v83, v105
	v_max_u32_e32 v17, v84, v101
	v_min_u32_e32 v18, v84, v101
	v_max_u32_e32 v19, v81, v106
	v_min_u32_e32 v32, v81, v106
	v_mfma_f32_32x32x16_bf16 v[0:15], v[44:47], v[20:23], v[0:15]
	v_max_u32_e32 v33, v104, v103
	v_min_u32_e32 v34, v104, v103
	v_max_u32_e32 v20, v102, v107
	v_min_u32_e32 v21, v102, v107
	v_max_u32_e32 v22, v108, v17
	v_min_u32_e32 v17, v108, v17
	v_max_u32_e32 v23, v110, v19
	v_mfma_f32_32x32x16_bf16 v[0:15], v[48:51], v[40:43], v[0:15]
	v_min_u32_e32 v19, v110, v19
	v_max_u32_e32 v35, v111, v33
	v_min_u32_e32 v33, v111, v33
	v_max_u32_e32 v40, v113, v20
	v_min_u32_e32 v20, v113, v20
	v_max_u32_e32 v41, v109, v18
	v_min_u32_e32 v18, v109, v18
	v_mfma_f32_32x32x16_bf16 v[0:15], v[60:63], v[36:39], v[0:15]
	v_max_u32_e32 v42, v82, v32
	v_min_u32_e32 v32, v82, v32
	v_max_u32_e32 v36, v112, v34
	v_min_u32_e32 v34, v112, v34
	v_max_u32_e32 v37, v16, v21
	v_min_u32_e32 v16, v16, v21
	v_max_u32_e32 v21, v22, v35
	v_mfma_f32_32x32x16_bf16 v[0:15], v[64:67], v[56:59], v[0:15]
	v_min_u32_e32 v22, v22, v35
	v_max_u32_e32 v35, v23, v40
	v_min_u32_e32 v23, v23, v40
	v_max_u32_e32 v38, v17, v33
	v_min_u32_e32 v17, v17, v33
	v_max_u32_e32 v33, v19, v20
	v_min_u32_e32 v19, v19, v20
	v_mfma_f32_32x32x16_bf16 v[0:15], v[72:75], v[52:55], v[0:15]
	v_max_u32_e32 v20, v41, v36
	v_min_u32_e32 v36, v41, v36
	v_max_u32_e32 v39, v42, v37
	v_min_u32_e32 v37, v42, v37
	v_max_u32_e32 v40, v18, v34
	v_min_u32_e32 v18, v18, v34
	v_max_u32_e32 v34, v32, v16
	s_waitcnt lgkmcnt(1)
	v_mfma_f32_32x32x16_bf16 v[0:15], v[76:79], v[68:71], v[0:15]
	v_min_u32_e32 v16, v32, v16
	v_min_u32_e32 v32, v21, v35
	v_min_u32_e32 v41, v22, v23
	v_min_u32_e32 v42, v38, v33
	v_min_u32_e32 v43, v17, v19
	v_min_u32_e32 v44, v20, v39
	v_min_u32_e32 v45, v36, v37
	s_waitcnt lgkmcnt(0)
	v_mfma_f32_32x32x16_bf16 v[0:15], v[28:31], v[24:27], v[0:15]
	v_min_u32_e32 v46, v40, v34
	v_min_u32_e32 v47, v18, v16
	v_ashrrev_i32_e32 v81, 31, v80
	s_nop 8
	v_ashrrev_i32_e32 v24, 31, v0
	v_ashrrev_i32_e32 v25, 31, v3
	v_ashrrev_i32_e32 v27, 31, v7
	v_ashrrev_i32_e32 v28, 31, v4
	v_ashrrev_i32_e32 v31, 31, v15
	v_ashrrev_i32_e32 v48, 31, v12
	v_ashrrev_i32_e32 v50, 31, v8
	v_ashrrev_i32_e32 v51, 31, v11
	v_bitop3_b32 v0, v24, v0, s76 bitop3:0x36
	v_ashrrev_i32_e32 v24, 31, v1
	v_bitop3_b32 v3, v25, v3, s76 bitop3:0x36
	v_ashrrev_i32_e32 v25, 31, v2
	v_bitop3_b32 v7, v27, v7, s76 bitop3:0x36
	v_ashrrev_i32_e32 v27, 31, v6
	v_bitop3_b32 v4, v28, v4, s76 bitop3:0x36
	v_ashrrev_i32_e32 v28, 31, v5
	v_bitop3_b32 v15, v31, v15, s76 bitop3:0x36
	v_ashrrev_i32_e32 v31, 31, v14
	v_bitop3_b32 v12, v48, v12, s76 bitop3:0x36
	v_ashrrev_i32_e32 v48, 31, v13
	v_bitop3_b32 v8, v50, v8, s76 bitop3:0x36
	v_ashrrev_i32_e32 v50, 31, v9
	v_bitop3_b32 v11, v51, v11, s76 bitop3:0x36
	v_ashrrev_i32_e32 v51, 31, v10
	v_bitop3_b32 v1, v24, v1, s76 bitop3:0x36
	v_bitop3_b32 v2, v25, v2, s76 bitop3:0x36
	v_bitop3_b32 v6, v27, v6, s76 bitop3:0x36
	v_bitop3_b32 v5, v28, v5, s76 bitop3:0x36
	v_bitop3_b32 v14, v31, v14, s76 bitop3:0x36
	v_bitop3_b32 v13, v48, v13, s76 bitop3:0x36
	v_bitop3_b32 v9, v50, v9, s76 bitop3:0x36
	v_bitop3_b32 v10, v51, v10, s76 bitop3:0x36
	v_and_or_b32 v0, v0, s77, v185
	v_and_or_b32 v1, v1, s77, v184
	v_and_or_b32 v3, v3, s77, v183
	v_and_or_b32 v2, v2, s77, v182
	v_and_or_b32 v7, v7, s77, v181
	v_and_or_b32 v6, v6, s77, v180
	v_and_or_b32 v4, v4, s77, v179
	v_and_or_b32 v5, v5, s77, v175
	v_and_or_b32 v15, v15, s77, v170
	v_and_or_b32 v14, v14, s77, v168
	v_and_or_b32 v12, v12, s77, v165
	v_and_or_b32 v13, v13, s77, v164
	v_and_or_b32 v8, v8, s77, v161
	v_and_or_b32 v9, v9, s77, v160
	v_and_or_b32 v11, v11, s77, v159
	v_and_or_b32 v10, v10, s77, v157
	v_max_u32_e32 v24, v0, v1
	v_min_u32_e32 v25, v3, v2
	v_min_u32_e32 v0, v0, v1
	v_max_u32_e32 v1, v3, v2
	v_max_u32_e32 v27, v7, v6
	v_min_u32_e32 v28, v4, v5
	v_min_u32_e32 v6, v7, v6
	v_max_u32_e32 v4, v4, v5
	v_max_u32_e32 v31, v15, v14
	v_min_u32_e32 v48, v12, v13
	v_min_u32_e32 v14, v15, v14
	v_max_u32_e32 v12, v12, v13
	v_max_u32_e32 v50, v8, v9
	v_min_u32_e32 v51, v11, v10
	v_min_u32_e32 v8, v8, v9
	v_max_u32_e32 v9, v11, v10
	v_max_u32_e32 v26, v24, v25
	v_max_u32_e32 v2, v0, v1
	v_min_u32_e32 v29, v27, v28
	v_min_u32_e32 v5, v6, v4
	v_min_u32_e32 v24, v24, v25
	v_min_u32_e32 v0, v0, v1
	v_max_u32_e32 v25, v27, v28
	v_max_u32_e32 v4, v6, v4
	v_max_u32_e32 v49, v31, v48
	v_max_u32_e32 v13, v14, v12
	v_min_u32_e32 v52, v50, v51
	v_min_u32_e32 v10, v8, v9
	v_min_u32_e32 v31, v31, v48
	v_min_u32_e32 v12, v14, v12
	v_max_u32_e32 v48, v50, v51
	v_max_u32_e32 v8, v8, v9
	v_max_u32_e32 v3, v26, v2
	v_min_u32_e32 v7, v29, v5
	v_max_u32_e32 v1, v24, v0
	v_min_u32_e32 v6, v25, v4
	v_min_u32_e32 v2, v26, v2
	v_max_u32_e32 v5, v29, v5
	v_min_u32_e32 v0, v24, v0
	v_max_u32_e32 v4, v25, v4
	v_max_u32_e32 v15, v49, v13
	v_min_u32_e32 v11, v52, v10
	v_max_u32_e32 v14, v31, v12
	v_min_u32_e32 v9, v48, v8
	v_min_u32_e32 v13, v49, v13
	v_max_u32_e32 v10, v52, v10
	v_min_u32_e32 v12, v31, v12
	v_max_u32_e32 v8, v48, v8
	v_max_u32_e32 v30, v3, v7
	v_max_u32_e32 v27, v1, v6
	v_max_u32_e32 v26, v2, v5
	v_max_u32_e32 v24, v0, v4
	v_min_u32_e32 v53, v15, v11
	v_min_u32_e32 v50, v14, v9
	v_min_u32_e32 v49, v13, v10
	v_min_u32_e32 v31, v12, v8
	v_min_u32_e32 v3, v3, v7
	v_min_u32_e32 v1, v1, v6
	v_min_u32_e32 v2, v2, v5
	v_min_u32_e32 v0, v0, v4
	v_max_u32_e32 v7, v15, v11
	v_max_u32_e32 v9, v14, v9
	v_max_u32_e32 v10, v13, v10
	v_max_u32_e32 v8, v12, v8
	v_max_u32_e32 v28, v30, v27
	v_max_u32_e32 v25, v26, v24
	v_min_u32_e32 v51, v53, v50
	v_min_u32_e32 v48, v49, v31
	v_max_u32_e32 v6, v3, v1
	v_max_u32_e32 v4, v2, v0
	v_min_u32_e32 v11, v7, v9
	v_min_u32_e32 v12, v10, v8
	v_min_u32_e32 v27, v30, v27
	v_min_u32_e32 v24, v26, v24
	v_max_u32_e32 v30, v53, v50
	v_max_u32_e32 v31, v49, v31
	v_min_u32_e32 v1, v3, v1
	v_min_u32_e32 v0, v2, v0
	v_max_u32_e32 v3, v7, v9
	v_max_u32_e32 v7, v10, v8
	v_max_u32_e32 v29, v28, v25
	v_min_u32_e32 v52, v51, v48
	v_max_u32_e32 v5, v6, v4
	v_min_u32_e32 v13, v11, v12
	v_max_u32_e32 v26, v27, v24
	v_min_u32_e32 v49, v30, v31
	v_max_u32_e32 v2, v1, v0
	v_min_u32_e32 v8, v3, v7
	v_min_u32_e32 v54, v29, v52
	v_min_u32_e32 v14, v5, v13
	v_min_u32_e32 v50, v26, v49
	v_min_u32_e32 v9, v2, v8
	v_min_u32_e32 v15, v54, v14
	v_min_u32_e32 v10, v50, v9
	v_min_u32_e32 v25, v28, v25
	v_max_u32_e32 v28, v51, v48
	v_min_u32_e32 v4, v6, v4
	v_max_u32_e32 v6, v11, v12
	v_min_u32_e32 v24, v27, v24
	v_max_u32_e32 v27, v30, v31
	v_min_u32_e32 v0, v1, v0
	v_max_u32_e32 v1, v3, v7
	v_max_u32_e32 v14, v54, v14
	v_max_u32_e32 v9, v50, v9
	v_min_u32_e32 v53, v15, v10
	v_min_u32_e32 v48, v25, v28
	v_min_u32_e32 v11, v4, v6
	v_min_u32_e32 v30, v24, v27
	v_min_u32_e32 v3, v0, v1
	v_max_u32_e32 v10, v15, v10
	v_min_u32_e32 v15, v14, v9
	v_max_u32_e32 v9, v14, v9
	v_max_u32_e32 v14, v29, v52
	v_max_u32_e32 v5, v5, v13
	v_max_u32_e32 v26, v26, v49
	v_max_u32_e32 v2, v2, v8
	v_max_u32_e32 v25, v25, v28
	v_max_u32_e32 v4, v4, v6
	v_max_u32_e32 v24, v24, v27
	v_max_u32_e32 v0, v0, v1
	v_min_u32_e32 v12, v48, v11
	v_min_u32_e32 v7, v30, v3
	v_max_u32_e32 v11, v48, v11
	v_max_u32_e32 v3, v30, v3
	v_min_u32_e32 v13, v14, v5
	v_min_u32_e32 v8, v26, v2
	v_min_u32_e32 v6, v25, v4
	v_min_u32_e32 v1, v24, v0
	v_max_u32_e32 v5, v14, v5
	v_max_u32_e32 v2, v26, v2
	v_max_u32_e32 v4, v25, v4
	v_max_u32_e32 v0, v24, v0
	v_min_u32_e32 v31, v12, v7
	v_max_u32_e32 v7, v12, v7
	v_min_u32_e32 v30, v11, v3
	v_max_u32_e32 v3, v11, v3
	v_min_u32_e32 v29, v13, v8
	v_min_u32_e32 v27, v6, v1
	v_max_u32_e32 v8, v13, v8
	v_max_u32_e32 v1, v6, v1
	v_min_u32_e32 v13, v5, v2
	v_min_u32_e32 v14, v4, v0
	v_max_u32_e32 v2, v5, v2
	v_max_u32_e32 v0, v4, v0
	v_min_u32_e32 v51, v53, v31
	v_min_u32_e32 v12, v10, v7
	v_min_u32_e32 v48, v15, v30
	v_min_u32_e32 v11, v9, v3
	v_min_u32_e32 v28, v29, v27
	v_min_u32_e32 v6, v8, v1
	v_min_u32_e32 v24, v13, v14
	v_min_u32_e32 v4, v2, v0
	v_max3_u32 v5, v21, v35, v51
	v_max3_u32 v21, v32, v53, v31
	v_max3_u32 v12, v22, v23, v12
	v_max3_u32 v7, v41, v10, v7
	v_max3_u32 v10, v38, v33, v48
	v_max3_u32 v15, v42, v15, v30
	v_max3_u32 v11, v17, v19, v11
	v_max3_u32 v3, v43, v9, v3
	v_max3_u32 v9, v20, v39, v28
	v_max3_u32 v17, v44, v29, v27
	v_max3_u32 v6, v36, v37, v6
	v_max3_u32 v1, v45, v8, v1
	v_max3_u32 v8, v40, v34, v24
	v_max3_u32 v13, v46, v13, v14
	v_max3_u32 v4, v18, v16, v4
	v_max3_u32 v0, v47, v2, v0
	v_max_u32_e32 v2, v5, v9
	v_min_u32_e32 v5, v5, v9
	v_max_u32_e32 v9, v21, v17
	v_min_u32_e32 v14, v21, v17
	v_max_u32_e32 v16, v12, v6
	v_min_u32_e32 v6, v12, v6
	v_max_u32_e32 v12, v7, v1
	v_min_u32_e32 v1, v7, v1
	v_max_u32_e32 v7, v10, v8
	v_min_u32_e32 v8, v10, v8
	v_max_u32_e32 v10, v15, v13
	v_min_u32_e32 v13, v15, v13
	v_max_u32_e32 v15, v11, v4
	v_min_u32_e32 v4, v11, v4
	v_max_u32_e32 v11, v3, v0
	v_min_u32_e32 v0, v3, v0
	v_max_u32_e32 v3, v2, v7
	v_min_u32_e32 v2, v2, v7
	v_max_u32_e32 v7, v9, v10
	v_min_u32_e32 v9, v9, v10
	v_max_u32_e32 v10, v16, v15
	v_min_u32_e32 v15, v16, v15
	v_max_u32_e32 v16, v12, v11
	v_min_u32_e32 v11, v12, v11
	v_max_u32_e32 v12, v5, v8
	v_min_u32_e32 v5, v5, v8
	v_max_u32_e32 v8, v14, v13
	v_min_u32_e32 v13, v14, v13
	v_max_u32_e32 v14, v6, v4
	v_min_u32_e32 v4, v6, v4
	v_max_u32_e32 v6, v1, v0
	v_min_u32_e32 v0, v1, v0
	v_max_u32_e32 v1, v3, v10
	v_min_u32_e32 v3, v3, v10
	v_max_u32_e32 v10, v7, v16
	v_min_u32_e32 v7, v7, v16
	v_max_u32_e32 v16, v2, v15
	v_min_u32_e32 v2, v2, v15
	v_max_u32_e32 v15, v9, v11
	v_min_u32_e32 v9, v9, v11
	v_max_u32_e32 v11, v12, v14
	v_min_u32_e32 v12, v12, v14
	v_max_u32_e32 v14, v8, v6
	v_min_u32_e32 v6, v8, v6
	v_max_u32_e32 v8, v5, v4
	v_min_u32_e32 v4, v5, v4
	v_max_u32_e32 v5, v13, v0
	v_min_u32_e32 v0, v13, v0
	v_max_u32_e32 v13, v1, v10
	v_min_u32_e32 v1, v1, v10
	v_max_u32_e32 v10, v3, v7
	v_min_u32_e32 v3, v3, v7
	v_max_u32_e32 v7, v16, v15
	v_min_u32_e32 v15, v16, v15
	v_max_u32_e32 v16, v2, v9
	v_min_u32_e32 v2, v2, v9
	v_max_u32_e32 v9, v11, v14
	v_min_u32_e32 v11, v11, v14
	v_max_u32_e32 v14, v12, v6
	v_min_u32_e32 v6, v12, v6
	v_max_u32_e32 v12, v8, v5
	v_min_u32_e32 v5, v8, v5
	v_max_u32_e32 v8, v4, v0
	v_min_u32_e32 v0, v4, v0
	ds_bpermute_b32 v4, v141, v13
	ds_bpermute_b32 v17, v141, v1
	ds_bpermute_b32 v18, v141, v10
	ds_bpermute_b32 v19, v141, v3
	ds_bpermute_b32 v20, v141, v7
	ds_bpermute_b32 v21, v141, v15
	ds_bpermute_b32 v22, v141, v16
	ds_bpermute_b32 v23, v141, v2
	ds_bpermute_b32 v24, v141, v9
	ds_bpermute_b32 v25, v141, v11
	ds_bpermute_b32 v26, v141, v14
	ds_bpermute_b32 v27, v141, v0
	ds_bpermute_b32 v28, v141, v8
	ds_bpermute_b32 v29, v141, v5
	ds_bpermute_b32 v30, v141, v12
	ds_bpermute_b32 v31, v141, v6
	s_waitcnt lgkmcnt(4)
	v_max_u32_e32 v13, v13, v27
	s_waitcnt lgkmcnt(3)
	v_max_u32_e32 v1, v1, v28
	s_waitcnt lgkmcnt(2)
	v_max_u32_e32 v10, v10, v29
	s_waitcnt lgkmcnt(1)
	v_max_u32_e32 v3, v3, v30
	s_waitcnt lgkmcnt(0)
	v_max_u32_e32 v7, v7, v31
	v_max_u32_e32 v15, v15, v26
	v_max_u32_e32 v16, v16, v25
	v_max_u32_e32 v2, v2, v24
	v_max_u32_e32 v9, v9, v23
	v_max_u32_e32 v11, v11, v22
	v_max_u32_e32 v14, v14, v21
	v_max_u32_e32 v6, v6, v20
	v_max_u32_e32 v12, v12, v19
	v_max_u32_e32 v5, v5, v18
	v_max_u32_e32 v8, v8, v17
	v_max_u32_e32 v0, v0, v4
	v_max_u32_e32 v4, v13, v9
	v_min_u32_e32 v9, v13, v9
	v_max_u32_e32 v13, v1, v11
	v_min_u32_e32 v1, v1, v11
	v_max_u32_e32 v11, v10, v14
	v_min_u32_e32 v10, v10, v14
	v_max_u32_e32 v14, v3, v6
	v_min_u32_e32 v3, v3, v6
	v_max_u32_e32 v6, v7, v12
	v_min_u32_e32 v7, v7, v12
	v_max_u32_e32 v12, v15, v5
	v_min_u32_e32 v5, v15, v5
	v_max_u32_e32 v15, v16, v8
	v_min_u32_e32 v8, v16, v8
	v_max_u32_e32 v16, v2, v0
	v_min_u32_e32 v0, v2, v0
	v_max_u32_e32 v2, v4, v6
	v_min_u32_e32 v4, v4, v6
	v_max_u32_e32 v6, v13, v12
	v_min_u32_e32 v12, v13, v12
	v_max_u32_e32 v13, v11, v15
	v_min_u32_e32 v11, v11, v15
	v_max_u32_e32 v15, v14, v16
	v_min_u32_e32 v14, v14, v16
	v_max_u32_e32 v16, v9, v7
	v_min_u32_e32 v7, v9, v7
	v_max_u32_e32 v9, v1, v5
	v_min_u32_e32 v1, v1, v5
	v_max_u32_e32 v5, v10, v8
	v_min_u32_e32 v8, v10, v8
	v_max_u32_e32 v10, v3, v0
	v_min_u32_e32 v0, v3, v0
	v_max_u32_e32 v3, v2, v13
	v_min_u32_e32 v2, v2, v13
	v_max_u32_e32 v13, v6, v15
	v_min_u32_e32 v6, v6, v15
	v_max_u32_e32 v15, v4, v11
	v_min_u32_e32 v4, v4, v11
	v_max_u32_e32 v11, v12, v14
	v_min_u32_e32 v14, v12, v14
	v_max_u32_e32 v17, v16, v5
	v_min_u32_e32 v5, v16, v5
	v_max_u32_e32 v16, v9, v10
	v_min_u32_e32 v9, v9, v10
	v_max_u32_e32 v10, v7, v8
	v_min_u32_e32 v7, v7, v8
	v_max_u32_e32 v8, v1, v0
	v_min_u32_e32 v0, v1, v0
	v_max_u32_e32 v12, v3, v13
	v_min_u32_e32 v18, v3, v13
	v_max_u32_e32 v31, v7, v0
	v_min_u32_e32 v3, v7, v0
	v_cndmask_b32_e64 v0, v140, -1, vcc
	v_cmp_lt_i32_e32 vcc, -1, v12
	v_bitop3_b32 v39, v0, v85, s77 bitop3:0x78
	v_max_u32_e32 v19, v2, v6
	v_cndmask_b32_e64 v0, v140, -1, vcc
	v_cmp_lt_i32_e32 vcc, -1, v86
	v_bitop3_b32 v0, v0, v12, s77 bitop3:0x78
	v_add_f32_e32 v48, v39, v0
	v_cndmask_b32_e64 v1, v140, -1, vcc
	v_cmp_lt_i32_e32 vcc, -1, v18
	v_bitop3_b32 v35, v1, v86, s77 bitop3:0x78
	v_max_u32_e32 v27, v5, v9
	v_cndmask_b32_e64 v1, v140, -1, vcc
	v_cmp_lt_i32_e32 vcc, -1, v87
	v_min_u32_e32 v28, v5, v9
	v_bitop3_b32 v9, v1, v18, s77 bitop3:0x78
	v_cndmask_b32_e64 v1, v140, -1, vcc
	v_cmp_lt_i32_e32 vcc, -1, v19
	v_ashrrev_i32_e32 v49, 31, v48
	v_bitop3_b32 v33, v1, v87, s77 bitop3:0x78
	v_cndmask_b32_e64 v1, v140, -1, vcc
	v_or_b32_e32 v49, 0x80000000, v49
	v_max_u32_e32 v21, v15, v11
	v_min_u32_e32 v22, v15, v11
	v_bitop3_b32 v15, v1, v19, s77 bitop3:0x78
	v_bitop3_b32 v48, v49, s78, v48 bitop3:0xde
	v_add_f32_e32 v49, v39, v9
	v_ashrrev_i32_e32 v50, 31, v49
	v_add_f32_e32 v52, v39, v15
	v_min_u32_e32 v20, v2, v6
	v_cmp_lt_i32_e32 vcc, -1, v88
	v_or_b32_e32 v50, 0x80000000, v50
	v_ashrrev_i32_e32 v53, 31, v52
	v_cndmask_b32_e64 v1, v140, -1, vcc
	v_cmp_lt_i32_e32 vcc, -1, v20
	v_bitop3_b32 v49, v50, s79, v49 bitop3:0x48
	v_or_b32_e32 v53, 0x80000000, v53
	v_max_u32_e32 v25, v17, v16
	v_min_u32_e32 v26, v17, v16
	v_bitop3_b32 v17, v1, v88, s77 bitop3:0x78
	v_cndmask_b32_e64 v1, v140, -1, vcc
	v_or_b32_e32 v49, 0xfe, v49
	v_bitop3_b32 v52, v53, s79, v52 bitop3:0x48
	v_bitop3_b32 v32, v1, v20, s77 bitop3:0x78
	v_max_u32_e32 v50, v48, v49
	v_or_b32_e32 v52, 0xfd, v52
	v_min_u32_e32 v51, v48, v49
	v_max_u32_e32 v53, v50, v52
	v_min_u32_e32 v50, v50, v52
	v_med3_u32 v48, v48, v49, v52
	v_add_f32_e32 v52, v39, v32
	v_ashrrev_i32_e32 v54, 31, v52
	v_cmp_lt_i32_e32 vcc, -1, v89
	v_or_b32_e32 v54, 0x80000000, v54
	v_bitop3_b32 v52, v54, s79, v52 bitop3:0x48
	v_cndmask_b32_e64 v1, v140, -1, vcc
	v_cmp_lt_i32_e32 vcc, -1, v21
	v_bitop3_b32 v16, v1, v89, s77 bitop3:0x78
	v_or_b32_e32 v52, 0xfc, v52
	v_cndmask_b32_e64 v1, v140, -1, vcc
	v_bitop3_b32 v34, v1, v21, s77 bitop3:0x78
	v_max_u32_e32 v54, v53, v52
	v_min_u32_e32 v52, v53, v52
	v_min_u32_e32 v49, v51, v50
	v_max_u32_e32 v53, v48, v52
	v_min_u32_e32 v48, v48, v52
	v_med3_u32 v50, v51, v50, v52
	v_add_f32_e32 v52, v39, v34
	v_ashrrev_i32_e32 v55, 31, v52
	v_or_b32_e32 v55, 0x80000000, v55
	v_cmp_lt_i32_e32 vcc, -1, v90
	v_bitop3_b32 v52, v55, s79, v52 bitop3:0x48
	v_or_b32_e32 v52, 0xfb, v52
	v_cndmask_b32_e64 v1, v140, -1, vcc
	v_cmp_lt_i32_e32 vcc, -1, v22
	v_max_u32_e32 v23, v4, v14
	v_min_u32_e32 v24, v4, v14
	v_bitop3_b32 v14, v1, v90, s77 bitop3:0x78
	v_cndmask_b32_e64 v1, v140, -1, vcc
	v_max_u32_e32 v55, v54, v52
	v_min_u32_e32 v52, v54, v52
	v_bitop3_b32 v38, v1, v22, s77 bitop3:0x78
	v_max_u32_e32 v54, v53, v52
	v_min_u32_e32 v52, v53, v52
	v_min_u32_e32 v51, v49, v48
	v_max_u32_e32 v53, v50, v52
	v_min_u32_e32 v50, v50, v52
	v_med3_u32 v48, v49, v48, v52
	v_add_f32_e32 v52, v39, v38
	v_ashrrev_i32_e32 v56, 31, v52
	v_or_b32_e32 v56, 0x80000000, v56
	v_bitop3_b32 v52, v56, s79, v52 bitop3:0x48
	v_cmp_lt_i32_e32 vcc, -1, v91
	v_or_b32_e32 v52, 0xfa, v52
	v_max_u32_e32 v56, v55, v52
	v_cndmask_b32_e64 v1, v140, -1, vcc
	v_cmp_lt_i32_e32 vcc, -1, v23
	v_min_u32_e32 v52, v55, v52
	v_bitop3_b32 v13, v1, v91, s77 bitop3:0x78
	v_cndmask_b32_e64 v1, v140, -1, vcc
	v_max_u32_e32 v55, v54, v52
	v_min_u32_e32 v52, v54, v52
	v_bitop3_b32 v37, v1, v23, s77 bitop3:0x78
	v_max_u32_e32 v54, v53, v52
	v_min_u32_e32 v52, v53, v52
	v_min_u32_e32 v49, v51, v50
	v_max_u32_e32 v53, v48, v52
	v_min_u32_e32 v48, v48, v52
	v_med3_u32 v50, v51, v50, v52
	v_add_f32_e32 v52, v39, v37
	v_ashrrev_i32_e32 v57, 31, v52
	v_or_b32_e32 v57, 0x80000000, v57
	v_bitop3_b32 v52, v57, s79, v52 bitop3:0x48
	v_or_b32_e32 v52, 0xf9, v52
	v_cmp_lt_i32_e32 vcc, -1, v92
	v_max_u32_e32 v57, v56, v52
	v_min_u32_e32 v52, v56, v52
	v_cndmask_b32_e64 v1, v140, -1, vcc
	v_cmp_lt_i32_e32 vcc, -1, v24
	v_max_u32_e32 v56, v55, v52
	v_min_u32_e32 v52, v55, v52
	v_bitop3_b32 v11, v1, v92, s77 bitop3:0x78
	v_cndmask_b32_e64 v1, v140, -1, vcc
	v_max_u32_e32 v55, v54, v52
	v_min_u32_e32 v52, v54, v52
	v_bitop3_b32 v36, v1, v24, s77 bitop3:0x78
	v_max_u32_e32 v54, v53, v52
	v_min_u32_e32 v52, v53, v52
	v_min_u32_e32 v51, v49, v48
	v_max_u32_e32 v53, v50, v52
	v_min_u32_e32 v50, v50, v52
	v_med3_u32 v48, v49, v48, v52
	v_add_f32_e32 v52, v39, v36
	v_ashrrev_i32_e32 v58, 31, v52
	v_or_b32_e32 v58, 0x80000000, v58
	v_bitop3_b32 v52, v58, s79, v52 bitop3:0x48
	v_or_b32_e32 v52, 0xf8, v52
	v_cmp_lt_i32_e32 vcc, -1, v93
	v_max_u32_e32 v58, v57, v52
	v_min_u32_e32 v52, v57, v52
	v_cndmask_b32_e64 v1, v140, -1, vcc
	v_cmp_lt_i32_e32 vcc, -1, v25
	v_max_u32_e32 v57, v56, v52
	v_min_u32_e32 v52, v56, v52
	v_max_u32_e32 v29, v10, v8
	v_min_u32_e32 v30, v10, v8
	v_bitop3_b32 v10, v1, v93, s77 bitop3:0x78
	v_cndmask_b32_e64 v1, v140, -1, vcc
	v_max_u32_e32 v56, v55, v52
	v_min_u32_e32 v52, v55, v52
	v_bitop3_b32 v40, v1, v25, s77 bitop3:0x78
	v_max_u32_e32 v55, v54, v52
	v_min_u32_e32 v52, v54, v52
	v_max_u32_e32 v54, v53, v52
	v_min_u32_e32 v52, v53, v52
	v_add_f32_e32 v40, v39, v40
	v_min_u32_e32 v49, v51, v50
	v_max_u32_e32 v53, v48, v52
	v_min_u32_e32 v48, v48, v52
	v_med3_u32 v50, v51, v50, v52
	v_ashrrev_i32_e32 v52, 31, v40
	v_or_b32_e32 v52, 0x80000000, v52
	v_bitop3_b32 v40, v52, s79, v40 bitop3:0x48
	v_or_b32_e32 v40, 0xf7, v40
	v_max_u32_e32 v52, v58, v40
	v_min_u32_e32 v40, v58, v40
	v_cmp_lt_i32_e32 vcc, -1, v94
	v_max_u32_e32 v58, v57, v40
	v_min_u32_e32 v40, v57, v40
	v_cndmask_b32_e64 v1, v140, -1, vcc
	v_cmp_lt_i32_e32 vcc, -1, v26
	v_max_u32_e32 v57, v56, v40
	v_min_u32_e32 v40, v56, v40
	v_bitop3_b32 v8, v1, v94, s77 bitop3:0x78
	v_cndmask_b32_e64 v1, v140, -1, vcc
	v_max_u32_e32 v56, v55, v40
	v_min_u32_e32 v40, v55, v40
	v_bitop3_b32 v41, v1, v26, s77 bitop3:0x78
	v_max_u32_e32 v55, v54, v40
	v_min_u32_e32 v40, v54, v40
	v_max_u32_e32 v54, v53, v40
	v_min_u32_e32 v40, v53, v40
	v_add_f32_e32 v41, v39, v41
	v_min_u32_e32 v51, v49, v48
	v_max_u32_e32 v53, v50, v40
	v_min_u32_e32 v50, v50, v40
	v_med3_u32 v40, v49, v48, v40
	v_ashrrev_i32_e32 v49, 31, v41
	v_or_b32_e32 v49, 0x80000000, v49
	v_bitop3_b32 v41, v49, s79, v41 bitop3:0x48
	v_or_b32_e32 v41, 0xf6, v41
	v_max_u32_e32 v49, v52, v41
	v_min_u32_e32 v41, v52, v41
	v_max_u32_e32 v52, v58, v41
	v_min_u32_e32 v41, v58, v41
	v_cmp_lt_i32_e32 vcc, -1, v95
	v_max_u32_e32 v58, v57, v41
	v_min_u32_e32 v41, v57, v41
	v_cndmask_b32_e64 v1, v140, -1, vcc
	v_cmp_lt_i32_e32 vcc, -1, v27
	v_max_u32_e32 v57, v56, v41
	v_min_u32_e32 v41, v56, v41
	v_bitop3_b32 v7, v1, v95, s77 bitop3:0x78
	v_cndmask_b32_e64 v1, v140, -1, vcc
	v_max_u32_e32 v56, v55, v41
	v_min_u32_e32 v41, v55, v41
	v_bitop3_b32 v42, v1, v27, s77 bitop3:0x78
	v_max_u32_e32 v55, v54, v41
	v_min_u32_e32 v41, v54, v41
	v_max_u32_e32 v54, v53, v41
	v_min_u32_e32 v41, v53, v41
	v_add_f32_e32 v42, v39, v42
	v_min_u32_e32 v48, v51, v50
	v_max_u32_e32 v53, v40, v41
	v_min_u32_e32 v40, v40, v41
	v_med3_u32 v41, v51, v50, v41
	v_ashrrev_i32_e32 v51, 31, v42
	v_or_b32_e32 v51, 0x80000000, v51
	v_bitop3_b32 v42, v51, s79, v42 bitop3:0x48
	v_or_b32_e32 v42, 0xf5, v42
	v_max_u32_e32 v51, v49, v42
	v_min_u32_e32 v42, v49, v42
	v_max_u32_e32 v49, v52, v42
	v_min_u32_e32 v42, v52, v42
	v_max_u32_e32 v52, v58, v42
	v_min_u32_e32 v42, v58, v42
	v_cmp_lt_i32_e32 vcc, -1, v96
	v_max_u32_e32 v58, v57, v42
	v_min_u32_e32 v42, v57, v42
	v_cndmask_b32_e64 v1, v140, -1, vcc
	v_cmp_lt_i32_e32 vcc, -1, v28
	v_max_u32_e32 v57, v56, v42
	v_min_u32_e32 v42, v56, v42
	v_bitop3_b32 v6, v1, v96, s77 bitop3:0x78
	v_cndmask_b32_e64 v1, v140, -1, vcc
	v_max_u32_e32 v56, v55, v42
	v_min_u32_e32 v42, v55, v42
	v_bitop3_b32 v43, v1, v28, s77 bitop3:0x78
	v_max_u32_e32 v55, v54, v42
	v_min_u32_e32 v42, v54, v42
	v_max_u32_e32 v54, v53, v42
	v_min_u32_e32 v42, v53, v42
	v_add_f32_e32 v43, v39, v43
	v_min_u32_e32 v50, v48, v40
	v_med3_u32 v40, v48, v40, v42
	v_ashrrev_i32_e32 v48, 31, v43
	v_or_b32_e32 v48, 0x80000000, v48
	v_bitop3_b32 v43, v48, s79, v43 bitop3:0x48
	v_or_b32_e32 v43, 0xf4, v43
	v_max_u32_e32 v48, v51, v43
	v_min_u32_e32 v43, v51, v43
	v_max_u32_e32 v51, v49, v43
	v_min_u32_e32 v43, v49, v43
	v_max_u32_e32 v49, v52, v43
	v_min_u32_e32 v43, v52, v43
	v_max_u32_e32 v52, v58, v43
	v_min_u32_e32 v43, v58, v43
	v_cmp_lt_i32_e32 vcc, -1, v97
	v_max_u32_e32 v58, v57, v43
	v_min_u32_e32 v43, v57, v43
	v_cndmask_b32_e64 v1, v140, -1, vcc
	v_cmp_lt_i32_e32 vcc, -1, v29
	v_max_u32_e32 v57, v56, v43
	v_min_u32_e32 v43, v56, v43
	v_bitop3_b32 v5, v1, v97, s77 bitop3:0x78
	v_cndmask_b32_e64 v1, v140, -1, vcc
	v_max_u32_e32 v56, v55, v43
	v_min_u32_e32 v43, v55, v43
	v_bitop3_b32 v44, v1, v29, s77 bitop3:0x78
	v_max_u32_e32 v53, v41, v42
	v_max_u32_e32 v55, v54, v43
	v_min_u32_e32 v43, v54, v43
	v_min_u32_e32 v41, v41, v42
	v_max_u32_e32 v54, v53, v43
	v_min_u32_e32 v43, v53, v43
	v_add_f32_e32 v44, v39, v44
	v_min_u32_e32 v42, v50, v41
	v_med3_u32 v41, v50, v41, v43
	v_ashrrev_i32_e32 v50, 31, v44
	v_or_b32_e32 v50, 0x80000000, v50
	v_bitop3_b32 v44, v50, s79, v44 bitop3:0x48
	v_or_b32_e32 v44, 0xf3, v44
	v_max_u32_e32 v50, v48, v44
	v_min_u32_e32 v44, v48, v44
	v_max_u32_e32 v48, v51, v44
	v_min_u32_e32 v44, v51, v44
	v_max_u32_e32 v51, v49, v44
	v_min_u32_e32 v44, v49, v44
	v_max_u32_e32 v49, v52, v44
	v_min_u32_e32 v44, v52, v44
	v_max_u32_e32 v52, v58, v44
	v_min_u32_e32 v44, v58, v44
	v_max_u32_e32 v58, v57, v44
	v_min_u32_e32 v44, v57, v44
	v_cmp_lt_i32_e32 vcc, -1, v98
	v_max_u32_e32 v57, v56, v44
	v_min_u32_e32 v44, v56, v44
	v_cndmask_b32_e64 v1, v140, -1, vcc
	v_cmp_lt_i32_e32 vcc, -1, v30
	v_max_u32_e32 v56, v55, v44
	v_min_u32_e32 v44, v55, v44
	v_bitop3_b32 v4, v1, v98, s77 bitop3:0x78
	v_cndmask_b32_e64 v1, v140, -1, vcc
	v_max_u32_e32 v53, v40, v43
	v_max_u32_e32 v55, v54, v44
	v_min_u32_e32 v44, v54, v44
	v_bitop3_b32 v45, v1, v30, s77 bitop3:0x78
	v_min_u32_e32 v40, v40, v43
	v_max_u32_e32 v54, v53, v44
	v_min_u32_e32 v44, v53, v44
	v_min_u32_e32 v43, v42, v40
	v_max_u32_e32 v53, v41, v44
	v_min_u32_e32 v41, v41, v44
	v_med3_u32 v40, v42, v40, v44
	v_add_f32_e32 v44, v39, v45
	v_ashrrev_i32_e32 v45, 31, v44
	v_or_b32_e32 v45, 0x80000000, v45
	v_bitop3_b32 v44, v45, s79, v44 bitop3:0x48
	v_or_b32_e32 v44, 0xf2, v44
	v_max_u32_e32 v45, v50, v44
	v_min_u32_e32 v44, v50, v44
	v_max_u32_e32 v50, v48, v44
	v_min_u32_e32 v44, v48, v44
	v_max_u32_e32 v48, v51, v44
	v_min_u32_e32 v44, v51, v44
	v_max_u32_e32 v51, v49, v44
	v_min_u32_e32 v44, v49, v44
	v_max_u32_e32 v49, v52, v44
	v_min_u32_e32 v44, v52, v44
	v_max_u32_e32 v52, v58, v44
	v_min_u32_e32 v44, v58, v44
	v_max_u32_e32 v58, v57, v44
	v_min_u32_e32 v44, v57, v44
	v_cmp_lt_i32_e32 vcc, -1, v99
	v_max_u32_e32 v57, v56, v44
	v_min_u32_e32 v44, v56, v44
	v_cndmask_b32_e64 v1, v140, -1, vcc
	v_cmp_lt_i32_e32 vcc, -1, v31
	v_max_u32_e32 v56, v55, v44
	v_min_u32_e32 v44, v55, v44
	v_bitop3_b32 v2, v1, v99, s77 bitop3:0x78
	v_cndmask_b32_e64 v1, v140, -1, vcc
	v_max_u32_e32 v55, v54, v44
	v_min_u32_e32 v44, v54, v44
	v_bitop3_b32 v46, v1, v31, s77 bitop3:0x78
	v_max_u32_e32 v54, v53, v44
	v_min_u32_e32 v44, v53, v44
	v_min_u32_e32 v42, v43, v41
	v_max_u32_e32 v53, v40, v44
	v_min_u32_e32 v40, v40, v44
	v_med3_u32 v41, v43, v41, v44
	v_add_f32_e32 v44, v39, v46
	v_ashrrev_i32_e32 v46, 31, v44
	v_or_b32_e32 v46, 0x80000000, v46
	v_bitop3_b32 v44, v46, s79, v44 bitop3:0x48
	v_or_b32_e32 v44, 0xf1, v44
	v_max_u32_e32 v46, v45, v44
	v_min_u32_e32 v44, v45, v44
	v_max_u32_e32 v45, v50, v44
	v_min_u32_e32 v44, v50, v44
	v_max_u32_e32 v50, v48, v44
	v_min_u32_e32 v44, v48, v44
	v_max_u32_e32 v48, v51, v44
	v_min_u32_e32 v44, v51, v44
	v_max_u32_e32 v51, v49, v44
	v_min_u32_e32 v44, v49, v44
	v_max_u32_e32 v49, v52, v44
	v_min_u32_e32 v44, v52, v44
	v_max_u32_e32 v52, v58, v44
	v_min_u32_e32 v44, v58, v44
	v_cmp_lt_i32_e32 vcc, -1, v100
	v_max_u32_e32 v58, v57, v44
	v_min_u32_e32 v44, v57, v44
	v_cndmask_b32_e64 v1, v140, -1, vcc
	v_cmp_lt_i32_e32 vcc, -1, v3
	v_max_u32_e32 v57, v56, v44
	v_min_u32_e32 v44, v56, v44
	v_cndmask_b32_e64 v47, v140, -1, vcc
	v_max_u32_e32 v56, v55, v44
	v_min_u32_e32 v44, v55, v44
	v_bitop3_b32 v47, v47, v3, s77 bitop3:0x78
	v_max_u32_e32 v55, v54, v44
	v_min_u32_e32 v44, v54, v44
	v_max_u32_e32 v54, v53, v44
	v_min_u32_e32 v44, v53, v44
	v_add_f32_e32 v39, v39, v47
	v_min_u32_e32 v43, v42, v40
	v_max_u32_e32 v53, v41, v44
	v_min_u32_e32 v41, v41, v44
	v_med3_u32 v40, v42, v40, v44
	v_ashrrev_i32_e32 v44, 31, v39
	v_or_b32_e32 v44, 0x80000000, v44
	v_bitop3_b32 v39, v44, s79, v39 bitop3:0x48
	v_or_b32_e32 v39, 0xf0, v39
	v_max_u32_e32 v44, v46, v39
	v_min_u32_e32 v39, v46, v39
	v_max_u32_e32 v46, v45, v39
	v_min_u32_e32 v39, v45, v39
	v_max_u32_e32 v45, v50, v39
	v_min_u32_e32 v39, v50, v39
	v_max_u32_e32 v47, v48, v39
	v_min_u32_e32 v39, v48, v39
	v_max_u32_e32 v48, v51, v39
	v_min_u32_e32 v39, v51, v39
	v_max_u32_e32 v50, v49, v39
	v_min_u32_e32 v39, v49, v39
	v_max_u32_e32 v49, v52, v39
	v_min_u32_e32 v39, v52, v39
	v_max_u32_e32 v51, v58, v39
	v_min_u32_e32 v39, v58, v39
	v_max_u32_e32 v52, v57, v39
	v_min_u32_e32 v39, v57, v39
	v_max_u32_e32 v57, v56, v39
	v_min_u32_e32 v39, v56, v39
	v_max_u32_e32 v56, v55, v39
	v_min_u32_e32 v39, v55, v39
	v_max_u32_e32 v55, v54, v39
	v_min_u32_e32 v39, v54, v39
	v_max_u32_e32 v54, v53, v39
	v_min_u32_e32 v39, v53, v39
	v_min_u32_e32 v42, v43, v41
	v_max_u32_e32 v53, v40, v39
	v_min_u32_e32 v40, v40, v39
	v_med3_u32 v39, v43, v41, v39
	v_add_f32_e32 v41, v35, v0
	v_min_u32_e32 v40, v42, v40
	v_ashrrev_i32_e32 v42, 31, v41
	v_or_b32_e32 v42, 0x80000000, v42
	v_bitop3_b32 v41, v42, s79, v41 bitop3:0x48
	v_or_b32_e32 v41, 0xef, v41
	v_max_u32_e32 v42, v44, v41
	v_min_u32_e32 v41, v44, v41
	v_max_u32_e32 v43, v46, v41
	v_min_u32_e32 v41, v46, v41
	v_max_u32_e32 v44, v45, v41
	v_min_u32_e32 v41, v45, v41
	v_max_u32_e32 v45, v47, v41
	v_min_u32_e32 v41, v47, v41
	v_max_u32_e32 v46, v48, v41
	v_min_u32_e32 v41, v48, v41
	v_max_u32_e32 v47, v50, v41
	v_min_u32_e32 v41, v50, v41
	v_max_u32_e32 v48, v49, v41
	v_min_u32_e32 v41, v49, v41
	v_max_u32_e32 v49, v51, v41
	v_min_u32_e32 v41, v51, v41
	v_max_u32_e32 v50, v52, v41
	v_min_u32_e32 v41, v52, v41
	v_max_u32_e32 v51, v57, v41
	v_min_u32_e32 v41, v57, v41
	v_max_u32_e32 v52, v56, v41
	v_min_u32_e32 v41, v56, v41
	v_max_u32_e32 v56, v55, v41
	v_min_u32_e32 v41, v55, v41
	v_max_u32_e32 v55, v54, v41
	v_min_u32_e32 v41, v54, v41
	v_max_u32_e32 v54, v53, v41
	v_min_u32_e32 v41, v53, v41
	v_max_u32_e32 v53, v39, v41
	v_min_u32_e32 v39, v39, v41
	v_add_f32_e32 v41, v35, v9
	v_ashrrev_i32_e32 v57, 31, v41
	v_or_b32_e32 v57, 0x80000000, v57
	v_bitop3_b32 v41, v57, s79, v41 bitop3:0x48
	v_or_b32_e32 v41, 0xee, v41
	v_max_u32_e32 v57, v42, v41
	v_min_u32_e32 v41, v42, v41
	v_max_u32_e32 v42, v43, v41
	v_min_u32_e32 v41, v43, v41
	v_max_u32_e32 v43, v44, v41
	v_min_u32_e32 v41, v44, v41
	v_max_u32_e32 v44, v45, v41
	v_min_u32_e32 v41, v45, v41
	v_max_u32_e32 v45, v46, v41
	v_min_u32_e32 v41, v46, v41
	v_max_u32_e32 v46, v47, v41
	v_min_u32_e32 v41, v47, v41
	v_max_u32_e32 v47, v48, v41
	v_min_u32_e32 v41, v48, v41
	v_max_u32_e32 v48, v49, v41
	v_min_u32_e32 v41, v49, v41
	v_max_u32_e32 v49, v50, v41
	v_min_u32_e32 v41, v50, v41
	v_max_u32_e32 v50, v51, v41
	v_min_u32_e32 v41, v51, v41
	v_max_u32_e32 v51, v52, v41
	v_min_u32_e32 v41, v52, v41
	v_max_u32_e32 v52, v56, v41
	v_min_u32_e32 v41, v56, v41
	v_max_u32_e32 v56, v55, v41
	v_min_u32_e32 v41, v55, v41
	v_max_u32_e32 v55, v54, v41
	v_min_u32_e32 v41, v54, v41
	v_max_u32_e32 v54, v53, v41
	v_min_u32_e32 v41, v53, v41
	v_max3_u32 v39, v40, v39, v41
	v_add_f32_e32 v40, v35, v15
	v_ashrrev_i32_e32 v41, 31, v40
	v_or_b32_e32 v41, 0x80000000, v41
	v_bitop3_b32 v40, v41, s79, v40 bitop3:0x48
	v_or_b32_e32 v40, 0xed, v40
	v_max_u32_e32 v41, v57, v40
	v_min_u32_e32 v40, v57, v40
	v_max_u32_e32 v53, v42, v40
	v_min_u32_e32 v40, v42, v40
	v_max_u32_e32 v42, v43, v40
	v_min_u32_e32 v40, v43, v40
	v_max_u32_e32 v43, v44, v40
	v_min_u32_e32 v40, v44, v40
	v_max_u32_e32 v44, v45, v40
	v_min_u32_e32 v40, v45, v40
	v_max_u32_e32 v45, v46, v40
	v_min_u32_e32 v40, v46, v40
	v_max_u32_e32 v46, v47, v40
	v_min_u32_e32 v40, v47, v40
	v_max_u32_e32 v47, v48, v40
	v_min_u32_e32 v40, v48, v40
	v_max_u32_e32 v48, v49, v40
	v_min_u32_e32 v40, v49, v40
	v_max_u32_e32 v49, v50, v40
	v_min_u32_e32 v40, v50, v40
	v_max_u32_e32 v50, v51, v40
	v_min_u32_e32 v40, v51, v40
	v_max_u32_e32 v51, v52, v40
	v_min_u32_e32 v40, v52, v40
	v_max_u32_e32 v52, v56, v40
	v_min_u32_e32 v40, v56, v40
	v_max_u32_e32 v56, v55, v40
	v_min_u32_e32 v40, v55, v40
	v_max_u32_e32 v55, v54, v40
	v_min_u32_e32 v40, v54, v40
	v_add_f32_e32 v54, v35, v32
	v_ashrrev_i32_e32 v57, 31, v54
	v_or_b32_e32 v57, 0x80000000, v57
	v_bitop3_b32 v54, v57, s79, v54 bitop3:0x48
	v_or_b32_e32 v54, 0xec, v54
	v_max_u32_e32 v57, v41, v54
	v_min_u32_e32 v41, v41, v54
	v_max_u32_e32 v54, v53, v41
	v_min_u32_e32 v41, v53, v41
	v_max_u32_e32 v53, v42, v41
	v_min_u32_e32 v41, v42, v41
	v_max_u32_e32 v42, v43, v41
	v_min_u32_e32 v41, v43, v41
	v_max_u32_e32 v43, v44, v41
	v_min_u32_e32 v41, v44, v41
	v_max_u32_e32 v44, v45, v41
	v_min_u32_e32 v41, v45, v41
	v_max_u32_e32 v45, v46, v41
	v_min_u32_e32 v41, v46, v41
	v_max_u32_e32 v46, v47, v41
	v_min_u32_e32 v41, v47, v41
	v_max_u32_e32 v47, v48, v41
	v_min_u32_e32 v41, v48, v41
	v_max_u32_e32 v48, v49, v41
	v_min_u32_e32 v41, v49, v41
	v_max_u32_e32 v49, v50, v41
	v_min_u32_e32 v41, v50, v41
	v_max_u32_e32 v50, v51, v41
	v_min_u32_e32 v41, v51, v41
	v_max_u32_e32 v51, v52, v41
	v_min_u32_e32 v41, v52, v41
	v_max_u32_e32 v52, v56, v41
	v_min_u32_e32 v41, v56, v41
	v_max_u32_e32 v56, v55, v41
	v_min_u32_e32 v41, v55, v41
	v_max3_u32 v39, v39, v40, v41
	v_add_f32_e32 v40, v35, v34
	v_ashrrev_i32_e32 v41, 31, v40
	v_or_b32_e32 v41, 0x80000000, v41
	v_bitop3_b32 v40, v41, s79, v40 bitop3:0x48
	v_or_b32_e32 v40, 0xeb, v40
	v_max_u32_e32 v41, v57, v40
	v_min_u32_e32 v40, v57, v40
	v_max_u32_e32 v55, v54, v40
	v_min_u32_e32 v40, v54, v40
	v_max_u32_e32 v54, v53, v40
	v_min_u32_e32 v40, v53, v40
	v_max_u32_e32 v53, v42, v40
	v_min_u32_e32 v40, v42, v40
	v_max_u32_e32 v42, v43, v40
	v_min_u32_e32 v40, v43, v40
	v_max_u32_e32 v43, v44, v40
	v_min_u32_e32 v40, v44, v40
	v_max_u32_e32 v44, v45, v40
	v_min_u32_e32 v40, v45, v40
	v_max_u32_e32 v45, v46, v40
	v_min_u32_e32 v40, v46, v40
	v_max_u32_e32 v46, v47, v40
	v_min_u32_e32 v40, v47, v40
	v_max_u32_e32 v47, v48, v40
	v_min_u32_e32 v40, v48, v40
	v_max_u32_e32 v48, v49, v40
	v_min_u32_e32 v40, v49, v40
	v_max_u32_e32 v49, v50, v40
	v_min_u32_e32 v40, v50, v40
	v_max_u32_e32 v50, v51, v40
	v_min_u32_e32 v40, v51, v40
	v_max_u32_e32 v51, v52, v40
	v_min_u32_e32 v40, v52, v40
	v_add_f32_e32 v38, v35, v38
	v_max_u32_e32 v52, v56, v40
	v_min_u32_e32 v40, v56, v40
	v_ashrrev_i32_e32 v56, 31, v38
	v_or_b32_e32 v56, 0x80000000, v56
	v_bitop3_b32 v38, v56, s79, v38 bitop3:0x48
	v_or_b32_e32 v38, 0xea, v38
	v_max_u32_e32 v56, v41, v38
	v_min_u32_e32 v38, v41, v38
	v_max_u32_e32 v41, v55, v38
	v_min_u32_e32 v38, v55, v38
	v_max_u32_e32 v55, v54, v38
	v_min_u32_e32 v38, v54, v38
	v_max_u32_e32 v54, v53, v38
	v_min_u32_e32 v38, v53, v38
	v_max_u32_e32 v53, v42, v38
	v_min_u32_e32 v38, v42, v38
	v_max_u32_e32 v42, v43, v38
	v_min_u32_e32 v38, v43, v38
	v_max_u32_e32 v43, v44, v38
	v_min_u32_e32 v38, v44, v38
	v_max_u32_e32 v44, v45, v38
	v_min_u32_e32 v38, v45, v38
	v_max_u32_e32 v45, v46, v38
	v_min_u32_e32 v38, v46, v38
	v_max_u32_e32 v46, v47, v38
	v_min_u32_e32 v38, v47, v38
	v_max_u32_e32 v47, v48, v38
	v_min_u32_e32 v38, v48, v38
	v_max_u32_e32 v48, v49, v38
	v_min_u32_e32 v38, v49, v38
	v_max_u32_e32 v49, v50, v38
	v_min_u32_e32 v38, v50, v38
	v_max_u32_e32 v50, v51, v38
	v_min_u32_e32 v38, v51, v38
	v_max_u32_e32 v51, v52, v38
	v_min_u32_e32 v38, v52, v38
	v_add_f32_e32 v37, v35, v37
	v_max3_u32 v38, v39, v40, v38
	v_ashrrev_i32_e32 v39, 31, v37
	v_or_b32_e32 v39, 0x80000000, v39
	v_bitop3_b32 v37, v39, s79, v37 bitop3:0x48
	v_or_b32_e32 v37, 0xe9, v37
	v_max_u32_e32 v39, v56, v37
	v_min_u32_e32 v37, v56, v37
	v_max_u32_e32 v40, v41, v37
	v_min_u32_e32 v37, v41, v37
	v_max_u32_e32 v41, v55, v37
	v_min_u32_e32 v37, v55, v37
	v_max_u32_e32 v52, v54, v37
	v_min_u32_e32 v37, v54, v37
	v_max_u32_e32 v54, v53, v37
	v_min_u32_e32 v37, v53, v37
	v_max_u32_e32 v53, v42, v37
	v_min_u32_e32 v37, v42, v37
	v_add_f32_e32 v35, v35, v36
	v_max_u32_e32 v42, v43, v37
	v_min_u32_e32 v37, v43, v37
	v_ashrrev_i32_e32 v36, 31, v35
	v_max_u32_e32 v43, v44, v37
	v_min_u32_e32 v37, v44, v37
	v_or_b32_e32 v36, 0x80000000, v36
	v_max_u32_e32 v44, v45, v37
	v_min_u32_e32 v37, v45, v37
	v_bitop3_b32 v35, v36, s79, v35 bitop3:0x48
	v_max_u32_e32 v45, v46, v37
	v_min_u32_e32 v37, v46, v37
	v_or_b32_e32 v35, 0xe8, v35
	v_max_u32_e32 v46, v47, v37
	v_min_u32_e32 v37, v47, v37
	v_max_u32_e32 v36, v39, v35
	v_min_u32_e32 v35, v39, v35
	v_max_u32_e32 v47, v48, v37
	v_min_u32_e32 v37, v48, v37
	v_max_u32_e32 v39, v40, v35
	v_min_u32_e32 v35, v40, v35
	v_max_u32_e32 v48, v49, v37
	v_min_u32_e32 v37, v49, v37
	v_max_u32_e32 v40, v41, v35
	v_min_u32_e32 v35, v41, v35
	v_max_u32_e32 v49, v50, v37
	v_min_u32_e32 v37, v50, v37
	v_max_u32_e32 v41, v52, v35
	v_min_u32_e32 v35, v52, v35
	v_max_u32_e32 v50, v51, v37
	v_min_u32_e32 v37, v51, v37
	v_max_u32_e32 v51, v54, v35
	v_min_u32_e32 v35, v54, v35
	v_max_u32_e32 v52, v53, v35
	v_min_u32_e32 v35, v53, v35
	v_max_u32_e32 v53, v42, v35
	v_min_u32_e32 v35, v42, v35
	v_max_u32_e32 v42, v43, v35
	v_min_u32_e32 v35, v43, v35
	v_max_u32_e32 v43, v44, v35
	v_min_u32_e32 v35, v44, v35
	v_max_u32_e32 v44, v45, v35
	v_min_u32_e32 v35, v45, v35
	v_max_u32_e32 v45, v46, v35
	v_min_u32_e32 v35, v46, v35
	v_max_u32_e32 v46, v47, v35
	v_min_u32_e32 v35, v47, v35
	v_max_u32_e32 v47, v48, v35
	v_min_u32_e32 v35, v48, v35
	v_max_u32_e32 v48, v49, v35
	v_min_u32_e32 v35, v49, v35
	v_max_u32_e32 v49, v50, v35
	v_min_u32_e32 v35, v50, v35
	v_max3_u32 v35, v38, v37, v35
	v_add_f32_e32 v37, v33, v0
	v_ashrrev_i32_e32 v38, 31, v37
	v_or_b32_e32 v38, 0x80000000, v38
	v_bitop3_b32 v37, v38, s79, v37 bitop3:0x48
	v_or_b32_e32 v37, 0xdf, v37
	v_max_u32_e32 v38, v36, v37
	v_min_u32_e32 v36, v36, v37
	v_max_u32_e32 v37, v39, v36
	v_min_u32_e32 v36, v39, v36
	v_max_u32_e32 v39, v40, v36
	v_min_u32_e32 v36, v40, v36
	v_max_u32_e32 v40, v41, v36
	v_min_u32_e32 v36, v41, v36
	v_max_u32_e32 v41, v51, v36
	v_min_u32_e32 v36, v51, v36
	v_max_u32_e32 v50, v52, v36
	v_min_u32_e32 v36, v52, v36
	v_max_u32_e32 v51, v53, v36
	v_min_u32_e32 v36, v53, v36
	v_max_u32_e32 v52, v42, v36
	v_min_u32_e32 v36, v42, v36
	v_max_u32_e32 v42, v43, v36
	v_min_u32_e32 v36, v43, v36
	v_max_u32_e32 v43, v44, v36
	v_min_u32_e32 v36, v44, v36
	v_max_u32_e32 v44, v45, v36
	v_min_u32_e32 v36, v45, v36
	v_max_u32_e32 v45, v46, v36
	v_min_u32_e32 v36, v46, v36
	v_max_u32_e32 v46, v47, v36
	v_min_u32_e32 v36, v47, v36
	v_max_u32_e32 v47, v48, v36
	v_min_u32_e32 v36, v48, v36
	v_max_u32_e32 v48, v49, v36
	v_min_u32_e32 v36, v49, v36
	v_add_f32_e32 v49, v33, v9
	v_ashrrev_i32_e32 v53, 31, v49
	v_or_b32_e32 v53, 0x80000000, v53
	v_bitop3_b32 v49, v53, s79, v49 bitop3:0x48
	v_or_b32_e32 v49, 0xde, v49
	v_max_u32_e32 v53, v38, v49
	v_min_u32_e32 v38, v38, v49
	v_max_u32_e32 v49, v37, v38
	v_min_u32_e32 v37, v37, v38
	v_max_u32_e32 v38, v39, v37
	v_min_u32_e32 v37, v39, v37
	v_max_u32_e32 v39, v40, v37
	v_min_u32_e32 v37, v40, v37
	v_max_u32_e32 v40, v41, v37
	v_min_u32_e32 v37, v41, v37
	v_max_u32_e32 v41, v50, v37
	v_min_u32_e32 v37, v50, v37
	v_max_u32_e32 v50, v51, v37
	v_min_u32_e32 v37, v51, v37
	v_max_u32_e32 v51, v52, v37
	v_min_u32_e32 v37, v52, v37
	v_max_u32_e32 v52, v42, v37
	v_min_u32_e32 v37, v42, v37
	v_max_u32_e32 v42, v43, v37
	v_min_u32_e32 v37, v43, v37
	v_max_u32_e32 v43, v44, v37
	v_min_u32_e32 v37, v44, v37
	v_max_u32_e32 v44, v45, v37
	v_min_u32_e32 v37, v45, v37
	v_max_u32_e32 v45, v46, v37
	v_min_u32_e32 v37, v46, v37
	v_max_u32_e32 v46, v47, v37
	v_min_u32_e32 v37, v47, v37
	v_max_u32_e32 v47, v48, v37
	v_min_u32_e32 v37, v48, v37
	v_max3_u32 v35, v35, v36, v37
	v_add_f32_e32 v36, v33, v15
	v_ashrrev_i32_e32 v37, 31, v36
	v_or_b32_e32 v37, 0x80000000, v37
	v_bitop3_b32 v36, v37, s79, v36 bitop3:0x48
	v_or_b32_e32 v36, 0xdd, v36
	v_max_u32_e32 v37, v53, v36
	v_min_u32_e32 v36, v53, v36
	v_max_u32_e32 v48, v49, v36
	v_min_u32_e32 v36, v49, v36
	v_max_u32_e32 v49, v38, v36
	v_min_u32_e32 v36, v38, v36
	v_max_u32_e32 v38, v39, v36
	v_min_u32_e32 v36, v39, v36
	v_max_u32_e32 v39, v40, v36
	v_min_u32_e32 v36, v40, v36
	v_max_u32_e32 v40, v41, v36
	v_min_u32_e32 v36, v41, v36
	v_max_u32_e32 v41, v50, v36
	v_min_u32_e32 v36, v50, v36
	v_max_u32_e32 v50, v51, v36
	v_min_u32_e32 v36, v51, v36
	v_max_u32_e32 v51, v52, v36
	v_min_u32_e32 v36, v52, v36
	v_max_u32_e32 v52, v42, v36
	v_min_u32_e32 v36, v42, v36
	v_max_u32_e32 v42, v43, v36
	v_min_u32_e32 v36, v43, v36
	v_max_u32_e32 v43, v44, v36
	v_min_u32_e32 v36, v44, v36
	v_max_u32_e32 v44, v45, v36
	v_min_u32_e32 v36, v45, v36
	v_max_u32_e32 v45, v46, v36
	v_min_u32_e32 v36, v46, v36
	v_max_u32_e32 v46, v47, v36
	v_min_u32_e32 v36, v47, v36
	v_add_f32_e32 v47, v33, v32
	v_ashrrev_i32_e32 v53, 31, v47
	v_or_b32_e32 v53, 0x80000000, v53
	v_bitop3_b32 v47, v53, s79, v47 bitop3:0x48
	v_or_b32_e32 v47, 0xdc, v47
	v_max_u32_e32 v53, v37, v47
	v_min_u32_e32 v37, v37, v47
	v_max_u32_e32 v47, v48, v37
	v_min_u32_e32 v37, v48, v37
	v_max_u32_e32 v48, v49, v37
	v_min_u32_e32 v37, v49, v37
	v_max_u32_e32 v49, v38, v37
	v_min_u32_e32 v37, v38, v37
	v_max_u32_e32 v38, v39, v37
	v_min_u32_e32 v37, v39, v37
	v_max_u32_e32 v39, v40, v37
	v_min_u32_e32 v37, v40, v37
	v_max_u32_e32 v40, v41, v37
	v_min_u32_e32 v37, v41, v37
	v_max_u32_e32 v41, v50, v37
	v_min_u32_e32 v37, v50, v37
	v_max_u32_e32 v50, v51, v37
	v_min_u32_e32 v37, v51, v37
	v_max_u32_e32 v51, v52, v37
	v_min_u32_e32 v37, v52, v37
	v_add_f32_e32 v33, v33, v34
	v_max_u32_e32 v52, v42, v37
	v_min_u32_e32 v37, v42, v37
	v_ashrrev_i32_e32 v34, 31, v33
	v_max_u32_e32 v42, v43, v37
	v_min_u32_e32 v37, v43, v37
	v_or_b32_e32 v34, 0x80000000, v34
	v_max_u32_e32 v43, v44, v37
	v_min_u32_e32 v37, v44, v37
	v_bitop3_b32 v33, v34, s79, v33 bitop3:0x48
	v_max_u32_e32 v44, v45, v37
	v_min_u32_e32 v37, v45, v37
	v_or_b32_e32 v33, 0xdb, v33
	v_max_u32_e32 v45, v46, v37
	v_min_u32_e32 v37, v46, v37
	v_max_u32_e32 v34, v53, v33
	v_min_u32_e32 v33, v53, v33
	v_max3_u32 v35, v35, v36, v37
	v_max_u32_e32 v36, v47, v33
	v_min_u32_e32 v33, v47, v33
	v_max_u32_e32 v37, v48, v33
	v_min_u32_e32 v33, v48, v33
	v_max_u32_e32 v46, v49, v33
	v_min_u32_e32 v33, v49, v33
	v_max_u32_e32 v47, v38, v33
	v_min_u32_e32 v33, v38, v33
	v_max_u32_e32 v38, v39, v33
	v_min_u32_e32 v33, v39, v33
	v_max_u32_e32 v39, v40, v33
	v_min_u32_e32 v33, v40, v33
	v_max_u32_e32 v40, v41, v33
	v_min_u32_e32 v33, v41, v33
	v_max_u32_e32 v41, v50, v33
	v_min_u32_e32 v33, v50, v33
	v_max_u32_e32 v48, v51, v33
	v_min_u32_e32 v33, v51, v33
	v_max_u32_e32 v49, v52, v33
	v_min_u32_e32 v33, v52, v33
	v_max_u32_e32 v50, v42, v33
	v_min_u32_e32 v33, v42, v33
	v_max_u32_e32 v42, v43, v33
	v_min_u32_e32 v33, v43, v33
	v_max_u32_e32 v43, v44, v33
	v_min_u32_e32 v33, v44, v33
	v_max_u32_e32 v44, v45, v33
	v_min_u32_e32 v33, v45, v33
	v_add_f32_e32 v45, v17, v0
	v_ashrrev_i32_e32 v51, 31, v45
	v_or_b32_e32 v51, 0x80000000, v51
	v_bitop3_b32 v45, v51, s79, v45 bitop3:0x48
	v_or_b32_e32 v45, 0xcf, v45
	v_max_u32_e32 v51, v34, v45
	v_min_u32_e32 v34, v34, v45
	v_max_u32_e32 v45, v36, v34
	v_min_u32_e32 v34, v36, v34
	v_max_u32_e32 v36, v37, v34
	v_min_u32_e32 v34, v37, v34
	v_max_u32_e32 v37, v46, v34
	v_min_u32_e32 v34, v46, v34
	v_max_u32_e32 v46, v47, v34
	v_min_u32_e32 v34, v47, v34
	v_max_u32_e32 v47, v38, v34
	v_min_u32_e32 v34, v38, v34
	v_max_u32_e32 v38, v39, v34
	v_min_u32_e32 v34, v39, v34
	v_max_u32_e32 v39, v40, v34
	v_min_u32_e32 v34, v40, v34
	v_max_u32_e32 v40, v41, v34
	v_min_u32_e32 v34, v41, v34
	v_max_u32_e32 v41, v48, v34
	v_min_u32_e32 v34, v48, v34
	v_max_u32_e32 v48, v49, v34
	v_min_u32_e32 v34, v49, v34
	v_max_u32_e32 v49, v50, v34
	v_min_u32_e32 v34, v50, v34
	v_max_u32_e32 v50, v42, v34
	v_min_u32_e32 v34, v42, v34
	v_max_u32_e32 v42, v43, v34
	v_min_u32_e32 v34, v43, v34
	v_max_u32_e32 v43, v44, v34
	v_min_u32_e32 v34, v44, v34
	v_max3_u32 v33, v35, v33, v34
	v_add_f32_e32 v34, v17, v9
	v_ashrrev_i32_e32 v35, 31, v34
	v_or_b32_e32 v35, 0x80000000, v35
	v_bitop3_b32 v34, v35, s79, v34 bitop3:0x48
	v_or_b32_e32 v34, 0xce, v34
	v_max_u32_e32 v35, v51, v34
	v_min_u32_e32 v34, v51, v34
	v_max_u32_e32 v44, v45, v34
	v_min_u32_e32 v34, v45, v34
	v_max_u32_e32 v45, v36, v34
	v_min_u32_e32 v34, v36, v34
	v_max_u32_e32 v36, v37, v34
	v_min_u32_e32 v34, v37, v34
	v_max_u32_e32 v37, v46, v34
	v_min_u32_e32 v34, v46, v34
	v_max_u32_e32 v46, v47, v34
	v_min_u32_e32 v34, v47, v34
	v_max_u32_e32 v47, v38, v34
	v_min_u32_e32 v34, v38, v34
	v_max_u32_e32 v38, v39, v34
	v_min_u32_e32 v34, v39, v34
	v_max_u32_e32 v39, v40, v34
	v_min_u32_e32 v34, v40, v34
	v_max_u32_e32 v40, v41, v34
	v_min_u32_e32 v34, v41, v34
	v_max_u32_e32 v41, v48, v34
	v_min_u32_e32 v34, v48, v34
	v_max_u32_e32 v48, v49, v34
	v_min_u32_e32 v34, v49, v34
	v_max_u32_e32 v49, v50, v34
	v_min_u32_e32 v34, v50, v34
	v_max_u32_e32 v50, v42, v34
	v_min_u32_e32 v34, v42, v34
	v_max_u32_e32 v42, v43, v34
	v_min_u32_e32 v34, v43, v34
	v_add_f32_e32 v43, v17, v15
	v_ashrrev_i32_e32 v51, 31, v43
	v_or_b32_e32 v51, 0x80000000, v51
	v_bitop3_b32 v43, v51, s79, v43 bitop3:0x48
	v_or_b32_e32 v43, 0xcd, v43
	v_max_u32_e32 v51, v35, v43
	v_min_u32_e32 v35, v35, v43
	v_max_u32_e32 v43, v44, v35
	v_min_u32_e32 v35, v44, v35
	v_max_u32_e32 v44, v45, v35
	v_min_u32_e32 v35, v45, v35
	v_max_u32_e32 v45, v36, v35
	v_min_u32_e32 v35, v36, v35
	v_max_u32_e32 v36, v37, v35
	v_min_u32_e32 v35, v37, v35
	v_max_u32_e32 v37, v46, v35
	v_min_u32_e32 v35, v46, v35
	v_max_u32_e32 v46, v47, v35
	v_min_u32_e32 v35, v47, v35
	v_max_u32_e32 v47, v38, v35
	v_min_u32_e32 v35, v38, v35
	v_max_u32_e32 v38, v39, v35
	v_min_u32_e32 v35, v39, v35
	v_max_u32_e32 v39, v40, v35
	v_min_u32_e32 v35, v40, v35
	v_add_f32_e32 v17, v17, v32
	v_max_u32_e32 v40, v41, v35
	v_min_u32_e32 v35, v41, v35
	v_ashrrev_i32_e32 v32, 31, v17
	v_max_u32_e32 v41, v48, v35
	v_min_u32_e32 v35, v48, v35
	v_or_b32_e32 v32, 0x80000000, v32
	v_max_u32_e32 v48, v49, v35
	v_min_u32_e32 v35, v49, v35
	v_bitop3_b32 v17, v32, s79, v17 bitop3:0x48
	v_max_u32_e32 v49, v50, v35
	v_min_u32_e32 v35, v50, v35
	v_or_b32_e32 v17, 0xcc, v17
	v_max_u32_e32 v50, v42, v35
	v_min_u32_e32 v35, v42, v35
	v_max_u32_e32 v32, v51, v17
	v_min_u32_e32 v17, v51, v17
	v_max3_u32 v33, v33, v34, v35
	v_max_u32_e32 v34, v43, v17
	v_min_u32_e32 v17, v43, v17
	v_max_u32_e32 v35, v44, v17
	v_min_u32_e32 v17, v44, v17
	v_max_u32_e32 v42, v45, v17
	v_min_u32_e32 v17, v45, v17
	v_max_u32_e32 v43, v36, v17
	v_min_u32_e32 v17, v36, v17
	v_max_u32_e32 v36, v37, v17
	v_min_u32_e32 v17, v37, v17
	v_max_u32_e32 v37, v46, v17
	v_min_u32_e32 v17, v46, v17
	v_max_u32_e32 v44, v47, v17
	v_min_u32_e32 v17, v47, v17
	v_max_u32_e32 v45, v38, v17
	v_min_u32_e32 v17, v38, v17
	v_max_u32_e32 v38, v39, v17
	v_min_u32_e32 v17, v39, v17
	v_max_u32_e32 v39, v40, v17
	v_min_u32_e32 v17, v40, v17
	v_max_u32_e32 v40, v41, v17
	v_min_u32_e32 v17, v41, v17
	v_max_u32_e32 v41, v48, v17
	v_min_u32_e32 v17, v48, v17
	v_add_f32_e32 v48, v16, v0
	v_max_u32_e32 v46, v49, v17
	v_min_u32_e32 v17, v49, v17
	v_ashrrev_i32_e32 v49, 31, v48
	v_or_b32_e32 v49, 0x80000000, v49
	v_bitop3_b32 v48, v49, s79, v48 bitop3:0x48
	v_or_b32_e32 v48, 0xbf, v48
	v_max_u32_e32 v49, v32, v48
	v_min_u32_e32 v32, v32, v48
	v_max_u32_e32 v48, v34, v32
	v_min_u32_e32 v32, v34, v32
	v_max_u32_e32 v34, v35, v32
	v_min_u32_e32 v32, v35, v32
	v_max_u32_e32 v35, v42, v32
	v_min_u32_e32 v32, v42, v32
	v_max_u32_e32 v42, v43, v32
	v_min_u32_e32 v32, v43, v32
	v_max_u32_e32 v43, v36, v32
	v_min_u32_e32 v32, v36, v32
	v_max_u32_e32 v36, v37, v32
	v_min_u32_e32 v32, v37, v32
	v_max_u32_e32 v37, v44, v32
	v_min_u32_e32 v32, v44, v32
	v_max_u32_e32 v44, v45, v32
	v_min_u32_e32 v32, v45, v32
	v_max_u32_e32 v45, v38, v32
	v_min_u32_e32 v32, v38, v32
	v_max_u32_e32 v38, v39, v32
	v_min_u32_e32 v32, v39, v32
	v_max_u32_e32 v39, v40, v32
	v_min_u32_e32 v32, v40, v32
	v_max_u32_e32 v40, v41, v32
	v_min_u32_e32 v32, v41, v32
	v_max_u32_e32 v47, v50, v17
	v_max_u32_e32 v41, v46, v32
	v_min_u32_e32 v32, v46, v32
	v_min_u32_e32 v17, v50, v17
	v_max_u32_e32 v46, v47, v32
	v_min_u32_e32 v32, v47, v32
	v_max3_u32 v17, v33, v17, v32
	v_add_f32_e32 v32, v16, v9
	v_ashrrev_i32_e32 v33, 31, v32
	v_or_b32_e32 v33, 0x80000000, v33
	v_bitop3_b32 v32, v33, s79, v32 bitop3:0x48
	v_or_b32_e32 v32, 0xbe, v32
	v_max_u32_e32 v33, v49, v32
	v_min_u32_e32 v32, v49, v32
	v_max_u32_e32 v47, v48, v32
	v_min_u32_e32 v32, v48, v32
	v_max_u32_e32 v48, v34, v32
	v_min_u32_e32 v32, v34, v32
	v_max_u32_e32 v34, v35, v32
	v_min_u32_e32 v32, v35, v32
	v_max_u32_e32 v35, v42, v32
	v_min_u32_e32 v32, v42, v32
	v_max_u32_e32 v42, v43, v32
	v_min_u32_e32 v32, v43, v32
	v_max_u32_e32 v43, v36, v32
	v_min_u32_e32 v32, v36, v32
	v_max_u32_e32 v36, v37, v32
	v_min_u32_e32 v32, v37, v32
	v_add_f32_e32 v15, v16, v15
	v_max_u32_e32 v37, v44, v32
	v_min_u32_e32 v32, v44, v32
	v_ashrrev_i32_e32 v16, 31, v15
	v_max_u32_e32 v44, v45, v32
	v_min_u32_e32 v32, v45, v32
	v_or_b32_e32 v16, 0x80000000, v16
	v_max_u32_e32 v45, v38, v32
	v_min_u32_e32 v32, v38, v32
	v_bitop3_b32 v15, v16, s79, v15 bitop3:0x48
	v_max_u32_e32 v38, v39, v32
	v_min_u32_e32 v32, v39, v32
	v_or_b32_e32 v15, 0xbd, v15
	v_max_u32_e32 v39, v40, v32
	v_min_u32_e32 v32, v40, v32
	v_max_u32_e32 v16, v33, v15
	v_min_u32_e32 v15, v33, v15
	v_max_u32_e32 v40, v41, v32
	v_min_u32_e32 v32, v41, v32
	v_max_u32_e32 v33, v47, v15
	v_min_u32_e32 v15, v47, v15
	v_max_u32_e32 v41, v46, v32
	v_min_u32_e32 v32, v46, v32
	v_max_u32_e32 v46, v48, v15
	v_min_u32_e32 v15, v48, v15
	v_max_u32_e32 v47, v34, v15
	v_min_u32_e32 v15, v34, v15
	v_max_u32_e32 v34, v35, v15
	v_min_u32_e32 v15, v35, v15
	v_max_u32_e32 v35, v42, v15
	v_min_u32_e32 v15, v42, v15
	v_max_u32_e32 v42, v43, v15
	v_min_u32_e32 v15, v43, v15
	v_max_u32_e32 v43, v36, v15
	v_min_u32_e32 v15, v36, v15
	v_max_u32_e32 v36, v37, v15
	v_min_u32_e32 v15, v37, v15
	v_max_u32_e32 v37, v44, v15
	v_min_u32_e32 v15, v44, v15
	v_max_u32_e32 v44, v45, v15
	v_min_u32_e32 v15, v45, v15
	v_max_u32_e32 v45, v38, v15
	v_min_u32_e32 v15, v38, v15
	v_max_u32_e32 v38, v39, v15
	v_min_u32_e32 v15, v39, v15
	v_max_u32_e32 v39, v40, v15
	v_min_u32_e32 v15, v40, v15
	v_max_u32_e32 v40, v41, v15
	v_min_u32_e32 v15, v41, v15
	v_max3_u32 v15, v17, v32, v15
	v_add_f32_e32 v17, v14, v0
	v_ashrrev_i32_e32 v32, 31, v17
	v_or_b32_e32 v32, 0x80000000, v32
	v_bitop3_b32 v17, v32, s79, v17 bitop3:0x48
	v_or_b32_e32 v17, 0xaf, v17
	v_max_u32_e32 v32, v16, v17
	v_min_u32_e32 v16, v16, v17
	v_max_u32_e32 v17, v33, v16
	v_min_u32_e32 v16, v33, v16
	v_max_u32_e32 v33, v46, v16
	v_min_u32_e32 v16, v46, v16
	v_max_u32_e32 v41, v47, v16
	v_min_u32_e32 v16, v47, v16
	v_max_u32_e32 v46, v34, v16
	v_min_u32_e32 v16, v34, v16
	v_max_u32_e32 v34, v35, v16
	v_min_u32_e32 v16, v35, v16
	v_max_u32_e32 v35, v42, v16
	v_min_u32_e32 v16, v42, v16
	v_max_u32_e32 v42, v43, v16
	v_min_u32_e32 v16, v43, v16
	v_max_u32_e32 v43, v36, v16
	v_min_u32_e32 v16, v36, v16
	v_max_u32_e32 v36, v37, v16
	v_min_u32_e32 v16, v37, v16
	v_max_u32_e32 v37, v44, v16
	v_min_u32_e32 v16, v44, v16
	v_max_u32_e32 v44, v45, v16
	v_min_u32_e32 v16, v45, v16
	v_max_u32_e32 v45, v38, v16
	v_min_u32_e32 v16, v38, v16
	v_max_u32_e32 v38, v39, v16
	v_min_u32_e32 v16, v39, v16
	v_add_f32_e32 v14, v14, v9
	v_max_u32_e32 v39, v40, v16
	v_min_u32_e32 v16, v40, v16
	v_ashrrev_i32_e32 v40, 31, v14
	v_or_b32_e32 v40, 0x80000000, v40
	v_bitop3_b32 v14, v40, s79, v14 bitop3:0x48
	v_or_b32_e32 v14, 0xae, v14
	v_max_u32_e32 v40, v32, v14
	v_min_u32_e32 v14, v32, v14
	v_max_u32_e32 v32, v17, v14
	v_min_u32_e32 v14, v17, v14
	v_max_u32_e32 v17, v33, v14
	v_min_u32_e32 v14, v33, v14
	v_max_u32_e32 v33, v41, v14
	v_min_u32_e32 v14, v41, v14
	v_max_u32_e32 v41, v46, v14
	v_min_u32_e32 v14, v46, v14
	v_max_u32_e32 v46, v34, v14
	v_min_u32_e32 v14, v34, v14
	v_max_u32_e32 v34, v35, v14
	v_min_u32_e32 v14, v35, v14
	v_max_u32_e32 v35, v42, v14
	v_min_u32_e32 v14, v42, v14
	v_max_u32_e32 v42, v43, v14
	v_min_u32_e32 v14, v43, v14
	v_max_u32_e32 v43, v36, v14
	v_min_u32_e32 v14, v36, v14
	v_max_u32_e32 v36, v37, v14
	v_min_u32_e32 v14, v37, v14
	v_max_u32_e32 v37, v44, v14
	v_min_u32_e32 v14, v44, v14
	v_max_u32_e32 v44, v45, v14
	v_min_u32_e32 v14, v45, v14
	v_max_u32_e32 v45, v38, v14
	v_min_u32_e32 v14, v38, v14
	v_max_u32_e32 v38, v39, v14
	v_min_u32_e32 v14, v39, v14
	v_max3_u32 v14, v15, v16, v14
	v_add_f32_e32 v15, v13, v0
	v_ashrrev_i32_e32 v16, 31, v15
	v_or_b32_e32 v16, 0x80000000, v16
	v_bitop3_b32 v15, v16, s79, v15 bitop3:0x48
	v_or_b32_e32 v15, 0x9f, v15
	v_max_u32_e32 v16, v40, v15
	v_min_u32_e32 v15, v40, v15
	v_max_u32_e32 v39, v32, v15
	v_min_u32_e32 v15, v32, v15
	v_max_u32_e32 v32, v17, v15
	v_min_u32_e32 v15, v17, v15
	v_max_u32_e32 v17, v33, v15
	v_min_u32_e32 v15, v33, v15
	v_max_u32_e32 v33, v41, v15
	v_min_u32_e32 v15, v41, v15
	v_max_u32_e32 v40, v46, v15
	v_min_u32_e32 v15, v46, v15
	v_max_u32_e32 v41, v34, v15
	v_min_u32_e32 v15, v34, v15
	v_max_u32_e32 v34, v35, v15
	v_min_u32_e32 v15, v35, v15
	v_max_u32_e32 v35, v42, v15
	v_min_u32_e32 v15, v42, v15
	v_max_u32_e32 v42, v43, v15
	v_min_u32_e32 v15, v43, v15
	v_max_u32_e32 v43, v36, v15
	v_min_u32_e32 v15, v36, v15
	v_max_u32_e32 v36, v37, v15
	v_min_u32_e32 v15, v37, v15
	v_max_u32_e32 v37, v44, v15
	v_min_u32_e32 v15, v44, v15
	v_max_u32_e32 v44, v45, v15
	v_min_u32_e32 v15, v45, v15
	v_add_f32_e32 v13, v13, v9
	v_max_u32_e32 v45, v38, v15
	v_min_u32_e32 v15, v38, v15
	v_ashrrev_i32_e32 v38, 31, v13
	v_or_b32_e32 v38, 0x80000000, v38
	v_bitop3_b32 v13, v38, s79, v13 bitop3:0x48
	v_or_b32_e32 v13, 0x9e, v13
	v_max_u32_e32 v38, v16, v13
	v_min_u32_e32 v13, v16, v13
	v_max_u32_e32 v16, v39, v13
	v_min_u32_e32 v13, v39, v13
	v_max_u32_e32 v39, v32, v13
	v_min_u32_e32 v13, v32, v13
	v_max_u32_e32 v32, v17, v13
	v_min_u32_e32 v13, v17, v13
	v_max_u32_e32 v17, v33, v13
	v_min_u32_e32 v13, v33, v13
	v_max_u32_e32 v33, v40, v13
	v_min_u32_e32 v13, v40, v13
	v_max_u32_e32 v40, v41, v13
	v_min_u32_e32 v13, v41, v13
	v_max_u32_e32 v41, v34, v13
	v_min_u32_e32 v13, v34, v13
	v_max_u32_e32 v34, v35, v13
	v_min_u32_e32 v13, v35, v13
	v_max_u32_e32 v35, v42, v13
	v_min_u32_e32 v13, v42, v13
	v_max_u32_e32 v42, v43, v13
	v_min_u32_e32 v13, v43, v13
	v_max_u32_e32 v43, v36, v13
	v_min_u32_e32 v13, v36, v13
	v_max_u32_e32 v36, v37, v13
	v_min_u32_e32 v13, v37, v13
	v_max_u32_e32 v37, v44, v13
	v_min_u32_e32 v13, v44, v13
	v_max_u32_e32 v44, v45, v13
	v_min_u32_e32 v13, v45, v13
	v_max3_u32 v13, v14, v15, v13
	v_add_f32_e32 v14, v11, v0
	v_ashrrev_i32_e32 v15, 31, v14
	v_add_f32_e32 v9, v11, v9
	v_or_b32_e32 v15, 0x80000000, v15
	v_ashrrev_i32_e32 v11, 31, v9
	v_bitop3_b32 v14, v15, s79, v14 bitop3:0x48
	v_or_b32_e32 v11, 0x80000000, v11
	v_or_b32_e32 v14, 0x8f, v14
	v_bitop3_b32 v9, v11, s79, v9 bitop3:0x48
	v_max_u32_e32 v15, v38, v14
	v_min_u32_e32 v14, v38, v14
	v_or_b32_e32 v9, 0x8e, v9
	v_max_u32_e32 v38, v16, v14
	v_min_u32_e32 v14, v16, v14
	v_max_u32_e32 v11, v15, v9
	v_min_u32_e32 v9, v15, v9
	v_max_u32_e32 v16, v39, v14
	v_min_u32_e32 v14, v39, v14
	v_max_u32_e32 v15, v38, v9
	v_min_u32_e32 v9, v38, v9
	v_max_u32_e32 v39, v32, v14
	v_min_u32_e32 v14, v32, v14
	v_max_u32_e32 v38, v16, v9
	v_min_u32_e32 v9, v16, v9
	v_max_u32_e32 v32, v17, v14
	v_min_u32_e32 v14, v17, v14
	v_max_u32_e32 v16, v39, v9
	v_min_u32_e32 v9, v39, v9
	v_max_u32_e32 v17, v33, v14
	v_min_u32_e32 v14, v33, v14
	v_max_u32_e32 v39, v32, v9
	v_min_u32_e32 v9, v32, v9
	v_max_u32_e32 v33, v40, v14
	v_min_u32_e32 v14, v40, v14
	v_max_u32_e32 v32, v17, v9
	v_min_u32_e32 v9, v17, v9
	v_max_u32_e32 v40, v41, v14
	v_min_u32_e32 v14, v41, v14
	v_max_u32_e32 v17, v33, v9
	v_min_u32_e32 v9, v33, v9
	v_max_u32_e32 v41, v34, v14
	v_min_u32_e32 v14, v34, v14
	v_max_u32_e32 v33, v40, v9
	v_min_u32_e32 v9, v40, v9
	v_max_u32_e32 v34, v35, v14
	v_min_u32_e32 v14, v35, v14
	v_max_u32_e32 v40, v41, v9
	v_min_u32_e32 v9, v41, v9
	v_max_u32_e32 v35, v42, v14
	v_min_u32_e32 v14, v42, v14
	v_max_u32_e32 v41, v34, v9
	v_min_u32_e32 v9, v34, v9
	v_max_u32_e32 v42, v43, v14
	v_min_u32_e32 v14, v43, v14
	v_max_u32_e32 v34, v35, v9
	v_min_u32_e32 v9, v35, v9
	v_max_u32_e32 v43, v36, v14
	v_min_u32_e32 v14, v36, v14
	v_max_u32_e32 v35, v42, v9
	v_min_u32_e32 v9, v42, v9
	v_max_u32_e32 v36, v37, v14
	v_min_u32_e32 v14, v37, v14
	v_max_u32_e32 v42, v43, v9
	v_min_u32_e32 v9, v43, v9
	v_max_u32_e32 v37, v44, v14
	v_max_u32_e32 v43, v36, v9
	v_min_u32_e32 v9, v36, v9
	v_min_u32_e32 v14, v44, v14
	v_max_u32_e32 v36, v37, v9
	v_min_u32_e32 v9, v37, v9
	v_add_f32_e32 v10, v10, v0
	v_max3_u32 v9, v13, v14, v9
	v_ashrrev_i32_e32 v13, 31, v10
	v_or_b32_e32 v13, 0x80000000, v13
	v_bitop3_b32 v10, v13, s79, v10 bitop3:0x48
	v_or_b32_e32 v10, 0x7f, v10
	v_max_u32_e32 v13, v11, v10
	v_min_u32_e32 v10, v11, v10
	v_max_u32_e32 v11, v15, v10
	v_min_u32_e32 v10, v15, v10
	v_max_u32_e32 v14, v38, v10
	v_min_u32_e32 v10, v38, v10
	v_max_u32_e32 v15, v16, v10
	v_min_u32_e32 v10, v16, v10
	v_max_u32_e32 v16, v39, v10
	v_min_u32_e32 v10, v39, v10
	v_max_u32_e32 v37, v32, v10
	v_min_u32_e32 v10, v32, v10
	v_max_u32_e32 v32, v17, v10
	v_min_u32_e32 v10, v17, v10
	v_max_u32_e32 v17, v33, v10
	v_min_u32_e32 v10, v33, v10
	v_max_u32_e32 v33, v40, v10
	v_min_u32_e32 v10, v40, v10
	v_max_u32_e32 v38, v41, v10
	v_min_u32_e32 v10, v41, v10
	v_max_u32_e32 v39, v34, v10
	v_min_u32_e32 v10, v34, v10
	v_max_u32_e32 v34, v35, v10
	v_min_u32_e32 v10, v35, v10
	v_max_u32_e32 v35, v42, v10
	v_min_u32_e32 v10, v42, v10
	v_max_u32_e32 v40, v43, v10
	v_min_u32_e32 v10, v43, v10
	v_add_f32_e32 v8, v8, v0
	v_max_u32_e32 v41, v36, v10
	v_min_u32_e32 v10, v36, v10
	v_ashrrev_i32_e32 v36, 31, v8
	v_or_b32_e32 v36, 0x80000000, v36
	v_bitop3_b32 v8, v36, s79, v8 bitop3:0x48
	v_or_b32_e32 v8, 0x6f, v8
	v_max_u32_e32 v36, v13, v8
	v_min_u32_e32 v8, v13, v8
	v_max_u32_e32 v13, v11, v8
	v_min_u32_e32 v8, v11, v8
	v_max_u32_e32 v11, v14, v8
	v_min_u32_e32 v8, v14, v8
	v_max_u32_e32 v14, v15, v8
	v_min_u32_e32 v8, v15, v8
	v_max_u32_e32 v15, v16, v8
	v_min_u32_e32 v8, v16, v8
	v_max_u32_e32 v16, v37, v8
	v_min_u32_e32 v8, v37, v8
	v_max_u32_e32 v37, v32, v8
	v_min_u32_e32 v8, v32, v8
	v_max_u32_e32 v32, v17, v8
	v_min_u32_e32 v8, v17, v8
	v_max_u32_e32 v17, v33, v8
	v_min_u32_e32 v8, v33, v8
	v_max_u32_e32 v33, v38, v8
	v_min_u32_e32 v8, v38, v8
	v_max_u32_e32 v38, v39, v8
	v_min_u32_e32 v8, v39, v8
	v_max_u32_e32 v39, v34, v8
	v_min_u32_e32 v8, v34, v8
	v_max_u32_e32 v34, v35, v8
	v_min_u32_e32 v8, v35, v8
	v_max_u32_e32 v35, v40, v8
	v_min_u32_e32 v8, v40, v8
	v_max_u32_e32 v40, v41, v8
	v_min_u32_e32 v8, v41, v8
	v_add_f32_e32 v7, v7, v0
	v_max3_u32 v8, v9, v10, v8
	v_ashrrev_i32_e32 v9, 31, v7
	v_or_b32_e32 v9, 0x80000000, v9
	v_bitop3_b32 v7, v9, s79, v7 bitop3:0x48
	v_or_b32_e32 v7, 0x5f, v7
	v_max_u32_e32 v9, v36, v7
	v_min_u32_e32 v7, v36, v7
	v_max_u32_e32 v10, v13, v7
	v_min_u32_e32 v7, v13, v7
	v_max_u32_e32 v13, v11, v7
	v_min_u32_e32 v7, v11, v7
	v_max_u32_e32 v11, v14, v7
	v_min_u32_e32 v7, v14, v7
	v_max_u32_e32 v14, v15, v7
	v_min_u32_e32 v7, v15, v7
	v_max_u32_e32 v15, v16, v7
	v_min_u32_e32 v7, v16, v7
	v_max_u32_e32 v16, v37, v7
	v_min_u32_e32 v7, v37, v7
	v_max_u32_e32 v36, v32, v7
	v_min_u32_e32 v7, v32, v7
	v_max_u32_e32 v32, v17, v7
	v_min_u32_e32 v7, v17, v7
	v_max_u32_e32 v17, v33, v7
	v_min_u32_e32 v7, v33, v7
	v_max_u32_e32 v33, v38, v7
	v_min_u32_e32 v7, v38, v7
	v_add_f32_e32 v6, v6, v0
	v_max_u32_e32 v37, v39, v7
	v_min_u32_e32 v7, v39, v7
	v_ashrrev_i32_e32 v39, 31, v6
	v_or_b32_e32 v39, 0x80000000, v39
	v_bitop3_b32 v6, v39, s79, v6 bitop3:0x48
	v_or_b32_e32 v6, 0x4f, v6
	v_max_u32_e32 v39, v9, v6
	v_min_u32_e32 v6, v9, v6
	v_max_u32_e32 v9, v10, v6
	v_min_u32_e32 v6, v10, v6
	v_max_u32_e32 v10, v13, v6
	v_min_u32_e32 v6, v13, v6
	v_max_u32_e32 v13, v11, v6
	v_min_u32_e32 v6, v11, v6
	v_max_u32_e32 v11, v14, v6
	v_min_u32_e32 v6, v14, v6
	v_max_u32_e32 v14, v15, v6
	v_min_u32_e32 v6, v15, v6
	v_max_u32_e32 v15, v16, v6
	v_min_u32_e32 v6, v16, v6
	v_max_u32_e32 v16, v36, v6
	v_min_u32_e32 v6, v36, v6
	v_max_u32_e32 v36, v32, v6
	v_min_u32_e32 v6, v32, v6
	v_max_u32_e32 v32, v17, v6
	v_min_u32_e32 v6, v17, v6
	v_max_u32_e32 v17, v33, v6
	v_min_u32_e32 v6, v33, v6
	v_max_u32_e32 v38, v34, v7
	v_min_u32_e32 v7, v34, v7
	v_max_u32_e32 v33, v37, v6
	v_min_u32_e32 v6, v37, v6
	v_max_u32_e32 v34, v35, v7
	v_min_u32_e32 v7, v35, v7
	v_max_u32_e32 v37, v38, v6
	v_min_u32_e32 v6, v38, v6
	v_max_u32_e32 v35, v40, v7
	v_max_u32_e32 v38, v34, v6
	v_min_u32_e32 v6, v34, v6
	v_min_u32_e32 v7, v40, v7
	v_max_u32_e32 v34, v35, v6
	v_min_u32_e32 v6, v35, v6
	v_add_f32_e32 v5, v5, v0
	v_max3_u32 v6, v8, v7, v6
	v_ashrrev_i32_e32 v7, 31, v5
	v_bitop3_b32 v5, v7, v5, s76 bitop3:0x36
	v_and_or_b32 v5, v5, s79, 63
	v_max_u32_e32 v7, v39, v5
	v_min_u32_e32 v5, v39, v5
	v_max_u32_e32 v8, v9, v5
	v_min_u32_e32 v5, v9, v5
	v_max_u32_e32 v9, v10, v5
	v_min_u32_e32 v5, v10, v5
	v_max_u32_e32 v10, v13, v5
	v_min_u32_e32 v5, v13, v5
	v_max_u32_e32 v13, v11, v5
	v_min_u32_e32 v5, v11, v5
	v_max_u32_e32 v11, v14, v5
	v_min_u32_e32 v5, v14, v5
	v_max_u32_e32 v14, v15, v5
	v_min_u32_e32 v5, v15, v5
	v_max_u32_e32 v15, v16, v5
	v_min_u32_e32 v5, v16, v5
	v_max_u32_e32 v16, v36, v5
	v_min_u32_e32 v5, v36, v5
	v_max_u32_e32 v35, v32, v5
	v_min_u32_e32 v5, v32, v5
	v_max_u32_e32 v32, v17, v5
	v_min_u32_e32 v5, v17, v5
	v_max_u32_e32 v17, v33, v5
	v_min_u32_e32 v5, v33, v5
	v_max_u32_e32 v33, v37, v5
	v_min_u32_e32 v5, v37, v5
	v_max_u32_e32 v36, v38, v5
	v_min_u32_e32 v5, v38, v5
	v_add_f32_e32 v4, v4, v0
	v_max_u32_e32 v37, v34, v5
	v_min_u32_e32 v5, v34, v5
	v_ashrrev_i32_e32 v34, 31, v4
	v_bitop3_b32 v4, v34, v4, s76 bitop3:0x36
	v_and_or_b32 v4, v4, s79, 47
	v_max_u32_e32 v34, v7, v4
	v_min_u32_e32 v4, v7, v4
	v_max_u32_e32 v7, v8, v4
	v_min_u32_e32 v4, v8, v4
	v_max_u32_e32 v8, v9, v4
	v_min_u32_e32 v4, v9, v4
	v_max_u32_e32 v9, v10, v4
	v_min_u32_e32 v4, v10, v4
	v_max_u32_e32 v10, v13, v4
	v_min_u32_e32 v4, v13, v4
	v_max_u32_e32 v13, v11, v4
	v_min_u32_e32 v4, v11, v4
	v_max_u32_e32 v11, v14, v4
	v_min_u32_e32 v4, v14, v4
	v_max_u32_e32 v14, v15, v4
	v_min_u32_e32 v4, v15, v4
	v_max_u32_e32 v15, v16, v4
	v_min_u32_e32 v4, v16, v4
	v_max_u32_e32 v16, v35, v4
	v_min_u32_e32 v4, v35, v4
	v_max_u32_e32 v35, v32, v4
	v_min_u32_e32 v4, v32, v4
	v_max_u32_e32 v32, v17, v4
	v_min_u32_e32 v4, v17, v4
	v_max_u32_e32 v17, v33, v4
	v_min_u32_e32 v4, v33, v4
	v_max_u32_e32 v33, v36, v4
	v_min_u32_e32 v4, v36, v4
	v_max_u32_e32 v36, v37, v4
	v_min_u32_e32 v4, v37, v4
	v_add_f32_e32 v2, v2, v0
	v_max3_u32 v37, v6, v5, v4
	v_ashrrev_i32_e32 v4, 31, v2
	v_bitop3_b32 v2, v4, v2, s76 bitop3:0x36
	v_and_or_b32 v2, v2, s79, 31
	v_max_u32_e32 v4, v34, v2
	v_min_u32_e32 v2, v34, v2
	v_max_u32_e32 v5, v7, v2
	v_min_u32_e32 v2, v7, v2
	v_max_u32_e32 v6, v8, v2
	v_min_u32_e32 v2, v8, v2
	v_max_u32_e32 v7, v9, v2
	v_min_u32_e32 v2, v9, v2
	v_max_u32_e32 v9, v10, v2
	v_min_u32_e32 v2, v10, v2
	v_max_u32_e32 v10, v13, v2
	v_min_u32_e32 v2, v13, v2
	v_bitop3_b32 v1, v1, v100, s77 bitop3:0x78
	v_max_u32_e32 v34, v11, v2
	v_min_u32_e32 v2, v11, v2
	v_max_u32_e32 v38, v14, v2
	v_min_u32_e32 v2, v14, v2
	v_add_f32_e32 v0, v1, v0
	v_max_u32_e32 v39, v15, v2
	v_min_u32_e32 v2, v15, v2
	v_ashrrev_i32_e32 v1, 31, v0
	v_max_u32_e32 v40, v16, v2
	v_min_u32_e32 v2, v16, v2
	v_bitop3_b32 v0, v1, v0, s76 bitop3:0x36
	v_max_u32_e32 v16, v35, v2
	v_min_u32_e32 v2, v35, v2
	v_and_or_b32 v0, v0, s79, 15
	v_max_u32_e32 v35, v32, v2
	v_min_u32_e32 v2, v32, v2
	v_max_u32_e32 v32, v4, v0
	v_min_u32_e32 v0, v4, v0
	v_max_u32_e32 v13, v5, v0
	v_min_u32_e32 v0, v5, v0
	v_max_u32_e32 v14, v6, v0
	v_min_u32_e32 v0, v6, v0
	v_max_u32_e32 v15, v7, v0
	v_min_u32_e32 v0, v7, v0
	v_max_u32_e32 v8, v9, v0
	v_min_u32_e32 v0, v9, v0
	v_max_u32_e32 v9, v10, v0
	v_min_u32_e32 v0, v10, v0
	v_max_u32_e32 v10, v34, v0
	v_min_u32_e32 v0, v34, v0
	v_max_u32_e32 v11, v38, v0
	v_min_u32_e32 v0, v38, v0
	v_max_u32_e32 v4, v39, v0
	v_min_u32_e32 v0, v39, v0
	v_max_u32_e32 v5, v40, v0
	v_min_u32_e32 v0, v40, v0
	v_max_u32_e32 v41, v17, v2
	v_min_u32_e32 v2, v17, v2
	v_max_u32_e32 v6, v16, v0
	v_min_u32_e32 v0, v16, v0
	v_max_u32_e32 v17, v33, v2
	v_min_u32_e32 v2, v33, v2
	v_min_u32_e32 v1, v35, v0
	v_max_u32_e32 v33, v36, v2
	v_min_u32_e32 v36, v36, v2
	v_min_u32_e32 v2, v41, v1
	v_min_u32_e32 v16, v17, v2
	v_max_u32_e32 v7, v35, v0
	v_max_u32_e32 v0, v41, v1
	v_max_u32_e32 v1, v17, v2
	v_max_u32_e32 v2, v33, v16
	v_min_u32_e32 v16, v33, v16
	v_max3_u32 v34, v37, v36, v16
	v_lshlrev_b64 v[16:17], 7, v[80:81]
	v_and_b32_e32 v33, 32, v128
	v_lshl_add_u64 v[16:17], v[16:17], 0, s[16:17]
	v_cmp_ne_u32_e32 vcc, 0, v33
	s_and_saveexec_b64 s[54:55], vcc
	s_xor_b64 s[54:55], exec, s[54:55]
	s_cbranch_execz .LBB0_1064
	v_cmp_lt_i32_e32 vcc, -1, v32
	s_mov_b32 s3, 0x36000000
	s_nop 0
	v_cndmask_b32_e64 v3, v140, -1, vcc
	v_cmp_lt_i32_e32 vcc, -1, v13
	v_bitop3_b32 v3, v3, v32, s79 bitop3:0x78
	v_sub_f32_e32 v12, v3, v3
	v_cndmask_b32_e64 v18, v140, -1, vcc
	v_cmp_lt_i32_e32 vcc, -1, v14
	v_bitop3_b32 v13, v18, v13, s79 bitop3:0x78
	v_mul_f32_e32 v12, 0x3fb8aa3b, v12
	v_cndmask_b32_e64 v18, v140, -1, vcc
	v_cmp_lt_i32_e32 vcc, -1, v15
	v_sub_f32_e32 v13, v13, v3
	v_bitop3_b32 v14, v18, v14, s79 bitop3:0x78
	v_cndmask_b32_e64 v18, v140, -1, vcc
	v_cmp_lt_i32_e32 vcc, -1, v8
	v_exp_f32_e32 v12, v12
	v_mul_f32_e32 v13, 0x3fb8aa3b, v13
	v_sub_f32_e32 v14, v14, v3
	v_bitop3_b32 v15, v18, v15, s79 bitop3:0x78
	v_cndmask_b32_e64 v19, v140, -1, vcc
	v_cmp_lt_i32_e32 vcc, -1, v9
	v_exp_f32_e32 v13, v13
	v_mul_f32_e32 v14, 0x3fb8aa3b, v14
	v_sub_f32_e32 v15, v15, v3
	v_bitop3_b32 v8, v19, v8, s79 bitop3:0x78
	v_cndmask_b32_e64 v19, v140, -1, vcc
	v_cmp_lt_i32_e32 vcc, -1, v10
	v_exp_f32_e32 v14, v14
	v_mul_f32_e32 v15, 0x3fb8aa3b, v15
	v_sub_f32_e32 v8, v8, v3
	v_bitop3_b32 v9, v19, v9, s79 bitop3:0x78
	v_cndmask_b32_e64 v19, v140, -1, vcc
	v_cmp_lt_i32_e32 vcc, -1, v11
	v_exp_f32_e32 v15, v15
	v_mul_f32_e32 v8, 0x3fb8aa3b, v8
	v_sub_f32_e32 v9, v9, v3
	v_bitop3_b32 v10, v19, v10, s79 bitop3:0x78
	v_cndmask_b32_e64 v19, v140, -1, vcc
	v_cmp_lt_i32_e32 vcc, -1, v4
	v_add_f32_e32 v18, 0, v12
	v_exp_f32_e32 v8, v8
	v_mul_f32_e32 v9, 0x3fb8aa3b, v9
	v_sub_f32_e32 v10, v10, v3
	v_bitop3_b32 v11, v19, v11, s79 bitop3:0x78
	v_cndmask_b32_e64 v19, v140, -1, vcc
	v_cmp_lt_i32_e32 vcc, -1, v5
	v_add_f32_e32 v18, v18, v13
	v_exp_f32_e32 v9, v9
	v_mul_f32_e32 v10, 0x3fb8aa3b, v10
	v_sub_f32_e32 v11, v11, v3
	v_bitop3_b32 v4, v19, v4, s79 bitop3:0x78
	v_cndmask_b32_e64 v19, v140, -1, vcc
	v_cmp_lt_i32_e32 vcc, -1, v6
	v_add_f32_e32 v18, v18, v14
	v_exp_f32_e32 v10, v10
	v_mul_f32_e32 v11, 0x3fb8aa3b, v11
	v_sub_f32_e32 v4, v4, v3
	v_bitop3_b32 v5, v19, v5, s79 bitop3:0x78
	v_cndmask_b32_e64 v19, v140, -1, vcc
	v_cmp_lt_i32_e32 vcc, -1, v7
	v_add_f32_e32 v18, v18, v15
	v_exp_f32_e32 v11, v11
	v_mul_f32_e32 v4, 0x3fb8aa3b, v4
	v_sub_f32_e32 v5, v5, v3
	v_bitop3_b32 v6, v19, v6, s79 bitop3:0x78
	v_cndmask_b32_e64 v19, v140, -1, vcc
	v_add_f32_e32 v18, v18, v8
	v_exp_f32_e32 v4, v4
	v_mul_f32_e32 v5, 0x3fb8aa3b, v5
	v_sub_f32_e32 v6, v6, v3
	v_bitop3_b32 v7, v19, v7, s79 bitop3:0x78
	v_add_f32_e32 v18, v18, v9
	v_exp_f32_e32 v5, v5
	v_mul_f32_e32 v6, 0x3fb8aa3b, v6
	v_sub_f32_e32 v7, v7, v3
	v_add_f32_e32 v18, v18, v10
	v_exp_f32_e32 v6, v6
	v_mul_f32_e32 v7, 0x3fb8aa3b, v7
	v_add_f32_e32 v18, v18, v11
	v_exp_f32_e32 v7, v7
	v_add_f32_e32 v18, v18, v4
	v_add_f32_e32 v18, v18, v5
	v_add_f32_e32 v18, v18, v6
	v_cmp_lt_i32_e32 vcc, -1, v0
	v_add_f32_e32 v22, v18, v7
	s_nop 0
	v_cndmask_b32_e64 v18, v140, -1, vcc
	v_bitop3_b32 v0, v18, v0, s79 bitop3:0x78
	v_sub_f32_e32 v0, v0, v3
	v_mul_f32_e32 v0, 0x3fb8aa3b, v0
	v_cmp_lt_i32_e32 vcc, -1, v1
	v_exp_f32_e32 v18, v0
	s_nop 0
	v_cndmask_b32_e64 v0, v140, -1, vcc
	v_bitop3_b32 v0, v0, v1, s79 bitop3:0x78
	v_sub_f32_e32 v0, v0, v3
	v_mul_f32_e32 v0, 0x3fb8aa3b, v0
	v_cmp_lt_i32_e32 vcc, -1, v2
	v_exp_f32_e32 v19, v0
	s_nop 0
	v_cndmask_b32_e64 v0, v140, -1, vcc
	v_bitop3_b32 v0, v0, v2, s79 bitop3:0x78
	v_sub_f32_e32 v0, v0, v3
	v_mul_f32_e32 v0, 0x3fb8aa3b, v0
	v_cmp_lt_i32_e32 vcc, -1, v34
	v_exp_f32_e32 v20, v0
	s_nop 0
	v_cndmask_b32_e64 v0, v140, -1, vcc
	v_bitop3_b32 v0, v0, v34, s79 bitop3:0x78
	v_sub_f32_e32 v0, v0, v3
	v_mul_f32_e32 v0, 0x3fb8aa3b, v0
	v_exp_f32_e32 v21, v0
	v_add_f32_e32 v0, v22, v18
	v_add_f32_e32 v0, v0, v19
	v_add_f32_e32 v0, v0, v20
	v_add_f32_e32 v0, v0, v21
	v_div_scale_f32 v1, s[56:57], v0, v0, 1.0
	v_rcp_f32_e32 v2, v1
	s_lshl_b64 s[56:57], s[48:49], 2
	s_add_u32 s56, s52, s56
	s_addc_u32 s57, s53, s57
	v_fma_f32 v3, -v1, v2, 1.0
	v_fmac_f32_e32 v2, v3, v2
	v_div_scale_f32 v3, vcc, 1.0, v0, 1.0
	v_mul_f32_e32 v22, v3, v2
	v_fma_f32 v23, -v1, v22, v3
	v_fmac_f32_e32 v22, v23, v2
	v_fma_f32 v1, -v1, v22, v3
	v_div_fmas_f32 v1, v1, v2, v22
	v_div_fixup_f32 v22, v1, v0, 1.0
	v_lshl_add_u64 v[16:17], v[16:17], 2, s[56:57]
	v_pk_mul_f32 v[0:1], v[12:13], v[22:23] op_sel_hi:[1,0]
	v_add_co_u32_e32 v12, vcc, s3, v16
	s_mov_b64 s[56:57], 0x36000000
	v_pk_mul_f32 v[2:3], v[14:15], v[22:23] op_sel_hi:[1,0]
	v_addc_co_u32_e32 v13, vcc, 0, v17, vcc
	v_lshl_add_u64 v[24:25], v[16:17], 0, s[56:57]
	global_store_dwordx4 v[12:13], v[0:3], off
	s_nop 1
	v_pk_mul_f32 v[0:1], v[8:9], v[22:23] op_sel_hi:[1,0]
	v_pk_mul_f32 v[2:3], v[10:11], v[22:23] op_sel_hi:[1,0]
	global_store_dwordx4 v[24:25], v[0:3], off offset:16
	s_nop 1
	v_pk_mul_f32 v[0:1], v[4:5], v[22:23] op_sel_hi:[1,0]
	v_pk_mul_f32 v[2:3], v[6:7], v[22:23] op_sel_hi:[1,0]
	global_store_dwordx4 v[24:25], v[0:3], off offset:32
	s_nop 1
	v_pk_mul_f32 v[0:1], v[18:19], v[22:23] op_sel_hi:[1,0]
	v_pk_mul_f32 v[2:3], v[20:21], v[22:23] op_sel_hi:[1,0]
	global_store_dwordx4 v[24:25], v[0:3], off offset:48
